# non-temporal policy on the once-read f32 weight loads of the conversion items (first phase and deferred copies); deferred copies take at most 4/5 items per idle CU
# speedup vs baseline: 1.0690x; 1.0050x over previous
; DI void conv_witem(const float* W, int K, int Nsrc, bf16_t* dst, const float* rowscale, bool perm_in, int kt, int ntile, int lane, bool glu_rows = false) {
;     const int k0 = kt * 16, c0 = ntile * 256, n4 = lane * 4;
;     const int cdst = c0 + n4;
;     int csrc = cdst;
;     if (perm_in && cdst >= C_RQ && cdst < C_RV) { const int pp = cdst & 63, g = pp >> 5, e = pp & 31; csrc = (cdst & ~63) + ((e < 16) ? g * 16 + e : 32 + g * 16 + (e - 16)); }
;     const bool valid = csrc < Nsrc;
;     const float* src = W + (size_t)k0 * Nsrc + csrc;
;     f32x4 v[16];
; #pragma unroll
;     for (int i = 0; i < 16; ++i) v[i] = valid ? *(const f32x4*)(src + (size_t)i * Nsrc) : (f32x4){0.f, 0.f, 0.f, 0.f};
; DI void prep_items(const Params& p, LAS unsigned char* lds, int l, unsigned* ctr, int max_items) {
;     ...
;     for (int done = 0; done < max_items; ++done) {
;         const int it = next_item(ctr, slot);
;         if (it >= N_ADA + n_tab + N_CONV) break;
;         if (it < N_ADA) {
.LBB0_25:
	s_or_b64 exec, exec, s[0:1]
	s_waitcnt lgkmcnt(0)
	s_barrier
	ds_read_b32 v0, v96
	s_movk_i32 s0, 0x6a3
	s_xor_b64 s[96:97], s[94:95], -1
	s_waitcnt lgkmcnt(0)
	v_cmp_lt_i32_e32 vcc, s0, v0
	v_readfirstlane_b32 s2, v0
	s_mov_b64 s[0:1], -1
	s_cbranch_vccnz .LBB0_20
	s_cmp_gt_i32 s2, 47
	s_cbranch_scc0 .LBB0_216
	s_cmpk_gt_u32 s2, 0x5f
	s_cbranch_scc0 .LBB0_181
	v_lshl_add_u32 v0, s2, 3, v93
	s_movk_i32 s0, 0xbff
	v_cmp_lt_i32_e32 vcc, s0, v0
	s_and_saveexec_b64 s[0:1], vcc
	s_xor_b64 s[0:1], exec, s[0:1]
	s_cbranch_execz .LBB0_146
	s_movk_i32 s3, 0xc7f
	v_cmp_lt_u32_e32 vcc, s3, v0
	s_and_saveexec_b64 s[12:13], vcc
	s_xor_b64 s[16:17], exec, s[12:13]
	s_cbranch_execz .LBB0_109
	s_movk_i32 s3, 0xd1f
	v_cmp_lt_u32_e32 vcc, s3, v0
	s_and_saveexec_b64 s[12:13], vcc
	s_xor_b64 s[18:19], exec, s[12:13]
	s_cbranch_execz .LBB0_72
	s_movk_i32 s3, 0x111f
	v_cmp_lt_u32_e32 vcc, s3, v0
	s_and_saveexec_b64 s[12:13], vcc
	s_xor_b64 s[28:29], exec, s[12:13]
	s_cbranch_execz .LBB0_69
	s_movk_i32 s3, 0x271f
	v_cmp_lt_u32_e32 vcc, s3, v0
	s_and_saveexec_b64 s[12:13], vcc
	s_xor_b64 s[22:23], exec, s[12:13]
	s_cbranch_execz .LBB0_66
	v_add_u32_e32 v2, 0xffffd8e0, v0
	s_mov_b32 s3, 0xba2e8ba3
	v_mul_hi_u32 v3, v2, s3
	v_lshrrev_b32_e32 v0, 8, v3
	v_mul_u32_u24_e32 v0, 0x160, v0
	v_sub_u32_e32 v0, v2, v0
	s_movk_i32 s3, 0xff00
	v_lshlrev_b32_e32 v0, 4, v0
	v_and_or_b32 v66, v3, s3, v83
	s_movk_i32 s3, 0xb00
	v_cmp_gt_u32_e64 s[12:13], s3, v2
	v_lshlrev_b64 v[2:3], 13, v[0:1]
	v_lshl_add_u64 v[2:3], s[42:43], 0, v[2:3]
	v_mov_b32_e32 v67, v1
	v_lshl_add_u64 v[78:79], v[66:67], 2, v[2:3]
	v_mov_b32_e32 v6, 0
	v_mov_b32_e32 v2, 0
	v_mov_b32_e32 v3, 0
	v_mov_b32_e32 v4, 0
	v_mov_b32_e32 v5, 0
	s_and_saveexec_b64 s[30:31], s[12:13]
	s_cbranch_execz .LBB0_35
	global_load_dwordx4 v[2:5], v[78:79], off nt
.LBB0_35:
	s_or_b64 exec, exec, s[30:31]
	v_mov_b32_e32 v7, 0
	v_mov_b32_e32 v8, 0
	v_mov_b32_e32 v9, 0
	s_and_saveexec_b64 s[30:31], s[12:13]
	s_cbranch_execz .LBB0_37
	v_add_co_u32_e32 v6, vcc, 0x2000, v78
	s_nop 1
	v_addc_co_u32_e32 v7, vcc, 0, v79, vcc
	global_load_dwordx4 v[6:9], v[6:7], off nt
.LBB0_37:
	s_or_b64 exec, exec, s[30:31]
	v_mov_b32_e32 v10, 0
	v_mov_b32_e32 v14, 0
	v_mov_b32_e32 v15, 0
	v_mov_b32_e32 v16, 0
	v_mov_b32_e32 v17, 0
	s_and_saveexec_b64 s[30:31], s[12:13]
	s_cbranch_execz .LBB0_39
	v_add_co_u32_e32 v12, vcc, 0x4000, v78
	s_nop 1
	v_addc_co_u32_e32 v13, vcc, 0, v79, vcc
	global_load_dwordx4 v[14:17], v[12:13], off nt
.LBB0_39:
	s_or_b64 exec, exec, s[30:31]
	v_mov_b32_e32 v11, 0
	v_mov_b32_e32 v12, 0
	v_mov_b32_e32 v13, 0
	s_and_saveexec_b64 s[30:31], s[12:13]
	s_cbranch_execz .LBB0_41
	v_add_co_u32_e32 v10, vcc, 0x6000, v78
	s_nop 1
	v_addc_co_u32_e32 v11, vcc, 0, v79, vcc
	global_load_dwordx4 v[10:13], v[10:11], off nt
.LBB0_41:
	s_or_b64 exec, exec, s[30:31]
	v_mov_b32_e32 v18, 0
	v_mov_b32_e32 v22, 0
	v_mov_b32_e32 v23, 0
	v_mov_b32_e32 v24, 0
	v_mov_b32_e32 v25, 0
	s_and_saveexec_b64 s[30:31], s[12:13]
	s_cbranch_execz .LBB0_43
	v_add_co_u32_e32 v20, vcc, 0x8000, v78
	s_nop 1
	v_addc_co_u32_e32 v21, vcc, 0, v79, vcc
	global_load_dwordx4 v[22:25], v[20:21], off nt
.LBB0_43:
	s_or_b64 exec, exec, s[30:31]
	v_mov_b32_e32 v19, 0
	v_mov_b32_e32 v20, 0
	v_mov_b32_e32 v21, 0
	s_and_saveexec_b64 s[30:31], s[12:13]
	s_cbranch_execz .LBB0_45
	v_add_co_u32_e32 v18, vcc, 0xa000, v78
	s_nop 1
	v_addc_co_u32_e32 v19, vcc, 0, v79, vcc
	global_load_dwordx4 v[18:21], v[18:19], off nt
.LBB0_45:
	s_or_b64 exec, exec, s[30:31]
	v_mov_b32_e32 v26, 0
	v_mov_b32_e32 v30, 0
	v_mov_b32_e32 v31, 0
	v_mov_b32_e32 v32, 0
	v_mov_b32_e32 v33, 0
	s_and_saveexec_b64 s[30:31], s[12:13]
	s_cbranch_execz .LBB0_47
	v_add_co_u32_e32 v28, vcc, 0xc000, v78
	s_nop 1
	v_addc_co_u32_e32 v29, vcc, 0, v79, vcc
	global_load_dwordx4 v[30:33], v[28:29], off nt
.LBB0_47:
	s_or_b64 exec, exec, s[30:31]
	v_mov_b32_e32 v27, 0
	v_mov_b32_e32 v28, 0
	v_mov_b32_e32 v29, 0
	s_and_saveexec_b64 s[30:31], s[12:13]
	s_cbranch_execz .LBB0_49
	v_add_co_u32_e32 v26, vcc, 0xe000, v78
	s_nop 1
	v_addc_co_u32_e32 v27, vcc, 0, v79, vcc
	global_load_dwordx4 v[26:29], v[26:27], off nt
.LBB0_49:
	s_or_b64 exec, exec, s[30:31]
	v_mov_b32_e32 v34, 0
	v_mov_b32_e32 v38, 0
	v_mov_b32_e32 v39, 0
	v_mov_b32_e32 v40, 0
	v_mov_b32_e32 v41, 0
	s_and_saveexec_b64 s[30:31], s[12:13]
	s_cbranch_execz .LBB0_51
	v_add_co_u32_e32 v36, vcc, 0x10000, v78
	s_nop 1
	v_addc_co_u32_e32 v37, vcc, 0, v79, vcc
	global_load_dwordx4 v[38:41], v[36:37], off nt
.LBB0_51:
	s_or_b64 exec, exec, s[30:31]
	v_mov_b32_e32 v35, 0
	v_mov_b32_e32 v36, 0
	v_mov_b32_e32 v37, 0
	s_and_saveexec_b64 s[30:31], s[12:13]
	s_cbranch_execz .LBB0_53
	v_add_co_u32_e32 v34, vcc, 0x12000, v78
	s_nop 1
	v_addc_co_u32_e32 v35, vcc, 0, v79, vcc
	global_load_dwordx4 v[34:37], v[34:35], off nt
.LBB0_53:
	s_or_b64 exec, exec, s[30:31]
	v_mov_b32_e32 v42, 0
	v_mov_b32_e32 v46, 0
	v_mov_b32_e32 v47, 0
	v_mov_b32_e32 v48, 0
	v_mov_b32_e32 v49, 0
	s_and_saveexec_b64 s[30:31], s[12:13]
	s_cbranch_execz .LBB0_55
	v_add_co_u32_e32 v44, vcc, 0x14000, v78
	s_nop 1
	v_addc_co_u32_e32 v45, vcc, 0, v79, vcc
	global_load_dwordx4 v[46:49], v[44:45], off nt
.LBB0_55:
	s_or_b64 exec, exec, s[30:31]
	v_mov_b32_e32 v43, 0
	v_mov_b32_e32 v44, 0
	v_mov_b32_e32 v45, 0
	s_and_saveexec_b64 s[30:31], s[12:13]
	s_cbranch_execz .LBB0_57
	v_add_co_u32_e32 v42, vcc, 0x16000, v78
	s_nop 1
	v_addc_co_u32_e32 v43, vcc, 0, v79, vcc
	global_load_dwordx4 v[42:45], v[42:43], off nt
.LBB0_57:
	s_or_b64 exec, exec, s[30:31]
	v_mov_b32_e32 v50, 0
	v_mov_b32_e32 v54, 0
	v_mov_b32_e32 v55, 0
	v_mov_b32_e32 v56, 0
	v_mov_b32_e32 v57, 0
	s_and_saveexec_b64 s[30:31], s[12:13]
	s_cbranch_execz .LBB0_59
	v_add_co_u32_e32 v52, vcc, 0x18000, v78
	s_nop 1
	v_addc_co_u32_e32 v53, vcc, 0, v79, vcc
	global_load_dwordx4 v[54:57], v[52:53], off nt
.LBB0_59:
	s_or_b64 exec, exec, s[30:31]
	v_mov_b32_e32 v51, 0
	v_mov_b32_e32 v52, 0
	v_mov_b32_e32 v53, 0
	s_and_saveexec_b64 s[30:31], s[12:13]
	s_cbranch_execz .LBB0_61
	v_add_co_u32_e32 v50, vcc, 0x1a000, v78
	s_nop 1
	v_addc_co_u32_e32 v51, vcc, 0, v79, vcc
	global_load_dwordx4 v[50:53], v[50:51], off nt
.LBB0_61:
	s_or_b64 exec, exec, s[30:31]
	v_mov_b32_e32 v58, 0
	v_mov_b32_e32 v62, 0
	v_mov_b32_e32 v63, 0
	v_mov_b32_e32 v64, 0
	v_mov_b32_e32 v65, 0
	s_and_saveexec_b64 s[30:31], s[12:13]
	s_cbranch_execz .LBB0_63
	v_add_co_u32_e32 v60, vcc, 0x1c000, v78
	s_nop 1
	v_addc_co_u32_e32 v61, vcc, 0, v79, vcc
	global_load_dwordx4 v[62:65], v[60:61], off nt
.LBB0_63:
	s_or_b64 exec, exec, s[30:31]
	v_mov_b32_e32 v59, 0
	v_mov_b32_e32 v60, 0
	v_mov_b32_e32 v61, 0
	s_and_saveexec_b64 s[30:31], s[12:13]
	s_cbranch_execz .LBB0_65
	v_add_co_u32_e32 v58, vcc, 0x1e000, v78
	s_nop 1
	v_addc_co_u32_e32 v59, vcc, 0, v79, vcc
	global_load_dwordx4 v[58:61], v[58:59], off nt

; DI unsigned cvt_pk_bf16(float lo, float hi) { unsigned r; asm volatile("v_cvt_pk_bf16_f32 %0, %1, %2" : "=v"(r) : "v"(lo), "v"(hi)); return r; }
; DI void conv_witem(const float* W, int K, int Nsrc, bf16_t* dst, const float* rowscale, bool perm_in, int kt, int ntile, int lane, bool glu_rows = false) {
;     const int k0 = kt * 16, c0 = ntile * 256, n4 = lane * 4;
;     const int cdst = c0 + n4;
;     int csrc = cdst;
;     if (perm_in && cdst >= C_RQ && cdst < C_RV) { const int pp = cdst & 63, g = pp >> 5, e = pp & 31; csrc = (cdst & ~63) + ((e < 16) ? g * 16 + e : 32 + g * 16 + (e - 16)); }
;     const bool valid = csrc < Nsrc;
;     const float* src = W + (size_t)k0 * Nsrc + csrc;
;     f32x4 v[16];
; #pragma unroll
;     for (int i = 0; i < 16; ++i) v[i] = valid ? *(const f32x4*)(src + (size_t)i * Nsrc) : (f32x4){0.f, 0.f, 0.f, 0.f};
;     if (rowscale) {
; #pragma unroll
;         for (int i = 0; i < 16; ++i) v[i] *= rowscale[k0 + i];
;     }
;     int drow = cdst;
;     if (glu_rows) { const int hf = cdst >= DFF ? 1 : 0, jj = cdst - hf * DFF; drow = (jj >> 7) * 256 + hf * 128 + (jj & 127); }
;     bf16_t* dp = dst + (size_t)drow * K + k0;
; #pragma unroll
;     for (int j = 0; j < 4; ++j) {
;         u32x4 w0, w1;
;         w0.x = cvt_pk_bf16(v[0][j], v[1][j]); w0.y = cvt_pk_bf16(v[2][j], v[3][j]); w0.z = cvt_pk_bf16(v[4][j], v[5][j]); w0.w = cvt_pk_bf16(v[6][j], v[7][j]);
;         w1.x = cvt_pk_bf16(v[8][j], v[9][j]); w1.y = cvt_pk_bf16(v[10][j], v[11][j]); w1.z = cvt_pk_bf16(v[12][j], v[13][j]); w1.w = cvt_pk_bf16(v[14][j], v[15][j]);
;         *(u32x4*)(dp + (size_t)j * K) = w0; *(u32x4*)(dp + (size_t)j * K + 8) = w1;
;     }
.LBB0_66:
	s_andn2_saveexec_b64 s[12:13], s[22:23]
	s_cbranch_execz .LBB0_68
	v_add_u32_e32 v66, 0xffffeee0, v0
	v_lshlrev_b32_e32 v0, 4, v66
	v_and_b32_e32 v78, 0x7f0, v0
	v_lshlrev_b32_e32 v0, 1, v66
	s_mov_b32 s3, 0x7fffff00
	v_and_or_b32 v0, v0, s3, v83
	v_mov_b64_e32 v[2:3], s[36:37]
	s_mov_b32 s3, 0xb000
	v_mad_u64_u32 v[2:3], s[22:23], v78, s3, v[2:3]
	v_lshl_add_u64 v[58:59], v[0:1], 2, v[2:3]
	v_add_co_u32_e32 v6, vcc, 0xb000, v58
	s_mov_b32 s3, 0x16000
	s_nop 0
	v_addc_co_u32_e32 v7, vcc, 0, v59, vcc
	v_add_co_u32_e32 v10, vcc, s3, v58
	global_load_dwordx4 v[2:5], v[58:59], off nt
	s_nop 0
	global_load_dwordx4 v[6:9], v[6:7], off nt
	v_addc_co_u32_e32 v11, vcc, 0, v59, vcc
	v_add_co_u32_e32 v14, vcc, 0x21000, v58
	s_movk_i32 s3, 0xaff
	s_nop 0
	v_addc_co_u32_e32 v15, vcc, 0, v59, vcc
	v_add_co_u32_e32 v18, vcc, 0x2c000, v58
	global_load_dwordx4 v[10:13], v[10:11], off nt
	s_nop 0
	global_load_dwordx4 v[14:17], v[14:15], off nt
	v_addc_co_u32_e32 v19, vcc, 0, v59, vcc
	v_add_co_u32_e32 v22, vcc, 0x37000, v58
	v_readlane_b32 s22, v253, 3
	s_nop 0
	v_addc_co_u32_e32 v23, vcc, 0, v59, vcc
	v_add_co_u32_e32 v26, vcc, 0x42000, v58
	global_load_dwordx4 v[18:21], v[18:19], off nt
	s_nop 0
	global_load_dwordx4 v[22:25], v[22:23], off nt
	v_addc_co_u32_e32 v27, vcc, 0, v59, vcc
	v_add_co_u32_e32 v30, vcc, 0x4d000, v58
	v_readlane_b32 s23, v253, 4
	s_nop 0
	v_addc_co_u32_e32 v31, vcc, 0, v59, vcc
	v_add_co_u32_e32 v34, vcc, 0x58000, v58
	global_load_dwordx4 v[26:29], v[26:27], off nt
	s_nop 0
	global_load_dwordx4 v[30:33], v[30:31], off nt
	v_addc_co_u32_e32 v35, vcc, 0, v59, vcc
	v_add_co_u32_e32 v38, vcc, 0x63000, v58
	s_nop 1
	v_addc_co_u32_e32 v39, vcc, 0, v59, vcc
	v_add_co_u32_e32 v42, vcc, 0x6e000, v58
	global_load_dwordx4 v[34:37], v[34:35], off nt
	s_nop 0
	global_load_dwordx4 v[38:41], v[38:39], off nt
	v_addc_co_u32_e32 v43, vcc, 0, v59, vcc
	v_add_co_u32_e32 v46, vcc, 0x79000, v58
	s_nop 1
	v_addc_co_u32_e32 v47, vcc, 0, v59, vcc
	v_add_co_u32_e32 v50, vcc, 0x84000, v58
	global_load_dwordx4 v[42:45], v[42:43], off nt
	s_nop 0
	global_load_dwordx4 v[46:49], v[46:47], off nt
	v_addc_co_u32_e32 v51, vcc, 0, v59, vcc
	v_add_co_u32_e32 v54, vcc, 0x8f000, v58
	s_nop 1
	v_addc_co_u32_e32 v55, vcc, 0, v59, vcc
	v_add_co_u32_e32 v60, vcc, 0x9a000, v58
	global_load_dwordx4 v[50:53], v[50:51], off nt
	s_nop 0
	global_load_dwordx4 v[54:57], v[54:55], off nt
	v_addc_co_u32_e32 v61, vcc, 0, v59, vcc
	v_add_co_u32_e32 v62, vcc, 0xa5000, v58
	s_nop 1
	v_addc_co_u32_e32 v63, vcc, 0, v59, vcc
	global_load_dwordx4 v[58:61], v[60:61], off nt
	s_nop 0
	global_load_dwordx4 v[62:65], v[62:63], off nt
	v_cmp_lt_u32_e32 vcc, s3, v66
	s_movk_i32 s3, 0x1000
	s_nop 0
	v_cndmask_b32_e32 v66, 0, v97, vcc
	v_add_lshl_u32 v0, v0, v66, 1
	v_and_b32_e32 v0, 0xffffff00, v0
	v_cndmask_b32_e32 v66, 0, v98, vcc
	v_or3_b32 v66, v66, v84, v0
	v_ashrrev_i32_e32 v67, 31, v66
	v_lshlrev_b64 v[66:67], 12, v[66:67]
	v_lshl_add_u64 v[66:67], s[22:23], 0, v[66:67]
	v_lshlrev_b32_e32 v0, 1, v78
	v_lshl_add_u64 v[66:67], v[66:67], 0, v[0:1]
	s_waitcnt vmcnt(14)
	v_cvt_pk_bf16_f32 v78, v2, v6
	s_waitcnt vmcnt(12)
	v_cvt_pk_bf16_f32 v79, v10, v14
	s_waitcnt vmcnt(10)
	v_cvt_pk_bf16_f32 v80, v18, v22
	s_waitcnt vmcnt(8)
	v_cvt_pk_bf16_f32 v81, v26, v30
	v_add_co_u32_e32 v2, vcc, s3, v66
	s_waitcnt vmcnt(6)
	v_cvt_pk_bf16_f32 v102, v34, v38
	s_waitcnt vmcnt(4)
	v_cvt_pk_bf16_f32 v103, v42, v46
	s_waitcnt vmcnt(2)
	v_cvt_pk_bf16_f32 v104, v50, v54
	s_waitcnt vmcnt(0)
	v_cvt_pk_bf16_f32 v105, v58, v62
	global_store_dwordx4 v[66:67], v[78:81], off
	global_store_dwordx4 v[66:67], v[102:105], off offset:16
	s_nop 0
	v_cvt_pk_bf16_f32 v78, v3, v7
	v_addc_co_u32_e32 v3, vcc, 0, v67, vcc
	v_add_co_u32_e32 v6, vcc, s84, v66
	v_cvt_pk_bf16_f32 v79, v11, v15
	v_cvt_pk_bf16_f32 v80, v19, v23
	v_cvt_pk_bf16_f32 v81, v27, v31
	v_cvt_pk_bf16_f32 v102, v35, v39
	s_nop 1
	v_addc_co_u32_e32 v7, vcc, 0, v67, vcc
	v_cvt_pk_bf16_f32 v103, v43, v47
	v_cvt_pk_bf16_f32 v104, v51, v55
	v_cvt_pk_bf16_f32 v105, v59, v63
	global_store_dwordx4 v[6:7], v[78:81], off offset:-4096
	global_store_dwordx4 v[2:3], v[102:105], off offset:16
	v_add_co_u32_e32 v10, vcc, 0x3000, v66
	v_cvt_pk_bf16_f32 v78, v4, v8
	v_cvt_pk_bf16_f32 v79, v12, v16
	v_cvt_pk_bf16_f32 v80, v20, v24
	v_cvt_pk_bf16_f32 v81, v28, v32
	s_nop 0
	v_cvt_pk_bf16_f32 v102, v36, v40
	v_cvt_pk_bf16_f32 v103, v44, v48
	v_cvt_pk_bf16_f32 v104, v52, v56
	v_cvt_pk_bf16_f32 v105, v60, v64
	global_store_dwordx4 v[6:7], v[78:81], off
	global_store_dwordx4 v[6:7], v[102:105], off offset:16
	v_cvt_pk_bf16_f32 v2, v5, v9
	v_cvt_pk_bf16_f32 v3, v13, v17
	v_cvt_pk_bf16_f32 v4, v21, v25
	v_cvt_pk_bf16_f32 v5, v29, v33
	v_addc_co_u32_e32 v11, vcc, 0, v67, vcc
	v_cvt_pk_bf16_f32 v6, v37, v41
	v_cvt_pk_bf16_f32 v7, v45, v49
	v_cvt_pk_bf16_f32 v8, v53, v57
	v_cvt_pk_bf16_f32 v9, v61, v65
	global_store_dwordx4 v[10:11], v[2:5], off
	global_store_dwordx4 v[10:11], v[6:9], off offset:16

; DI unsigned cvt_pk_bf16(float lo, float hi) { unsigned r; asm volatile("v_cvt_pk_bf16_f32 %0, %1, %2" : "=v"(r) : "v"(lo), "v"(hi)); return r; }
; DI void conv_witem(const float* W, int K, int Nsrc, bf16_t* dst, const float* rowscale, bool perm_in, int kt, int ntile, int lane, bool glu_rows = false) {
;     const int k0 = kt * 16, c0 = ntile * 256, n4 = lane * 4;
;     const int cdst = c0 + n4;
;     int csrc = cdst;
;     if (perm_in && cdst >= C_RQ && cdst < C_RV) { const int pp = cdst & 63, g = pp >> 5, e = pp & 31; csrc = (cdst & ~63) + ((e < 16) ? g * 16 + e : 32 + g * 16 + (e - 16)); }
;     const bool valid = csrc < Nsrc;
;     const float* src = W + (size_t)k0 * Nsrc + csrc;
;     f32x4 v[16];
; #pragma unroll
;     for (int i = 0; i < 16; ++i) v[i] = valid ? *(const f32x4*)(src + (size_t)i * Nsrc) : (f32x4){0.f, 0.f, 0.f, 0.f};
;     if (rowscale) {
; #pragma unroll
;         for (int i = 0; i < 16; ++i) v[i] *= rowscale[k0 + i];
;     }
;     int drow = cdst;
;     if (glu_rows) { const int hf = cdst >= DFF ? 1 : 0, jj = cdst - hf * DFF; drow = (jj >> 7) * 256 + hf * 128 + (jj & 127); }
;     bf16_t* dp = dst + (size_t)drow * K + k0;
; #pragma unroll
;     for (int j = 0; j < 4; ++j) {
;         u32x4 w0, w1;
;         w0.x = cvt_pk_bf16(v[0][j], v[1][j]); w0.y = cvt_pk_bf16(v[2][j], v[3][j]); w0.z = cvt_pk_bf16(v[4][j], v[5][j]); w0.w = cvt_pk_bf16(v[6][j], v[7][j]);
;         w1.x = cvt_pk_bf16(v[8][j], v[9][j]); w1.y = cvt_pk_bf16(v[10][j], v[11][j]); w1.z = cvt_pk_bf16(v[12][j], v[13][j]); w1.w = cvt_pk_bf16(v[14][j], v[15][j]);
;         *(u32x4*)(dp + (size_t)j * K) = w0; *(u32x4*)(dp + (size_t)j * K + 8) = w1;
;     }
.LBB0_69:
	s_andn2_saveexec_b64 s[12:13], s[28:29]
	s_cbranch_execz .LBB0_71
	v_add_u32_e32 v0, 0xfffff2e0, v0
	v_lshlrev_b32_e32 v2, 4, v0
	v_and_b32_e32 v78, 0x7f0, v2
	v_lshlrev_b32_e32 v0, 1, v0
	s_mov_b32 s3, 0x7fffff00
	v_and_or_b32 v66, v0, s3, v83
	v_lshlrev_b32_e32 v0, 13, v78
	v_lshl_add_u64 v[2:3], s[62:63], 0, v[0:1]
	v_mov_b32_e32 v67, v1
	v_lshl_add_u64 v[58:59], v[66:67], 2, v[2:3]
	v_add_co_u32_e32 v6, vcc, 0x2000, v58
	v_readlane_b32 s22, v253, 5
	s_nop 0
	v_addc_co_u32_e32 v7, vcc, 0, v59, vcc
	v_add_co_u32_e32 v10, vcc, 0x4000, v58
	global_load_dwordx4 v[2:5], v[58:59], off nt
	s_nop 0
	global_load_dwordx4 v[6:9], v[6:7], off nt
	v_addc_co_u32_e32 v11, vcc, 0, v59, vcc
	v_add_co_u32_e32 v14, vcc, 0x6000, v58
	v_lshlrev_b64 v[66:67], 12, v[66:67]
	s_nop 0
	v_addc_co_u32_e32 v15, vcc, 0, v59, vcc
	v_add_co_u32_e32 v18, vcc, 0x8000, v58
	global_load_dwordx4 v[10:13], v[10:11], off nt
	s_nop 0
	global_load_dwordx4 v[14:17], v[14:15], off nt
	v_addc_co_u32_e32 v19, vcc, 0, v59, vcc
	v_add_co_u32_e32 v22, vcc, 0xa000, v58
	v_readlane_b32 s23, v253, 6
	s_nop 0
	v_addc_co_u32_e32 v23, vcc, 0, v59, vcc
	v_add_co_u32_e32 v26, vcc, s27, v58
	global_load_dwordx4 v[18:21], v[18:19], off nt
	s_nop 0
	global_load_dwordx4 v[22:25], v[22:23], off nt
	v_addc_co_u32_e32 v27, vcc, 0, v59, vcc
	v_add_co_u32_e32 v30, vcc, 0xe000, v58
	v_lshl_add_u64 v[66:67], s[22:23], 0, v[66:67]
	s_nop 0
	v_addc_co_u32_e32 v31, vcc, 0, v59, vcc
	v_add_co_u32_e32 v34, vcc, 0x10000, v58
	global_load_dwordx4 v[26:29], v[26:27], off nt
	s_nop 0
	global_load_dwordx4 v[30:33], v[30:31], off nt
	v_addc_co_u32_e32 v35, vcc, 0, v59, vcc
	v_add_co_u32_e32 v38, vcc, 0x12000, v58
	v_lshlrev_b32_e32 v0, 1, v78
	s_nop 0
	v_addc_co_u32_e32 v39, vcc, 0, v59, vcc
	v_add_co_u32_e32 v42, vcc, 0x14000, v58
	global_load_dwordx4 v[34:37], v[34:35], off nt
	s_nop 0
	global_load_dwordx4 v[38:41], v[38:39], off nt
	v_addc_co_u32_e32 v43, vcc, 0, v59, vcc
	v_add_co_u32_e32 v46, vcc, 0x16000, v58
	v_lshl_add_u64 v[66:67], v[66:67], 0, v[0:1]
	s_nop 0
	v_addc_co_u32_e32 v47, vcc, 0, v59, vcc
	v_add_co_u32_e32 v50, vcc, 0x18000, v58
	global_load_dwordx4 v[42:45], v[42:43], off nt
	s_nop 0
	global_load_dwordx4 v[46:49], v[46:47], off nt
	v_addc_co_u32_e32 v51, vcc, 0, v59, vcc
	v_add_co_u32_e32 v54, vcc, 0x1a000, v58
	s_movk_i32 s3, 0x1000
	s_nop 0
	v_addc_co_u32_e32 v55, vcc, 0, v59, vcc
	v_add_co_u32_e32 v60, vcc, 0x1c000, v58
	global_load_dwordx4 v[50:53], v[50:51], off nt
	s_nop 0
	global_load_dwordx4 v[54:57], v[54:55], off nt
	v_addc_co_u32_e32 v61, vcc, 0, v59, vcc
	v_add_co_u32_e32 v62, vcc, 0x1e000, v58
	s_nop 1
	v_addc_co_u32_e32 v63, vcc, 0, v59, vcc
	global_load_dwordx4 v[58:61], v[60:61], off nt
	s_nop 0
	global_load_dwordx4 v[62:65], v[62:63], off nt
	s_waitcnt vmcnt(14)
	v_cvt_pk_bf16_f32 v78, v2, v6
	s_waitcnt vmcnt(12)
	v_cvt_pk_bf16_f32 v79, v10, v14
	s_waitcnt vmcnt(10)
	v_cvt_pk_bf16_f32 v80, v18, v22
	s_waitcnt vmcnt(8)
	v_cvt_pk_bf16_f32 v81, v26, v30
	v_add_co_u32_e32 v2, vcc, s3, v66
	s_waitcnt vmcnt(6)
	v_cvt_pk_bf16_f32 v102, v34, v38
	s_waitcnt vmcnt(4)
	v_cvt_pk_bf16_f32 v103, v42, v46
	s_waitcnt vmcnt(2)
	v_cvt_pk_bf16_f32 v104, v50, v54
	s_waitcnt vmcnt(0)
	v_cvt_pk_bf16_f32 v105, v58, v62
	global_store_dwordx4 v[66:67], v[78:81], off
	global_store_dwordx4 v[66:67], v[102:105], off offset:16
	s_nop 0
	v_cvt_pk_bf16_f32 v78, v3, v7
	v_addc_co_u32_e32 v3, vcc, 0, v67, vcc
	v_add_co_u32_e32 v6, vcc, s84, v66
	v_cvt_pk_bf16_f32 v79, v11, v15
	v_cvt_pk_bf16_f32 v80, v19, v23
	v_cvt_pk_bf16_f32 v81, v27, v31
	v_cvt_pk_bf16_f32 v102, v35, v39
	s_nop 1
	v_addc_co_u32_e32 v7, vcc, 0, v67, vcc
	v_cvt_pk_bf16_f32 v103, v43, v47
	v_cvt_pk_bf16_f32 v104, v51, v55
	v_cvt_pk_bf16_f32 v105, v59, v63
	global_store_dwordx4 v[6:7], v[78:81], off offset:-4096
	global_store_dwordx4 v[2:3], v[102:105], off offset:16
	v_add_co_u32_e32 v10, vcc, 0x3000, v66
	v_cvt_pk_bf16_f32 v78, v4, v8
	v_cvt_pk_bf16_f32 v79, v12, v16
	v_cvt_pk_bf16_f32 v80, v20, v24
	v_cvt_pk_bf16_f32 v81, v28, v32
	s_nop 0
	v_cvt_pk_bf16_f32 v102, v36, v40
	v_cvt_pk_bf16_f32 v103, v44, v48
	v_cvt_pk_bf16_f32 v104, v52, v56
	v_cvt_pk_bf16_f32 v105, v60, v64
	global_store_dwordx4 v[6:7], v[78:81], off
	global_store_dwordx4 v[6:7], v[102:105], off offset:16
	v_cvt_pk_bf16_f32 v2, v5, v9
	v_cvt_pk_bf16_f32 v3, v13, v17
	v_cvt_pk_bf16_f32 v4, v21, v25
	v_cvt_pk_bf16_f32 v5, v29, v33
	v_addc_co_u32_e32 v11, vcc, 0, v67, vcc
	v_cvt_pk_bf16_f32 v6, v37, v41
	v_cvt_pk_bf16_f32 v7, v45, v49
	v_cvt_pk_bf16_f32 v8, v53, v57
	v_cvt_pk_bf16_f32 v9, v61, v65
	global_store_dwordx4 v[10:11], v[2:5], off
	global_store_dwordx4 v[10:11], v[6:9], off offset:16

; DI void conv_witem(const float* W, int K, int Nsrc, bf16_t* dst, const float* rowscale, bool perm_in, int kt, int ntile, int lane, bool glu_rows = false) {
;     const int k0 = kt * 16, c0 = ntile * 256, n4 = lane * 4;
;     const int cdst = c0 + n4;
;     int csrc = cdst;
;     if (perm_in && cdst >= C_RQ && cdst < C_RV) { const int pp = cdst & 63, g = pp >> 5, e = pp & 31; csrc = (cdst & ~63) + ((e < 16) ? g * 16 + e : 32 + g * 16 + (e - 16)); }
;     const bool valid = csrc < Nsrc;
;     const float* src = W + (size_t)k0 * Nsrc + csrc;
;     f32x4 v[16];
; #pragma unroll
;     for (int i = 0; i < 16; ++i) v[i] = valid ? *(const f32x4*)(src + (size_t)i * Nsrc) : (f32x4){0.f, 0.f, 0.f, 0.f};
.LBB0_72:
	s_andn2_saveexec_b64 s[18:19], s[18:19]
	s_cbranch_execz .LBB0_108
	v_lshlrev_b32_e32 v2, 4, v0
	v_lshlrev_b32_e32 v0, 3, v0
	v_and_b32_e32 v101, 0x1f0, v2
	v_and_b32_e32 v0, 0x7f00, v0
	v_mov_b64_e32 v[2:3], s[56:57]
	v_mov_b32_e32 v8, v1
	v_mov_b32_e32 v9, v1
	v_add_u32_e32 v78, v0, v85
	v_mad_u64_u32 v[2:3], s[22:23], v101, s30, v[2:3]
	v_mov_b32_e32 v79, v1
	v_mov_b32_e32 v10, v1
	v_mov_b32_e32 v11, v1
	v_mov_b64_e32 v[4:5], v[8:9]
	v_cmp_gt_i32_e64 s[12:13], s31, v78
	v_lshl_add_u64 v[80:81], v[78:79], 2, v[2:3]
	v_mov_b64_e32 v[6:7], v[10:11]
	s_and_saveexec_b64 s[22:23], s[12:13]
	s_cbranch_execz .LBB0_75
	global_load_dwordx4 v[4:7], v[80:81], off nt
.LBB0_75:
	s_or_b64 exec, exec, s[22:23]
	s_and_saveexec_b64 s[22:23], s[12:13]
	s_cbranch_execz .LBB0_77
	v_add_co_u32_e32 v2, vcc, 0x1000, v80
	s_nop 1
	v_addc_co_u32_e32 v3, vcc, 0, v81, vcc
	global_load_dwordx4 v[8:11], v[2:3], off offset:1024 nt
.LBB0_77:
	s_or_b64 exec, exec, s[22:23]
	v_mov_b32_e32 v2, v1
	v_mov_b32_e32 v3, v1
	v_mov_b32_e32 v0, v1
	v_mov_b64_e32 v[14:15], v[2:3]
	v_mov_b64_e32 v[12:13], v[0:1]
	s_and_saveexec_b64 s[22:23], s[12:13]
	s_cbranch_execz .LBB0_79
	v_add_co_u32_e32 v12, vcc, 0x2000, v80
	s_nop 1
	v_addc_co_u32_e32 v13, vcc, 0, v81, vcc
	global_load_dwordx4 v[12:15], v[12:13], off offset:2048 nt
.LBB0_79:
	s_or_b64 exec, exec, s[22:23]
	v_mov_b64_e32 v[18:19], v[2:3]
	v_mov_b64_e32 v[16:17], v[0:1]
	s_and_saveexec_b64 s[22:23], s[12:13]
	s_cbranch_execz .LBB0_81
	v_add_co_u32_e32 v2, vcc, 0x3000, v80
	s_nop 1
	v_addc_co_u32_e32 v3, vcc, 0, v81, vcc
	global_load_dwordx4 v[16:19], v[2:3], off offset:3072 nt
.LBB0_81:
	s_or_b64 exec, exec, s[22:23]
	v_mov_b32_e32 v2, v1
	v_mov_b32_e32 v3, v1
	v_mov_b32_e32 v0, v1
	v_mov_b64_e32 v[22:23], v[2:3]
	v_mov_b64_e32 v[20:21], v[0:1]
	s_and_saveexec_b64 s[22:23], s[12:13]
	s_cbranch_execz .LBB0_83
	v_add_co_u32_e32 v20, vcc, 0x5000, v80
	s_nop 1
	v_addc_co_u32_e32 v21, vcc, 0, v81, vcc
	global_load_dwordx4 v[20:23], v[20:21], off nt
.LBB0_83:
	s_or_b64 exec, exec, s[22:23]
	v_mov_b64_e32 v[26:27], v[2:3]
	v_mov_b64_e32 v[24:25], v[0:1]
	s_and_saveexec_b64 s[22:23], s[12:13]
	s_cbranch_execz .LBB0_85
	v_add_co_u32_e32 v2, vcc, 0x6000, v80
	s_nop 1
	v_addc_co_u32_e32 v3, vcc, 0, v81, vcc
	global_load_dwordx4 v[24:27], v[2:3], off offset:1024 nt
.LBB0_85:
	s_or_b64 exec, exec, s[22:23]
	v_mov_b32_e32 v2, v1
	v_mov_b32_e32 v3, v1
	v_mov_b32_e32 v0, v1
	v_mov_b64_e32 v[30:31], v[2:3]
	v_mov_b64_e32 v[28:29], v[0:1]
	s_and_saveexec_b64 s[22:23], s[12:13]
	s_cbranch_execz .LBB0_87
	v_add_co_u32_e32 v28, vcc, 0x7000, v80
	s_nop 1
	v_addc_co_u32_e32 v29, vcc, 0, v81, vcc
	global_load_dwordx4 v[28:31], v[28:29], off offset:2048 nt
.LBB0_87:
	s_or_b64 exec, exec, s[22:23]
	v_mov_b64_e32 v[34:35], v[2:3]
	v_mov_b64_e32 v[32:33], v[0:1]
	s_and_saveexec_b64 s[22:23], s[12:13]
	s_cbranch_execz .LBB0_89
	v_add_co_u32_e32 v2, vcc, 0x8000, v80
	s_nop 1
	v_addc_co_u32_e32 v3, vcc, 0, v81, vcc
	global_load_dwordx4 v[32:35], v[2:3], off offset:3072 nt
.LBB0_89:
	s_or_b64 exec, exec, s[22:23]
	v_mov_b32_e32 v2, v1
	v_mov_b32_e32 v3, v1
	v_mov_b32_e32 v0, v1
	v_mov_b64_e32 v[38:39], v[2:3]
	v_mov_b64_e32 v[36:37], v[0:1]
	s_and_saveexec_b64 s[22:23], s[12:13]
	s_cbranch_execz .LBB0_91
	v_add_co_u32_e32 v36, vcc, 0xa000, v80
	s_nop 1
	v_addc_co_u32_e32 v37, vcc, 0, v81, vcc
	global_load_dwordx4 v[36:39], v[36:37], off nt
.LBB0_91:
	s_or_b64 exec, exec, s[22:23]
	v_mov_b64_e32 v[42:43], v[2:3]
	v_mov_b64_e32 v[40:41], v[0:1]
	s_and_saveexec_b64 s[22:23], s[12:13]
	s_cbranch_execz .LBB0_93
	v_add_co_u32_e32 v2, vcc, 0xb000, v80
	s_nop 1
	v_addc_co_u32_e32 v3, vcc, 0, v81, vcc
	global_load_dwordx4 v[40:43], v[2:3], off offset:1024 nt
.LBB0_93:
	s_or_b64 exec, exec, s[22:23]
	v_mov_b32_e32 v2, v1
	v_mov_b32_e32 v3, v1
	v_mov_b32_e32 v0, v1
	v_mov_b64_e32 v[46:47], v[2:3]
	v_mov_b64_e32 v[44:45], v[0:1]
	s_and_saveexec_b64 s[22:23], s[12:13]
	s_cbranch_execz .LBB0_95
	v_add_co_u32_e32 v44, vcc, 0xc000, v80
	s_nop 1
	v_addc_co_u32_e32 v45, vcc, 0, v81, vcc
	global_load_dwordx4 v[44:47], v[44:45], off offset:2048 nt
; DI void conv_witem(const float* W, int K, int Nsrc, bf16_t* dst, const float* rowscale, bool perm_in, int kt, int ntile, int lane, bool glu_rows = false) {
;     ...
;     const float* src = W + (size_t)k0 * Nsrc + csrc;
;     f32x4 v[16];
; #pragma unroll
;     for (int i = 0; i < 16; ++i) v[i] = valid ? *(const f32x4*)(src + (size_t)i * Nsrc) : (f32x4){0.f, 0.f, 0.f, 0.f};
;     if (rowscale) {
; #pragma unroll
;         for (int i = 0; i < 16; ++i) v[i] *= rowscale[k0 + i];
;     }
.LBB0_95:
	s_or_b64 exec, exec, s[22:23]
	v_mov_b64_e32 v[50:51], v[2:3]
	v_mov_b64_e32 v[48:49], v[0:1]
	s_and_saveexec_b64 s[22:23], s[12:13]
	s_cbranch_execz .LBB0_97
	v_add_co_u32_e32 v2, vcc, 0xd000, v80
	s_nop 1
	v_addc_co_u32_e32 v3, vcc, 0, v81, vcc
	global_load_dwordx4 v[48:51], v[2:3], off offset:3072 nt
.LBB0_97:
	s_or_b64 exec, exec, s[22:23]
	v_mov_b32_e32 v2, v1
	v_mov_b32_e32 v3, v1
	v_mov_b32_e32 v0, v1
	v_mov_b64_e32 v[54:55], v[2:3]
	v_mov_b64_e32 v[52:53], v[0:1]
	s_and_saveexec_b64 s[22:23], s[12:13]
	s_cbranch_execz .LBB0_99
	v_add_co_u32_e32 v52, vcc, 0xf000, v80
	s_nop 1
	v_addc_co_u32_e32 v53, vcc, 0, v81, vcc
	global_load_dwordx4 v[52:55], v[52:53], off nt
.LBB0_99:
	s_or_b64 exec, exec, s[22:23]
	v_mov_b64_e32 v[58:59], v[2:3]
	v_mov_b64_e32 v[56:57], v[0:1]
	s_and_saveexec_b64 s[22:23], s[12:13]
	s_cbranch_execz .LBB0_101
	v_add_co_u32_e32 v2, vcc, 0x10000, v80
	s_nop 1
	v_addc_co_u32_e32 v3, vcc, 0, v81, vcc
	global_load_dwordx4 v[56:59], v[2:3], off offset:1024 nt
.LBB0_101:
	s_or_b64 exec, exec, s[22:23]
	v_mov_b32_e32 v2, v1
	v_mov_b32_e32 v3, v1
	v_mov_b32_e32 v0, v1
	v_mov_b64_e32 v[62:63], v[2:3]
	v_mov_b64_e32 v[60:61], v[0:1]
	s_and_saveexec_b64 s[22:23], s[12:13]
	s_cbranch_execz .LBB0_103
	v_add_co_u32_e32 v60, vcc, 0x11000, v80
	s_nop 1
	v_addc_co_u32_e32 v61, vcc, 0, v81, vcc
	global_load_dwordx4 v[60:63], v[60:61], off offset:2048 nt
.LBB0_103:
	s_or_b64 exec, exec, s[22:23]
	v_mov_b64_e32 v[66:67], v[2:3]
	v_mov_b64_e32 v[64:65], v[0:1]
	s_and_saveexec_b64 s[22:23], s[12:13]
	s_cbranch_execz .LBB0_105
	v_add_co_u32_e32 v2, vcc, 0x12000, v80
	s_nop 1
	v_addc_co_u32_e32 v3, vcc, 0, v81, vcc
	global_load_dwordx4 v[64:67], v[2:3], off offset:3072 nt
.LBB0_105:
	s_or_b64 exec, exec, s[22:23]
	v_readlane_b32 s12, v253, 9
	v_readlane_b32 s13, v253, 10
	s_and_b64 vcc, exec, s[12:13]
	s_cbranch_vccz .LBB0_107
	v_lshlrev_b32_e32 v0, 2, v101
	global_load_dwordx4 v[102:105], v0, s[52:53]
	global_load_dwordx4 v[106:109], v0, s[52:53] offset:16 nt
	global_load_dwordx4 v[110:113], v0, s[52:53] offset:32 nt
	global_load_dwordx4 v[114:117], v0, s[52:53] offset:48 nt
	s_waitcnt vmcnt(3)
	v_pk_mul_f32 v[6:7], v[6:7], v[102:103] op_sel_hi:[1,0]
	v_pk_mul_f32 v[4:5], v[4:5], v[102:103] op_sel_hi:[1,0]
	v_pk_mul_f32 v[10:11], v[10:11], v[102:103] op_sel:[0,1]
	v_pk_mul_f32 v[8:9], v[8:9], v[102:103] op_sel:[0,1]
	v_mov_b32_e32 v0, v105
	s_waitcnt vmcnt(2)
	v_mov_b32_e32 v2, v109
	s_waitcnt vmcnt(1)
	v_mov_b32_e32 v80, v113
	s_waitcnt vmcnt(0)
	v_mov_b32_e32 v102, v117
	v_pk_mul_f32 v[14:15], v[14:15], v[104:105] op_sel_hi:[1,0]
	v_pk_mul_f32 v[12:13], v[12:13], v[104:105] op_sel_hi:[1,0]
	v_pk_mul_f32 v[22:23], v[22:23], v[106:107] op_sel_hi:[1,0]
	v_pk_mul_f32 v[20:21], v[20:21], v[106:107] op_sel_hi:[1,0]
	v_pk_mul_f32 v[26:27], v[26:27], v[106:107] op_sel:[0,1]
	v_pk_mul_f32 v[24:25], v[24:25], v[106:107] op_sel:[0,1]
	v_pk_mul_f32 v[30:31], v[30:31], v[108:109] op_sel_hi:[1,0]
	v_pk_mul_f32 v[28:29], v[28:29], v[108:109] op_sel_hi:[1,0]
	v_pk_mul_f32 v[38:39], v[38:39], v[110:111] op_sel_hi:[1,0]
	v_pk_mul_f32 v[36:37], v[36:37], v[110:111] op_sel_hi:[1,0]
	v_pk_mul_f32 v[42:43], v[42:43], v[110:111] op_sel:[0,1]
	v_pk_mul_f32 v[40:41], v[40:41], v[110:111] op_sel:[0,1]
	v_pk_mul_f32 v[46:47], v[46:47], v[112:113] op_sel_hi:[1,0]
	v_pk_mul_f32 v[44:45], v[44:45], v[112:113] op_sel_hi:[1,0]
	v_pk_mul_f32 v[54:55], v[54:55], v[114:115] op_sel_hi:[1,0]
	v_pk_mul_f32 v[52:53], v[52:53], v[114:115] op_sel_hi:[1,0]
	v_pk_mul_f32 v[58:59], v[58:59], v[114:115] op_sel:[0,1]
	v_pk_mul_f32 v[56:57], v[56:57], v[114:115] op_sel:[0,1]
	v_pk_mul_f32 v[62:63], v[62:63], v[116:117] op_sel_hi:[1,0]
	v_pk_mul_f32 v[60:61], v[60:61], v[116:117] op_sel_hi:[1,0]
	v_pk_mul_f32 v[18:19], v[18:19], v[0:1] op_sel_hi:[1,0]
	v_pk_mul_f32 v[16:17], v[16:17], v[0:1] op_sel_hi:[1,0]
	v_pk_mul_f32 v[34:35], v[34:35], v[2:3] op_sel_hi:[1,0]
	v_pk_mul_f32 v[32:33], v[32:33], v[2:3] op_sel_hi:[1,0]
	v_pk_mul_f32 v[50:51], v[50:51], v[80:81] op_sel_hi:[1,0]
	v_pk_mul_f32 v[48:49], v[48:49], v[80:81] op_sel_hi:[1,0]
	v_pk_mul_f32 v[66:67], v[66:67], v[102:103] op_sel_hi:[1,0]
	v_pk_mul_f32 v[64:65], v[64:65], v[102:103] op_sel_hi:[1,0]

; DI void conv_witem(const float* W, int K, int Nsrc, bf16_t* dst, const float* rowscale, bool perm_in, int kt, int ntile, int lane, bool glu_rows = false) {
;     const int k0 = kt * 16, c0 = ntile * 256, n4 = lane * 4;
;     const int cdst = c0 + n4;
;     int csrc = cdst;
;     if (perm_in && cdst >= C_RQ && cdst < C_RV) { const int pp = cdst & 63, g = pp >> 5, e = pp & 31; csrc = (cdst & ~63) + ((e < 16) ? g * 16 + e : 32 + g * 16 + (e - 16)); }
;     const bool valid = csrc < Nsrc;
;     const float* src = W + (size_t)k0 * Nsrc + csrc;
;     f32x4 v[16];
; #pragma unroll
;     for (int i = 0; i < 16; ++i) v[i] = valid ? *(const f32x4*)(src + (size_t)i * Nsrc) : (f32x4){0.f, 0.f, 0.f, 0.f};
.LBB0_109:
	s_andn2_saveexec_b64 s[16:17], s[16:17]
	s_cbranch_execz .LBB0_145
	v_lshlrev_b32_e32 v2, 4, v0
	v_lshlrev_b32_e32 v0, 3, v0
	v_and_b32_e32 v0, 0x7f00, v0
	v_add_u32_e32 v78, v0, v86
	s_movk_i32 s3, 0x3c0
	v_and_b32_e32 v101, 0x1f0, v2
	v_cmp_gt_i32_e64 s[12:13], s3, v78
	v_mov_b64_e32 v[2:3], s[54:55]
	s_movk_i32 s3, 0xf00
	v_mov_b32_e32 v6, v1
	v_mov_b32_e32 v7, v1
	v_mad_u64_u32 v[2:3], s[18:19], v101, s3, v[2:3]
	v_mov_b32_e32 v79, v1
	v_mov_b32_e32 v4, v1
	v_mov_b32_e32 v5, v1
	v_mov_b64_e32 v[10:11], v[6:7]
	v_lshl_add_u64 v[80:81], v[78:79], 2, v[2:3]
	v_mov_b64_e32 v[8:9], v[4:5]
	s_and_saveexec_b64 s[18:19], s[12:13]
	s_cbranch_execz .LBB0_112
	global_load_dwordx4 v[8:11], v[80:81], off nt
.LBB0_112:
	s_or_b64 exec, exec, s[18:19]
	s_and_saveexec_b64 s[18:19], s[12:13]
	s_cbranch_execz .LBB0_114
	global_load_dwordx4 v[4:7], v[80:81], off offset:3840 nt
.LBB0_114:
	s_or_b64 exec, exec, s[18:19]
	v_mov_b32_e32 v2, v1
	v_mov_b32_e32 v3, v1
	v_mov_b32_e32 v0, v1
	v_mov_b64_e32 v[14:15], v[2:3]
	v_mov_b64_e32 v[12:13], v[0:1]
	s_and_saveexec_b64 s[18:19], s[12:13]
	s_cbranch_execz .LBB0_116
	v_add_co_u32_e32 v12, vcc, 0x1000, v80
	s_nop 1
	v_addc_co_u32_e32 v13, vcc, 0, v81, vcc
	global_load_dwordx4 v[12:15], v[12:13], off offset:3584 nt
.LBB0_116:
	s_or_b64 exec, exec, s[18:19]
	v_mov_b64_e32 v[18:19], v[2:3]
	v_mov_b64_e32 v[16:17], v[0:1]
	s_and_saveexec_b64 s[18:19], s[12:13]
	s_cbranch_execz .LBB0_118
	v_add_co_u32_e32 v2, vcc, 0x2000, v80
	s_nop 1
	v_addc_co_u32_e32 v3, vcc, 0, v81, vcc
	global_load_dwordx4 v[16:19], v[2:3], off offset:3328 nt
.LBB0_118:
	s_or_b64 exec, exec, s[18:19]
	v_mov_b32_e32 v2, v1
	v_mov_b32_e32 v3, v1
	v_mov_b32_e32 v0, v1
	v_mov_b64_e32 v[22:23], v[2:3]
	v_mov_b64_e32 v[20:21], v[0:1]
	s_and_saveexec_b64 s[18:19], s[12:13]
	s_cbranch_execz .LBB0_120
	v_add_co_u32_e32 v20, vcc, 0x3000, v80
	s_nop 1
	v_addc_co_u32_e32 v21, vcc, 0, v81, vcc
	global_load_dwordx4 v[20:23], v[20:21], off offset:3072 nt
.LBB0_120:
	s_or_b64 exec, exec, s[18:19]
	v_mov_b64_e32 v[26:27], v[2:3]
	v_mov_b64_e32 v[24:25], v[0:1]
	s_and_saveexec_b64 s[18:19], s[12:13]
	s_cbranch_execz .LBB0_122
	v_add_co_u32_e32 v2, vcc, 0x4000, v80
	s_nop 1
	v_addc_co_u32_e32 v3, vcc, 0, v81, vcc
	global_load_dwordx4 v[24:27], v[2:3], off offset:2816 nt
.LBB0_122:
	s_or_b64 exec, exec, s[18:19]
	v_mov_b32_e32 v2, v1
	v_mov_b32_e32 v3, v1
	v_mov_b32_e32 v0, v1
	v_mov_b64_e32 v[30:31], v[2:3]
	v_mov_b64_e32 v[28:29], v[0:1]
	s_and_saveexec_b64 s[18:19], s[12:13]
	s_cbranch_execz .LBB0_124
	v_add_co_u32_e32 v28, vcc, 0x5000, v80
	s_nop 1
	v_addc_co_u32_e32 v29, vcc, 0, v81, vcc
	global_load_dwordx4 v[28:31], v[28:29], off offset:2560 nt
.LBB0_124:
	s_or_b64 exec, exec, s[18:19]
	v_mov_b64_e32 v[34:35], v[2:3]
	v_mov_b64_e32 v[32:33], v[0:1]
	s_and_saveexec_b64 s[18:19], s[12:13]
	s_cbranch_execz .LBB0_126
	v_add_co_u32_e32 v2, vcc, 0x6000, v80
	s_nop 1
	v_addc_co_u32_e32 v3, vcc, 0, v81, vcc
	global_load_dwordx4 v[32:35], v[2:3], off offset:2304 nt
.LBB0_126:
	s_or_b64 exec, exec, s[18:19]
	v_mov_b32_e32 v2, v1
	v_mov_b32_e32 v3, v1
	v_mov_b32_e32 v0, v1
	v_mov_b64_e32 v[38:39], v[2:3]
	v_mov_b64_e32 v[36:37], v[0:1]
	s_and_saveexec_b64 s[18:19], s[12:13]
	s_cbranch_execz .LBB0_128
	v_add_co_u32_e32 v36, vcc, 0x7000, v80
	s_nop 1
	v_addc_co_u32_e32 v37, vcc, 0, v81, vcc
	global_load_dwordx4 v[36:39], v[36:37], off offset:2048 nt
.LBB0_128:
	s_or_b64 exec, exec, s[18:19]
	v_mov_b64_e32 v[42:43], v[2:3]
	v_mov_b64_e32 v[40:41], v[0:1]
	s_and_saveexec_b64 s[18:19], s[12:13]
	s_cbranch_execz .LBB0_130
	v_add_co_u32_e32 v2, vcc, 0x8000, v80
	s_nop 1
	v_addc_co_u32_e32 v3, vcc, 0, v81, vcc
	global_load_dwordx4 v[40:43], v[2:3], off offset:1792 nt
.LBB0_130:
	s_or_b64 exec, exec, s[18:19]
	v_mov_b32_e32 v2, v1
	v_mov_b32_e32 v3, v1
	v_mov_b32_e32 v0, v1
	v_mov_b64_e32 v[46:47], v[2:3]
	v_mov_b64_e32 v[44:45], v[0:1]
	s_and_saveexec_b64 s[18:19], s[12:13]
	s_cbranch_execz .LBB0_132
	v_add_co_u32_e32 v44, vcc, 0x9000, v80
	s_nop 1
	v_addc_co_u32_e32 v45, vcc, 0, v81, vcc
	global_load_dwordx4 v[44:47], v[44:45], off offset:1536 nt
; DI void conv_witem(const float* W, int K, int Nsrc, bf16_t* dst, const float* rowscale, bool perm_in, int kt, int ntile, int lane, bool glu_rows = false) {
;     ...
;     const float* src = W + (size_t)k0 * Nsrc + csrc;
;     f32x4 v[16];
; #pragma unroll
;     for (int i = 0; i < 16; ++i) v[i] = valid ? *(const f32x4*)(src + (size_t)i * Nsrc) : (f32x4){0.f, 0.f, 0.f, 0.f};
;     if (rowscale) {
; #pragma unroll
;         for (int i = 0; i < 16; ++i) v[i] *= rowscale[k0 + i];
.LBB0_132:
	s_or_b64 exec, exec, s[18:19]
	v_mov_b64_e32 v[50:51], v[2:3]
	v_mov_b64_e32 v[48:49], v[0:1]
	s_and_saveexec_b64 s[18:19], s[12:13]
	s_cbranch_execz .LBB0_134
	v_add_co_u32_e32 v2, vcc, 0xa000, v80
	s_nop 1
	v_addc_co_u32_e32 v3, vcc, 0, v81, vcc
	global_load_dwordx4 v[48:51], v[2:3], off offset:1280 nt
.LBB0_134:
	s_or_b64 exec, exec, s[18:19]
	v_mov_b32_e32 v2, v1
	v_mov_b32_e32 v3, v1
	v_mov_b32_e32 v0, v1
	v_mov_b64_e32 v[54:55], v[2:3]
	v_mov_b64_e32 v[52:53], v[0:1]
	s_and_saveexec_b64 s[18:19], s[12:13]
	s_cbranch_execz .LBB0_136
	v_add_co_u32_e32 v52, vcc, 0xb000, v80
	s_nop 1
	v_addc_co_u32_e32 v53, vcc, 0, v81, vcc
	global_load_dwordx4 v[52:55], v[52:53], off offset:1024 nt
.LBB0_136:
	s_or_b64 exec, exec, s[18:19]
	v_mov_b64_e32 v[58:59], v[2:3]
	v_mov_b64_e32 v[56:57], v[0:1]
	s_and_saveexec_b64 s[18:19], s[12:13]
	s_cbranch_execz .LBB0_138
	v_add_co_u32_e32 v2, vcc, 0xc000, v80
	s_nop 1
	v_addc_co_u32_e32 v3, vcc, 0, v81, vcc
	global_load_dwordx4 v[56:59], v[2:3], off offset:768 nt
.LBB0_138:
	s_or_b64 exec, exec, s[18:19]
	v_mov_b32_e32 v2, v1
	v_mov_b32_e32 v3, v1
	v_mov_b32_e32 v0, v1
	v_mov_b64_e32 v[62:63], v[2:3]
	v_mov_b64_e32 v[60:61], v[0:1]
	s_and_saveexec_b64 s[18:19], s[12:13]
	s_cbranch_execz .LBB0_140
	v_add_co_u32_e32 v60, vcc, 0xd000, v80
	s_nop 1
	v_addc_co_u32_e32 v61, vcc, 0, v81, vcc
	global_load_dwordx4 v[60:63], v[60:61], off offset:512 nt
.LBB0_140:
	s_or_b64 exec, exec, s[18:19]
	v_mov_b64_e32 v[66:67], v[2:3]
	v_mov_b64_e32 v[64:65], v[0:1]
	s_and_saveexec_b64 s[18:19], s[12:13]
	s_cbranch_execz .LBB0_142
	v_add_co_u32_e32 v2, vcc, 0xe000, v80
	s_nop 1
	v_addc_co_u32_e32 v3, vcc, 0, v81, vcc
	global_load_dwordx4 v[64:67], v[2:3], off offset:256 nt
.LBB0_142:
	s_or_b64 exec, exec, s[18:19]
	v_readlane_b32 s12, v253, 13
	v_readlane_b32 s13, v253, 14
	s_and_b64 vcc, exec, s[12:13]
	s_cbranch_vccz .LBB0_144
	v_lshlrev_b32_e32 v0, 2, v101
	global_load_dwordx4 v[102:105], v0, s[82:83]
	global_load_dwordx4 v[106:109], v0, s[82:83] offset:16 nt
	global_load_dwordx4 v[110:113], v0, s[82:83] offset:32 nt
	global_load_dwordx4 v[114:117], v0, s[82:83] offset:48 nt
	s_waitcnt vmcnt(3)
	v_pk_mul_f32 v[10:11], v[10:11], v[102:103] op_sel_hi:[1,0]
	v_pk_mul_f32 v[8:9], v[8:9], v[102:103] op_sel_hi:[1,0]
	v_pk_mul_f32 v[6:7], v[6:7], v[102:103] op_sel:[0,1]
	v_pk_mul_f32 v[4:5], v[4:5], v[102:103] op_sel:[0,1]
	v_mov_b32_e32 v0, v105
	s_waitcnt vmcnt(2)
	v_mov_b32_e32 v2, v109
	s_waitcnt vmcnt(1)
	v_mov_b32_e32 v80, v113
	s_waitcnt vmcnt(0)
	v_mov_b32_e32 v102, v117
	v_pk_mul_f32 v[14:15], v[14:15], v[104:105] op_sel_hi:[1,0]
	v_pk_mul_f32 v[12:13], v[12:13], v[104:105] op_sel_hi:[1,0]
	v_pk_mul_f32 v[22:23], v[22:23], v[106:107] op_sel_hi:[1,0]
	v_pk_mul_f32 v[20:21], v[20:21], v[106:107] op_sel_hi:[1,0]
	v_pk_mul_f32 v[26:27], v[26:27], v[106:107] op_sel:[0,1]
	v_pk_mul_f32 v[24:25], v[24:25], v[106:107] op_sel:[0,1]
	v_pk_mul_f32 v[30:31], v[30:31], v[108:109] op_sel_hi:[1,0]
	v_pk_mul_f32 v[28:29], v[28:29], v[108:109] op_sel_hi:[1,0]
	v_pk_mul_f32 v[38:39], v[38:39], v[110:111] op_sel_hi:[1,0]
	v_pk_mul_f32 v[36:37], v[36:37], v[110:111] op_sel_hi:[1,0]
	v_pk_mul_f32 v[42:43], v[42:43], v[110:111] op_sel:[0,1]
	v_pk_mul_f32 v[40:41], v[40:41], v[110:111] op_sel:[0,1]
	v_pk_mul_f32 v[46:47], v[46:47], v[112:113] op_sel_hi:[1,0]
	v_pk_mul_f32 v[44:45], v[44:45], v[112:113] op_sel_hi:[1,0]
	v_pk_mul_f32 v[54:55], v[54:55], v[114:115] op_sel_hi:[1,0]
	v_pk_mul_f32 v[52:53], v[52:53], v[114:115] op_sel_hi:[1,0]
	v_pk_mul_f32 v[58:59], v[58:59], v[114:115] op_sel:[0,1]
	v_pk_mul_f32 v[56:57], v[56:57], v[114:115] op_sel:[0,1]
	v_pk_mul_f32 v[62:63], v[62:63], v[116:117] op_sel_hi:[1,0]
	v_pk_mul_f32 v[60:61], v[60:61], v[116:117] op_sel_hi:[1,0]
	v_pk_mul_f32 v[18:19], v[18:19], v[0:1] op_sel_hi:[1,0]
	v_pk_mul_f32 v[16:17], v[16:17], v[0:1] op_sel_hi:[1,0]
	v_pk_mul_f32 v[34:35], v[34:35], v[2:3] op_sel_hi:[1,0]
	v_pk_mul_f32 v[32:33], v[32:33], v[2:3] op_sel_hi:[1,0]
	v_pk_mul_f32 v[50:51], v[50:51], v[80:81] op_sel_hi:[1,0]
	v_pk_mul_f32 v[48:49], v[48:49], v[80:81] op_sel_hi:[1,0]
	v_pk_mul_f32 v[66:67], v[66:67], v[102:103] op_sel_hi:[1,0]
	v_pk_mul_f32 v[64:65], v[64:65], v[102:103] op_sel_hi:[1,0]

; DI void conv_witem(const float* W, int K, int Nsrc, bf16_t* dst, const float* rowscale, bool perm_in, int kt, int ntile, int lane, bool glu_rows = false) {
;     const int k0 = kt * 16, c0 = ntile * 256, n4 = lane * 4;
;     const int cdst = c0 + n4;
;     int csrc = cdst;
;     if (perm_in && cdst >= C_RQ && cdst < C_RV) { const int pp = cdst & 63, g = pp >> 5, e = pp & 31; csrc = (cdst & ~63) + ((e < 16) ? g * 16 + e : 32 + g * 16 + (e - 16)); }
;     const bool valid = csrc < Nsrc;
;     const float* src = W + (size_t)k0 * Nsrc + csrc;
;     f32x4 v[16];
; #pragma unroll
;     for (int i = 0; i < 16; ++i) v[i] = valid ? *(const f32x4*)(src + (size_t)i * Nsrc) : (f32x4){0.f, 0.f, 0.f, 0.f};
.LBB0_146:
	s_andn2_saveexec_b64 s[0:1], s[0:1]
	s_cbranch_execz .LBB0_180
	v_ashrrev_i32_e32 v2, 31, v0
	v_lshrrev_b32_e32 v2, 25, v2
	v_add_u32_e32 v2, v0, v2
	v_and_b32_e32 v3, 0xfffff80, v2
	v_sub_u32_e32 v0, v0, v3
	v_lshlrev_b32_e32 v66, 4, v0
	v_lshlrev_b32_e32 v0, 1, v2
	v_and_b32_e32 v0, 0xffffff00, v0
	v_or_b32_e32 v78, v0, v83
	s_movk_i32 s3, 0x1fc0
	v_add_u32_e32 v2, 0xfffff2c0, v78
	v_bitop3_b32 v0, v0, s3, v83 bitop3:0xc8
	v_add_u32_e32 v0, v0, v87
	v_cmp_gt_u32_e32 vcc, s31, v2
	s_movk_i32 s3, 0x1740
	v_mov_b64_e32 v[4:5], s[80:81]
	v_cndmask_b32_e32 v2, v78, v0, vcc
	v_cmp_gt_i32_e64 s[12:13], s3, v2
	s_movk_i32 s3, 0x5d00
	v_mad_i64_i32 v[4:5], s[16:17], v66, s3, v[4:5]
	v_ashrrev_i32_e32 v3, 31, v2
	v_lshl_add_u64 v[80:81], v[2:3], 2, v[4:5]
	v_mov_b32_e32 v6, 0
	v_mov_b32_e32 v2, 0
	v_mov_b32_e32 v3, 0
	v_mov_b32_e32 v4, 0
	v_mov_b32_e32 v5, 0
	s_and_saveexec_b64 s[16:17], s[12:13]
	s_cbranch_execz .LBB0_149
	global_load_dwordx4 v[2:5], v[80:81], off nt
.LBB0_149:
	s_or_b64 exec, exec, s[16:17]
	v_mov_b32_e32 v7, 0
	v_mov_b32_e32 v8, 0
	v_mov_b32_e32 v9, 0
	s_and_saveexec_b64 s[16:17], s[12:13]
	s_cbranch_execz .LBB0_151
	v_add_co_u32_e32 v6, vcc, 0x5000, v80
	s_nop 1
	v_addc_co_u32_e32 v7, vcc, 0, v81, vcc
	global_load_dwordx4 v[6:9], v[6:7], off offset:3328 nt
.LBB0_151:
	s_or_b64 exec, exec, s[16:17]
	v_mov_b32_e32 v10, 0
	v_mov_b32_e32 v14, 0
	v_mov_b32_e32 v15, 0
	v_mov_b32_e32 v16, 0
	v_mov_b32_e32 v17, 0
	s_and_saveexec_b64 s[16:17], s[12:13]
	s_cbranch_execz .LBB0_153
	v_add_co_u32_e32 v12, vcc, 0xb000, v80
	s_nop 1
	v_addc_co_u32_e32 v13, vcc, 0, v81, vcc
	global_load_dwordx4 v[14:17], v[12:13], off offset:2560 nt
.LBB0_153:
	s_or_b64 exec, exec, s[16:17]
	v_mov_b32_e32 v11, 0
	v_mov_b32_e32 v12, 0
	v_mov_b32_e32 v13, 0
	s_and_saveexec_b64 s[16:17], s[12:13]
	s_cbranch_execz .LBB0_155
	v_add_co_u32_e32 v10, vcc, 0x11000, v80
	s_nop 1
	v_addc_co_u32_e32 v11, vcc, 0, v81, vcc
	global_load_dwordx4 v[10:13], v[10:11], off offset:1792 nt
.LBB0_155:
	s_or_b64 exec, exec, s[16:17]
	v_mov_b32_e32 v18, 0
	v_mov_b32_e32 v22, 0
	v_mov_b32_e32 v23, 0
	v_mov_b32_e32 v24, 0
	v_mov_b32_e32 v25, 0
	s_and_saveexec_b64 s[16:17], s[12:13]
	s_cbranch_execz .LBB0_157
	v_add_co_u32_e32 v20, vcc, 0x17000, v80
	s_nop 1
	v_addc_co_u32_e32 v21, vcc, 0, v81, vcc
	global_load_dwordx4 v[22:25], v[20:21], off offset:1024 nt
.LBB0_157:
	s_or_b64 exec, exec, s[16:17]
	v_mov_b32_e32 v19, 0
	v_mov_b32_e32 v20, 0
	v_mov_b32_e32 v21, 0
	s_and_saveexec_b64 s[16:17], s[12:13]
	s_cbranch_execz .LBB0_159
	v_add_co_u32_e32 v18, vcc, 0x1d000, v80
	s_nop 1
	v_addc_co_u32_e32 v19, vcc, 0, v81, vcc
	global_load_dwordx4 v[18:21], v[18:19], off offset:256 nt
.LBB0_159:
	s_or_b64 exec, exec, s[16:17]
	v_mov_b32_e32 v26, 0
	v_mov_b32_e32 v30, 0
	v_mov_b32_e32 v31, 0
	v_mov_b32_e32 v32, 0
	v_mov_b32_e32 v33, 0
	s_and_saveexec_b64 s[16:17], s[12:13]
	s_cbranch_execz .LBB0_161
	v_add_co_u32_e32 v28, vcc, 0x22000, v80
	s_nop 1
	v_addc_co_u32_e32 v29, vcc, 0, v81, vcc
	global_load_dwordx4 v[30:33], v[28:29], off offset:3584 nt
.LBB0_161:
	s_or_b64 exec, exec, s[16:17]
	v_mov_b32_e32 v27, 0
	v_mov_b32_e32 v28, 0
	v_mov_b32_e32 v29, 0
	s_and_saveexec_b64 s[16:17], s[12:13]
	s_cbranch_execz .LBB0_163
	v_add_co_u32_e32 v26, vcc, 0x28000, v80
	s_nop 1
	v_addc_co_u32_e32 v27, vcc, 0, v81, vcc
	global_load_dwordx4 v[26:29], v[26:27], off offset:2816 nt
.LBB0_163:
	s_or_b64 exec, exec, s[16:17]
	v_mov_b32_e32 v34, 0
	v_mov_b32_e32 v38, 0
	v_mov_b32_e32 v39, 0
	v_mov_b32_e32 v40, 0
	v_mov_b32_e32 v41, 0
	s_and_saveexec_b64 s[16:17], s[12:13]
	s_cbranch_execz .LBB0_165
	v_add_co_u32_e32 v36, vcc, 0x2e000, v80
	s_nop 1
	v_addc_co_u32_e32 v37, vcc, 0, v81, vcc
	global_load_dwordx4 v[38:41], v[36:37], off offset:2048 nt
.LBB0_165:
	s_or_b64 exec, exec, s[16:17]
	v_mov_b32_e32 v35, 0
	v_mov_b32_e32 v36, 0
	v_mov_b32_e32 v37, 0
	s_and_saveexec_b64 s[16:17], s[12:13]
	s_cbranch_execz .LBB0_167
	v_add_co_u32_e32 v34, vcc, 0x34000, v80
	s_nop 1
	v_addc_co_u32_e32 v35, vcc, 0, v81, vcc
	global_load_dwordx4 v[34:37], v[34:35], off offset:1280 nt
.LBB0_167:
	s_or_b64 exec, exec, s[16:17]
	v_mov_b32_e32 v42, 0
	v_mov_b32_e32 v46, 0
	v_mov_b32_e32 v47, 0
	v_mov_b32_e32 v48, 0
	v_mov_b32_e32 v49, 0
	s_and_saveexec_b64 s[16:17], s[12:13]
	s_cbranch_execz .LBB0_169
	v_add_co_u32_e32 v44, vcc, 0x3a000, v80
	s_nop 1
	v_addc_co_u32_e32 v45, vcc, 0, v81, vcc
	global_load_dwordx4 v[46:49], v[44:45], off offset:512 nt
.LBB0_169:
	s_or_b64 exec, exec, s[16:17]
	v_mov_b32_e32 v43, 0
	v_mov_b32_e32 v44, 0
	v_mov_b32_e32 v45, 0
	s_and_saveexec_b64 s[16:17], s[12:13]
	s_cbranch_execz .LBB0_171
	v_add_co_u32_e32 v42, vcc, 0x3f000, v80
	s_nop 1
	v_addc_co_u32_e32 v43, vcc, 0, v81, vcc
	global_load_dwordx4 v[42:45], v[42:43], off offset:3840 nt
.LBB0_171:
	s_or_b64 exec, exec, s[16:17]
	v_mov_b32_e32 v50, 0
	v_mov_b32_e32 v54, 0
	v_mov_b32_e32 v55, 0
	v_mov_b32_e32 v56, 0
	v_mov_b32_e32 v57, 0
	s_and_saveexec_b64 s[16:17], s[12:13]
	s_cbranch_execz .LBB0_173
	v_add_co_u32_e32 v52, vcc, 0x45000, v80
	s_nop 1
	v_addc_co_u32_e32 v53, vcc, 0, v81, vcc
	global_load_dwordx4 v[54:57], v[52:53], off offset:3072 nt
.LBB0_173:
	s_or_b64 exec, exec, s[16:17]
	v_mov_b32_e32 v51, 0
	v_mov_b32_e32 v52, 0
	v_mov_b32_e32 v53, 0
	s_and_saveexec_b64 s[16:17], s[12:13]
	s_cbranch_execz .LBB0_175
	v_add_co_u32_e32 v50, vcc, 0x4b000, v80
	s_nop 1
	v_addc_co_u32_e32 v51, vcc, 0, v81, vcc
	global_load_dwordx4 v[50:53], v[50:51], off offset:2304 nt
.LBB0_175:
	s_or_b64 exec, exec, s[16:17]
	v_mov_b32_e32 v58, 0
	v_mov_b32_e32 v62, 0
	v_mov_b32_e32 v63, 0
	v_mov_b32_e32 v64, 0
	v_mov_b32_e32 v65, 0
	s_and_saveexec_b64 s[16:17], s[12:13]
	s_cbranch_execz .LBB0_177
	v_add_co_u32_e32 v60, vcc, 0x51000, v80
	s_nop 1
	v_addc_co_u32_e32 v61, vcc, 0, v81, vcc
	global_load_dwordx4 v[62:65], v[60:61], off offset:1536 nt
.LBB0_177:
	s_or_b64 exec, exec, s[16:17]
	v_mov_b32_e32 v59, 0
	v_mov_b32_e32 v60, 0
	v_mov_b32_e32 v61, 0
	s_and_saveexec_b64 s[16:17], s[12:13]
	s_cbranch_execz .LBB0_179
	v_add_co_u32_e32 v58, vcc, 0x57000, v80
	s_nop 1
	v_addc_co_u32_e32 v59, vcc, 0, v81, vcc
	global_load_dwordx4 v[58:61], v[58:59], off offset:768 nt

; #define LAS __attribute__((address_space(3)))
; DI void prep_items(const Params& p, LAS unsigned char* lds, int l, unsigned* ctr, int max_items) {
;     ...
;             const int n0 = it * 256;
;             const float* W = p.in[4] + (size_t)l * 2048 * 12288 + n0 + lane * 4;
;             f32x4 a0 = (f32x4){0.f, 0.f, 0.f, 0.f}, a1 = a0, a2 = a0, a3 = a0, a4 = a0;
; #pragma unroll 8
;             for (int k = wid; k < 2048; k += 8) { const f32x4 w = *(const f32x4*)(W + (size_t)k * 12288); a0 += w * s_c[k]; a1 += w * s_c[2048 + k]; a2 += w * s_c[4096 + k]; a3 += w * s_c[6144 + k]; a4 += w * s_c[8192 + k]; }
;             *(LAS f32x4*)(s_red + (wid * 5 + 0) * 256 + lane * 4) = a0; *(LAS f32x4*)(s_red + (wid * 5 + 1) * 256 + lane * 4) = a1; *(LAS f32x4*)(s_red + (wid * 5 + 2) * 256 + lane * 4) = a2;
;             *(LAS f32x4*)(s_red + (wid * 5 + 3) * 256 + lane * 4) = a3; *(LAS f32x4*)(s_red + (wid * 5 + 4) * 256 + lane * 4) = a4;
.LBB0_225:
	global_load_dwordx4 v[26:29], v[22:23], off nt
	ds_read2st64_b32 v[30:31], v24 offset1:32
	ds_read2st64_b32 v[32:33], v24 offset0:64 offset1:96
	ds_read_b32 v34, v24 offset:32768
	s_mov_b64 s[2:3], 0x60000
	v_add_co_u32_e32 v0, vcc, 1, v0
	s_waitcnt lgkmcnt(2)
	v_mov_b32_e32 v38, v31
	s_waitcnt lgkmcnt(1)
	v_mov_b32_e32 v40, v33
	v_add_u32_e32 v36, 8, v36
	v_add_u32_e32 v24, 32, v24
	v_lshl_add_u64 v[22:23], v[22:23], 0, s[2:3]
	s_or_b64 s[18:19], vcc, s[18:19]
	s_waitcnt vmcnt(0)
	v_pk_fma_f32 v[4:5], v[28:29], v[30:31], v[4:5] op_sel_hi:[1,0,1]
	v_pk_fma_f32 v[2:3], v[26:27], v[30:31], v[2:3] op_sel_hi:[1,0,1]
	v_pk_fma_f32 v[8:9], v[28:29], v[38:39], v[8:9] op_sel_hi:[1,0,1]
	v_pk_fma_f32 v[6:7], v[26:27], v[38:39], v[6:7] op_sel_hi:[1,0,1]
	v_pk_fma_f32 v[12:13], v[28:29], v[32:33], v[12:13] op_sel_hi:[1,0,1]
	v_pk_fma_f32 v[10:11], v[26:27], v[32:33], v[10:11] op_sel_hi:[1,0,1]
	v_pk_fma_f32 v[16:17], v[28:29], v[40:41], v[16:17] op_sel_hi:[1,0,1]
	v_pk_fma_f32 v[14:15], v[26:27], v[40:41], v[14:15] op_sel_hi:[1,0,1]
	s_waitcnt lgkmcnt(0)
	v_pk_fma_f32 v[20:21], v[28:29], v[34:35], v[20:21] op_sel_hi:[1,0,1]
	v_pk_fma_f32 v[18:19], v[26:27], v[34:35], v[18:19] op_sel_hi:[1,0,1]
	s_andn2_b64 exec, exec, s[18:19]
	s_cbranch_execnz .LBB0_225
	s_or_b64 exec, exec, s[18:19]

; #define LAS __attribute__((address_space(3)))
; DI void prep_items(const Params& p, LAS unsigned char* lds, int l, unsigned* ctr, int max_items) {
;     ...
;             const int n0 = it * 256;
;             const float* W = p.in[4] + (size_t)l * 2048 * 12288 + n0 + lane * 4;
;             f32x4 a0 = (f32x4){0.f, 0.f, 0.f, 0.f}, a1 = a0, a2 = a0, a3 = a0, a4 = a0;
; #pragma unroll 8
;             for (int k = wid; k < 2048; k += 8) { const f32x4 w = *(const f32x4*)(W + (size_t)k * 12288); a0 += w * s_c[k]; a1 += w * s_c[2048 + k]; a2 += w * s_c[4096 + k]; a3 += w * s_c[6144 + k]; a4 += w * s_c[8192 + k]; }
;             *(LAS f32x4*)(s_red + (wid * 5 + 0) * 256 + lane * 4) = a0; *(LAS f32x4*)(s_red + (wid * 5 + 1) * 256 + lane * 4) = a1; *(LAS f32x4*)(s_red + (wid * 5 + 2) * 256 + lane * 4) = a2;
;             *(LAS f32x4*)(s_red + (wid * 5 + 3) * 256 + lane * 4) = a3; *(LAS f32x4*)(s_red + (wid * 5 + 4) * 256 + lane * 4) = a4;
.LBB0_229:
	v_lshl_add_u64 v[42:43], v[36:37], 0, s[18:19]
	v_lshl_add_u64 v[44:45], v[34:35], 0, s[18:19]
	v_lshl_add_u64 v[58:59], v[30:31], 0, s[18:19]
	ds_read2_b32 v[38:39], v48 offset1:8
	v_add_u32_e32 v49, 0x2000, v48
	v_lshl_add_u64 v[46:47], v[32:33], 0, s[18:19]
	ds_read2_b32 v[40:41], v48 offset0:16 offset1:24
	v_lshl_add_u64 v[62:63], v[28:29], 0, s[18:19]
	ds_read2_b32 v[110:111], v48 offset0:32 offset1:40
	ds_read2_b32 v[112:113], v48 offset0:48 offset1:56
	global_load_dwordx4 v[50:53], v[42:43], off nt
	s_nop 0
	global_load_dwordx4 v[42:45], v[44:45], off nt
	s_nop 0
	global_load_dwordx4 v[54:57], v[46:47], off nt
	s_nop 0
	global_load_dwordx4 v[58:61], v[58:59], off nt
	v_add_u32_e32 v101, 0x4000, v48
	ds_read2_b32 v[46:47], v49 offset1:8
	ds_read2_b32 v[114:115], v101 offset1:8
	global_load_dwordx4 v[62:65], v[62:63], off nt
	v_add_u32_e32 v138, 0x6000, v48
	v_lshl_add_u64 v[66:67], v[26:27], 0, s[18:19]
	v_lshl_add_u64 v[102:103], v[24:25], 0, s[18:19]
	v_lshl_add_u64 v[106:107], v[22:23], 0, s[18:19]
	v_add_u32_e32 v140, 0x8000, v48
	ds_read2_b32 v[116:117], v138 offset1:8
	ds_read2_b32 v[118:119], v140 offset1:8
	ds_read2_b32 v[120:121], v49 offset0:16 offset1:24
	ds_read2_b32 v[122:123], v101 offset0:16 offset1:24
	ds_read2_b32 v[124:125], v138 offset0:16 offset1:24
	ds_read2_b32 v[126:127], v140 offset0:16 offset1:24
	global_load_dwordx4 v[78:81], v[66:67], off nt
	s_nop 0
	global_load_dwordx4 v[102:105], v[102:103], off nt
	s_nop 0
	global_load_dwordx4 v[106:109], v[106:107], off nt
	s_waitcnt lgkmcnt(11)
	v_mov_b32_e32 v142, v39
	s_waitcnt lgkmcnt(7)
	v_mov_b32_e32 v150, v47
	s_waitcnt lgkmcnt(6)
	v_mov_b32_e32 v152, v115
	s_waitcnt lgkmcnt(5)
	v_mov_b32_e32 v154, v117
	s_waitcnt lgkmcnt(4)
	v_mov_b32_e32 v156, v119
	ds_read2_b32 v[66:67], v49 offset0:32 offset1:40
	ds_read2_b32 v[128:129], v101 offset0:32 offset1:40
	ds_read2_b32 v[130:131], v138 offset0:32 offset1:40
	ds_read2_b32 v[132:133], v140 offset0:32 offset1:40
	ds_read2_b32 v[134:135], v49 offset0:48 offset1:56
	ds_read2_b32 v[136:137], v101 offset0:48 offset1:56
	ds_read2_b32 v[138:139], v138 offset0:48 offset1:56
	ds_read2_b32 v[140:141], v140 offset0:48 offset1:56
	v_mov_b32_e32 v144, v41
	s_waitcnt lgkmcnt(11)
	v_mov_b32_e32 v158, v121
	s_waitcnt lgkmcnt(10)
	v_mov_b32_e32 v160, v123
	s_waitcnt lgkmcnt(9)
	v_mov_b32_e32 v162, v125
	s_waitcnt lgkmcnt(8)
	v_mov_b32_e32 v164, v127
	v_mov_b32_e32 v146, v111
	s_waitcnt lgkmcnt(7)
	v_mov_b32_e32 v166, v67
	s_waitcnt lgkmcnt(6)
	v_mov_b32_e32 v168, v129
	s_waitcnt lgkmcnt(5)
	v_mov_b32_e32 v170, v131
	s_waitcnt lgkmcnt(4)
	v_mov_b32_e32 v172, v133
	v_add_u32_e32 v0, 64, v0
	s_movk_i32 s2, 0x7bf
	v_cmp_lt_i32_e32 vcc, s2, v0
	v_mov_b32_e32 v148, v113
	s_waitcnt lgkmcnt(3)
	v_mov_b32_e32 v174, v135
	s_waitcnt lgkmcnt(2)
	v_mov_b32_e32 v176, v137
	s_waitcnt lgkmcnt(1)
	v_mov_b32_e32 v178, v139
	s_waitcnt lgkmcnt(0)
	v_mov_b32_e32 v180, v141
	v_lshl_add_u64 v[22:23], v[22:23], 0, s[92:93]
	v_lshl_add_u64 v[24:25], v[24:25], 0, s[92:93]
	v_lshl_add_u64 v[26:27], v[26:27], 0, s[92:93]
	v_lshl_add_u64 v[28:29], v[28:29], 0, s[92:93]
	v_lshl_add_u64 v[30:31], v[30:31], 0, s[92:93]
	v_lshl_add_u64 v[32:33], v[32:33], 0, s[92:93]
	v_lshl_add_u64 v[34:35], v[34:35], 0, s[92:93]
	v_add_u32_e32 v48, 0x100, v48
	v_lshl_add_u64 v[36:37], v[36:37], 0, s[92:93]
	s_or_b64 s[22:23], vcc, s[22:23]
	s_waitcnt vmcnt(7)
	v_pk_fma_f32 v[2:3], v[50:51], v[38:39], v[2:3] op_sel_hi:[1,0,1]
	v_pk_fma_f32 v[4:5], v[52:53], v[38:39], v[4:5] op_sel_hi:[1,0,1]
	v_pk_fma_f32 v[6:7], v[50:51], v[46:47], v[6:7] op_sel_hi:[1,0,1]
	v_pk_fma_f32 v[8:9], v[52:53], v[46:47], v[8:9] op_sel_hi:[1,0,1]
	v_pk_fma_f32 v[10:11], v[50:51], v[114:115], v[10:11] op_sel_hi:[1,0,1]
	v_pk_fma_f32 v[12:13], v[52:53], v[114:115], v[12:13] op_sel_hi:[1,0,1]
	v_pk_fma_f32 v[14:15], v[50:51], v[116:117], v[14:15] op_sel_hi:[1,0,1]
	v_pk_fma_f32 v[16:17], v[52:53], v[116:117], v[16:17] op_sel_hi:[1,0,1]
	v_pk_fma_f32 v[18:19], v[50:51], v[118:119], v[18:19] op_sel_hi:[1,0,1]
	v_pk_fma_f32 v[20:21], v[52:53], v[118:119], v[20:21] op_sel_hi:[1,0,1]
	s_waitcnt vmcnt(6)
	v_pk_fma_f32 v[4:5], v[44:45], v[142:143], v[4:5] op_sel_hi:[1,0,1]
	v_pk_fma_f32 v[2:3], v[42:43], v[142:143], v[2:3] op_sel_hi:[1,0,1]
	v_pk_fma_f32 v[8:9], v[44:45], v[150:151], v[8:9] op_sel_hi:[1,0,1]
	v_pk_fma_f32 v[6:7], v[42:43], v[150:151], v[6:7] op_sel_hi:[1,0,1]
	v_pk_fma_f32 v[12:13], v[44:45], v[152:153], v[12:13] op_sel_hi:[1,0,1]
	v_pk_fma_f32 v[10:11], v[42:43], v[152:153], v[10:11] op_sel_hi:[1,0,1]
	v_pk_fma_f32 v[16:17], v[44:45], v[154:155], v[16:17] op_sel_hi:[1,0,1]
	v_pk_fma_f32 v[14:15], v[42:43], v[154:155], v[14:15] op_sel_hi:[1,0,1]
	v_pk_fma_f32 v[20:21], v[44:45], v[156:157], v[20:21] op_sel_hi:[1,0,1]
	v_pk_fma_f32 v[18:19], v[42:43], v[156:157], v[18:19] op_sel_hi:[1,0,1]
	s_waitcnt vmcnt(5)
; #define LAS __attribute__((address_space(3)))
; DI void prep_items(const Params& p, LAS unsigned char* lds, int l, unsigned* ctr, int max_items) {
;     ...
;             const int n0 = it * 256;
;             const float* W = p.in[4] + (size_t)l * 2048 * 12288 + n0 + lane * 4;
;             f32x4 a0 = (f32x4){0.f, 0.f, 0.f, 0.f}, a1 = a0, a2 = a0, a3 = a0, a4 = a0;
; #pragma unroll 8
;             for (int k = wid; k < 2048; k += 8) { const f32x4 w = *(const f32x4*)(W + (size_t)k * 12288); a0 += w * s_c[k]; a1 += w * s_c[2048 + k]; a2 += w * s_c[4096 + k]; a3 += w * s_c[6144 + k]; a4 += w * s_c[8192 + k]; }
;             *(LAS f32x4*)(s_red + (wid * 5 + 0) * 256 + lane * 4) = a0; *(LAS f32x4*)(s_red + (wid * 5 + 1) * 256 + lane * 4) = a1; *(LAS f32x4*)(s_red + (wid * 5 + 2) * 256 + lane * 4) = a2;
;             *(LAS f32x4*)(s_red + (wid * 5 + 3) * 256 + lane * 4) = a3; *(LAS f32x4*)(s_red + (wid * 5 + 4) * 256 + lane * 4) = a4;
	v_pk_fma_f32 v[4:5], v[56:57], v[40:41], v[4:5] op_sel_hi:[1,0,1]
	v_pk_fma_f32 v[2:3], v[54:55], v[40:41], v[2:3] op_sel_hi:[1,0,1]
	v_pk_fma_f32 v[8:9], v[56:57], v[120:121], v[8:9] op_sel_hi:[1,0,1]
	v_pk_fma_f32 v[6:7], v[54:55], v[120:121], v[6:7] op_sel_hi:[1,0,1]
	v_pk_fma_f32 v[12:13], v[56:57], v[122:123], v[12:13] op_sel_hi:[1,0,1]
	v_pk_fma_f32 v[10:11], v[54:55], v[122:123], v[10:11] op_sel_hi:[1,0,1]
	v_pk_fma_f32 v[16:17], v[56:57], v[124:125], v[16:17] op_sel_hi:[1,0,1]
	v_pk_fma_f32 v[14:15], v[54:55], v[124:125], v[14:15] op_sel_hi:[1,0,1]
	v_pk_fma_f32 v[20:21], v[56:57], v[126:127], v[20:21] op_sel_hi:[1,0,1]
	v_pk_fma_f32 v[18:19], v[54:55], v[126:127], v[18:19] op_sel_hi:[1,0,1]
	s_waitcnt vmcnt(4)
	v_pk_fma_f32 v[4:5], v[60:61], v[144:145], v[4:5] op_sel_hi:[1,0,1]
	v_pk_fma_f32 v[2:3], v[58:59], v[144:145], v[2:3] op_sel_hi:[1,0,1]
	v_pk_fma_f32 v[8:9], v[60:61], v[158:159], v[8:9] op_sel_hi:[1,0,1]
	v_pk_fma_f32 v[6:7], v[58:59], v[158:159], v[6:7] op_sel_hi:[1,0,1]
	v_pk_fma_f32 v[12:13], v[60:61], v[160:161], v[12:13] op_sel_hi:[1,0,1]
	v_pk_fma_f32 v[10:11], v[58:59], v[160:161], v[10:11] op_sel_hi:[1,0,1]
	v_pk_fma_f32 v[16:17], v[60:61], v[162:163], v[16:17] op_sel_hi:[1,0,1]
	v_pk_fma_f32 v[14:15], v[58:59], v[162:163], v[14:15] op_sel_hi:[1,0,1]
	v_pk_fma_f32 v[20:21], v[60:61], v[164:165], v[20:21] op_sel_hi:[1,0,1]
	v_pk_fma_f32 v[18:19], v[58:59], v[164:165], v[18:19] op_sel_hi:[1,0,1]
	s_waitcnt vmcnt(3)
	v_pk_fma_f32 v[4:5], v[64:65], v[110:111], v[4:5] op_sel_hi:[1,0,1]
	v_pk_fma_f32 v[2:3], v[62:63], v[110:111], v[2:3] op_sel_hi:[1,0,1]
	v_pk_fma_f32 v[8:9], v[64:65], v[66:67], v[8:9] op_sel_hi:[1,0,1]
	v_pk_fma_f32 v[6:7], v[62:63], v[66:67], v[6:7] op_sel_hi:[1,0,1]
	v_pk_fma_f32 v[12:13], v[64:65], v[128:129], v[12:13] op_sel_hi:[1,0,1]
	v_pk_fma_f32 v[10:11], v[62:63], v[128:129], v[10:11] op_sel_hi:[1,0,1]
	v_pk_fma_f32 v[16:17], v[64:65], v[130:131], v[16:17] op_sel_hi:[1,0,1]
	v_pk_fma_f32 v[14:15], v[62:63], v[130:131], v[14:15] op_sel_hi:[1,0,1]
	v_pk_fma_f32 v[20:21], v[64:65], v[132:133], v[20:21] op_sel_hi:[1,0,1]
	v_pk_fma_f32 v[18:19], v[62:63], v[132:133], v[18:19] op_sel_hi:[1,0,1]
	s_waitcnt vmcnt(2)
	v_pk_fma_f32 v[4:5], v[80:81], v[146:147], v[4:5] op_sel_hi:[1,0,1]
	v_pk_fma_f32 v[2:3], v[78:79], v[146:147], v[2:3] op_sel_hi:[1,0,1]
	v_pk_fma_f32 v[8:9], v[80:81], v[166:167], v[8:9] op_sel_hi:[1,0,1]
	v_pk_fma_f32 v[6:7], v[78:79], v[166:167], v[6:7] op_sel_hi:[1,0,1]
	v_pk_fma_f32 v[12:13], v[80:81], v[168:169], v[12:13] op_sel_hi:[1,0,1]
	v_pk_fma_f32 v[10:11], v[78:79], v[168:169], v[10:11] op_sel_hi:[1,0,1]
	v_pk_fma_f32 v[16:17], v[80:81], v[170:171], v[16:17] op_sel_hi:[1,0,1]
	v_pk_fma_f32 v[14:15], v[78:79], v[170:171], v[14:15] op_sel_hi:[1,0,1]
	v_pk_fma_f32 v[20:21], v[80:81], v[172:173], v[20:21] op_sel_hi:[1,0,1]
	v_pk_fma_f32 v[18:19], v[78:79], v[172:173], v[18:19] op_sel_hi:[1,0,1]
	s_waitcnt vmcnt(1)
	v_pk_fma_f32 v[4:5], v[104:105], v[112:113], v[4:5] op_sel_hi:[1,0,1]
	v_pk_fma_f32 v[2:3], v[102:103], v[112:113], v[2:3] op_sel_hi:[1,0,1]
	v_pk_fma_f32 v[8:9], v[104:105], v[134:135], v[8:9] op_sel_hi:[1,0,1]
	v_pk_fma_f32 v[6:7], v[102:103], v[134:135], v[6:7] op_sel_hi:[1,0,1]
	v_pk_fma_f32 v[12:13], v[104:105], v[136:137], v[12:13] op_sel_hi:[1,0,1]
	v_pk_fma_f32 v[10:11], v[102:103], v[136:137], v[10:11] op_sel_hi:[1,0,1]
	v_pk_fma_f32 v[16:17], v[104:105], v[138:139], v[16:17] op_sel_hi:[1,0,1]
	v_pk_fma_f32 v[14:15], v[102:103], v[138:139], v[14:15] op_sel_hi:[1,0,1]
	v_pk_fma_f32 v[20:21], v[104:105], v[140:141], v[20:21] op_sel_hi:[1,0,1]
	v_pk_fma_f32 v[18:19], v[102:103], v[140:141], v[18:19] op_sel_hi:[1,0,1]
	s_waitcnt vmcnt(0)
	v_pk_fma_f32 v[4:5], v[108:109], v[148:149], v[4:5] op_sel_hi:[1,0,1]
	v_pk_fma_f32 v[2:3], v[106:107], v[148:149], v[2:3] op_sel_hi:[1,0,1]
	v_pk_fma_f32 v[8:9], v[108:109], v[174:175], v[8:9] op_sel_hi:[1,0,1]
	v_pk_fma_f32 v[6:7], v[106:107], v[174:175], v[6:7] op_sel_hi:[1,0,1]
	v_pk_fma_f32 v[12:13], v[108:109], v[176:177], v[12:13] op_sel_hi:[1,0,1]
	v_pk_fma_f32 v[10:11], v[106:107], v[176:177], v[10:11] op_sel_hi:[1,0,1]
	v_pk_fma_f32 v[16:17], v[108:109], v[178:179], v[16:17] op_sel_hi:[1,0,1]
	v_pk_fma_f32 v[14:15], v[106:107], v[178:179], v[14:15] op_sel_hi:[1,0,1]
	v_pk_fma_f32 v[20:21], v[108:109], v[180:181], v[20:21] op_sel_hi:[1,0,1]
	v_pk_fma_f32 v[18:19], v[106:107], v[180:181], v[18:19] op_sel_hi:[1,0,1]
	s_andn2_b64 exec, exec, s[22:23]
	s_cbranch_execnz .LBB0_229
	s_or_b64 exec, exec, s[22:23]

; DI void conv_witem(const float* W, int K, int Nsrc, bf16_t* dst, const float* rowscale, bool perm_in, int kt, int ntile, int lane, bool glu_rows = false) {
;     ...
;     const float* src = W + (size_t)k0 * Nsrc + csrc;
;     f32x4 v[16];
; #pragma unroll
;     for (int i = 0; i < 16; ++i) v[i] = valid ? *(const f32x4*)(src + (size_t)i * Nsrc) : (f32x4){0.f, 0.f, 0.f, 0.f};
; DI void prep_items(const Params& p, LAS unsigned char* lds, int l, unsigned* ctr, int max_items) {
;     ...
;             int id = (it - N_ADA - n_tab) * 8 + wid;
;             if (id < 3072) conv_witem(p.in[6] + (size_t)l * 2048 * INW, 2048, INW, (bf16_t*)(p.ws + WS_WIN) + (size_t)l * 6144 * 2048, nullptr, true, id % 128, id / 128, lane);
;             else if ((id -= 3072) < 128) conv_witem(p.in[9] + (size_t)l * 512 * 960, 512, 960, (bf16_t*)(p.ws + WS_WUQ) + (size_t)l * 1024 * 512, p.in[7] + l * 512, false, id % 32, id / 32, lane);
;             else if ((id -= 128) < 160) conv_witem(p.in[10] + (size_t)l * 512 * 1280, 512, 1280, (bf16_t*)(p.ws + WS_WUKV) + (size_t)l * 1280 * 512, p.in[8] + l * 512, false, id % 32, id / 32, lane);
;             else if ((id -= 160) < 1024) conv_witem(p.in[13] + (size_t)l * 2048 * 2048, 2048, 2048, (bf16_t*)(p.ws + WS_WO) + (size_t)l * 2048 * 2048, nullptr, false, id % 128, id / 128, lane);
;             else if ((id -= 1024) < 5632) conv_witem(p.in[16] + (size_t)l * 2048 * 11264, 2048, 11264, (bf16_t*)(p.ws + WS_WUP) + (size_t)l * 11264 * 2048, nullptr, false, id % 128, id / 128, lane, true);
;             else { id -= 5632; conv_witem(p.in[19] + (size_t)l * 5632 * 2048, 5632, 2048, (bf16_t*)(p.ws + WS_WDN) + (size_t)l * 2048 * 5632, nullptr, false, id % 352, id / 352, lane); }
.LBB0_243:
	s_or_b64 exec, exec, s[12:13]
	s_waitcnt lgkmcnt(0)
	s_barrier
	ds_read_b32 v0, v94
	s_movk_i32 s12, 47
	s_xor_b64 s[86:87], s[76:77], -1
	s_waitcnt lgkmcnt(0)
	v_cmp_lt_i32_e32 vcc, s12, v0
	v_readfirstlane_b32 s30, v0
	s_mov_b64 s[12:13], -1
	s_cbranch_vccnz .LBB0_238
	s_cmp_gt_i32 s30, 47
	s_cbranch_scc0 .LBB0_398
	v_lshl_add_u32 v0, s30, 3, v91
	s_movk_i32 s12, 0xbff
	v_cmp_lt_i32_e32 vcc, s12, v0
	s_and_saveexec_b64 s[12:13], vcc
	s_xor_b64 s[88:89], exec, s[12:13]
	s_cbranch_execz .LBB0_363
	s_movk_i32 s12, 0xc7f
	v_cmp_lt_u32_e32 vcc, s12, v0
	s_and_saveexec_b64 s[12:13], vcc
	s_xor_b64 s[16:17], exec, s[12:13]
	s_cbranch_execz .LBB0_326
	s_movk_i32 s12, 0xd1f
	v_cmp_lt_u32_e32 vcc, s12, v0
	s_and_saveexec_b64 s[12:13], vcc
	s_xor_b64 s[18:19], exec, s[12:13]
	s_cbranch_execz .LBB0_289
	s_movk_i32 s12, 0x111f
	v_cmp_lt_u32_e32 vcc, s12, v0
	s_and_saveexec_b64 s[12:13], vcc
	s_xor_b64 s[90:91], exec, s[12:13]
	s_cbranch_execz .LBB0_286
	s_movk_i32 s12, 0x271f
	v_cmp_lt_u32_e32 vcc, s12, v0
	s_and_saveexec_b64 s[12:13], vcc
	s_xor_b64 s[92:93], exec, s[12:13]
	s_cbranch_execz .LBB0_283
	v_add_u32_e32 v2, 0xffffd8e0, v0
	s_mov_b32 s12, 0xba2e8ba3
	v_mul_hi_u32 v3, v2, s12
	v_lshrrev_b32_e32 v0, 8, v3
	v_mul_u32_u24_e32 v0, 0x160, v0
	v_sub_u32_e32 v0, v2, v0
	s_movk_i32 s12, 0xff00
	v_lshlrev_b32_e32 v0, 4, v0
	v_and_or_b32 v66, v3, s12, v83
	s_movk_i32 s12, 0xb00
	v_readlane_b32 s94, v253, 17
	v_cmp_gt_u32_e64 s[12:13], s12, v2
	v_lshlrev_b64 v[2:3], 13, v[0:1]
	v_readlane_b32 s95, v253, 18
	v_mov_b32_e32 v67, v1
	v_mov_b32_e32 v6, 0
	v_lshl_add_u64 v[2:3], s[94:95], 0, v[2:3]
	v_lshl_add_u64 v[78:79], v[66:67], 2, v[2:3]
	v_mov_b32_e32 v2, 0
	v_mov_b32_e32 v3, 0
	v_mov_b32_e32 v4, 0
	v_mov_b32_e32 v5, 0
	s_and_saveexec_b64 s[94:95], s[12:13]
	s_cbranch_execz .LBB0_252
	global_load_dwordx4 v[2:5], v[78:79], off nt
.LBB0_252:
	s_or_b64 exec, exec, s[94:95]
	v_mov_b32_e32 v7, 0
	v_mov_b32_e32 v8, 0
	v_mov_b32_e32 v9, 0
	s_and_saveexec_b64 s[94:95], s[12:13]
	s_cbranch_execz .LBB0_254
	v_add_co_u32_e32 v6, vcc, 0x2000, v78
	s_nop 1
	v_addc_co_u32_e32 v7, vcc, 0, v79, vcc
	global_load_dwordx4 v[6:9], v[6:7], off nt
.LBB0_254:
	s_or_b64 exec, exec, s[94:95]
	v_mov_b32_e32 v10, 0
	v_mov_b32_e32 v14, 0
	v_mov_b32_e32 v15, 0
	v_mov_b32_e32 v16, 0
	v_mov_b32_e32 v17, 0
	s_and_saveexec_b64 s[94:95], s[12:13]
	s_cbranch_execz .LBB0_256
	v_add_co_u32_e32 v12, vcc, 0x4000, v78
	s_nop 1
	v_addc_co_u32_e32 v13, vcc, 0, v79, vcc
	global_load_dwordx4 v[14:17], v[12:13], off nt
.LBB0_256:
	s_or_b64 exec, exec, s[94:95]
	v_mov_b32_e32 v11, 0
	v_mov_b32_e32 v12, 0
	v_mov_b32_e32 v13, 0
	s_and_saveexec_b64 s[94:95], s[12:13]
	s_cbranch_execz .LBB0_258
	v_add_co_u32_e32 v10, vcc, 0x6000, v78
	s_nop 1
	v_addc_co_u32_e32 v11, vcc, 0, v79, vcc
	global_load_dwordx4 v[10:13], v[10:11], off nt
.LBB0_258:
	s_or_b64 exec, exec, s[94:95]
	v_mov_b32_e32 v18, 0
	v_mov_b32_e32 v22, 0
	v_mov_b32_e32 v23, 0
	v_mov_b32_e32 v24, 0
	v_mov_b32_e32 v25, 0
	s_and_saveexec_b64 s[94:95], s[12:13]
	s_cbranch_execz .LBB0_260
	v_add_co_u32_e32 v20, vcc, 0x8000, v78
	s_nop 1
	v_addc_co_u32_e32 v21, vcc, 0, v79, vcc
	global_load_dwordx4 v[22:25], v[20:21], off nt
.LBB0_260:
	s_or_b64 exec, exec, s[94:95]
	v_mov_b32_e32 v19, 0
	v_mov_b32_e32 v20, 0
	v_mov_b32_e32 v21, 0
	s_and_saveexec_b64 s[94:95], s[12:13]
	s_cbranch_execz .LBB0_262
	v_add_co_u32_e32 v18, vcc, 0xa000, v78
	s_nop 1
	v_addc_co_u32_e32 v19, vcc, 0, v79, vcc
	global_load_dwordx4 v[18:21], v[18:19], off nt
.LBB0_262:
	s_or_b64 exec, exec, s[94:95]
	v_mov_b32_e32 v26, 0
	v_mov_b32_e32 v30, 0
	v_mov_b32_e32 v31, 0
	v_mov_b32_e32 v32, 0
	v_mov_b32_e32 v33, 0
	s_and_saveexec_b64 s[94:95], s[12:13]
	s_cbranch_execz .LBB0_264
	v_add_co_u32_e32 v28, vcc, 0xc000, v78
	s_nop 1
	v_addc_co_u32_e32 v29, vcc, 0, v79, vcc
	global_load_dwordx4 v[30:33], v[28:29], off nt
.LBB0_264:
	s_or_b64 exec, exec, s[94:95]
	v_mov_b32_e32 v27, 0
	v_mov_b32_e32 v28, 0
	v_mov_b32_e32 v29, 0
	s_and_saveexec_b64 s[94:95], s[12:13]
	s_cbranch_execz .LBB0_266
	v_add_co_u32_e32 v26, vcc, 0xe000, v78
	s_nop 1
	v_addc_co_u32_e32 v27, vcc, 0, v79, vcc
	global_load_dwordx4 v[26:29], v[26:27], off nt
.LBB0_266:
	s_or_b64 exec, exec, s[94:95]
	v_mov_b32_e32 v34, 0
	v_mov_b32_e32 v38, 0
	v_mov_b32_e32 v39, 0
	v_mov_b32_e32 v40, 0
	v_mov_b32_e32 v41, 0
	s_and_saveexec_b64 s[94:95], s[12:13]
	s_cbranch_execz .LBB0_268
	v_add_co_u32_e32 v36, vcc, 0x10000, v78
	s_nop 1
	v_addc_co_u32_e32 v37, vcc, 0, v79, vcc
	global_load_dwordx4 v[38:41], v[36:37], off nt
.LBB0_268:
	s_or_b64 exec, exec, s[94:95]
	v_mov_b32_e32 v35, 0
	v_mov_b32_e32 v36, 0
	v_mov_b32_e32 v37, 0
	s_and_saveexec_b64 s[94:95], s[12:13]
	s_cbranch_execz .LBB0_270
	v_add_co_u32_e32 v34, vcc, 0x12000, v78
	s_nop 1
	v_addc_co_u32_e32 v35, vcc, 0, v79, vcc
	global_load_dwordx4 v[34:37], v[34:35], off nt
.LBB0_270:
	s_or_b64 exec, exec, s[94:95]
	v_mov_b32_e32 v42, 0
	v_mov_b32_e32 v46, 0
	v_mov_b32_e32 v47, 0
	v_mov_b32_e32 v48, 0
	v_mov_b32_e32 v49, 0
	s_and_saveexec_b64 s[94:95], s[12:13]
	s_cbranch_execz .LBB0_272
	v_add_co_u32_e32 v44, vcc, 0x14000, v78
	s_nop 1
	v_addc_co_u32_e32 v45, vcc, 0, v79, vcc
	global_load_dwordx4 v[46:49], v[44:45], off nt
.LBB0_272:
	s_or_b64 exec, exec, s[94:95]
	v_mov_b32_e32 v43, 0
	v_mov_b32_e32 v44, 0
	v_mov_b32_e32 v45, 0
	s_and_saveexec_b64 s[94:95], s[12:13]
	s_cbranch_execz .LBB0_274
	v_add_co_u32_e32 v42, vcc, 0x16000, v78
	s_nop 1
	v_addc_co_u32_e32 v43, vcc, 0, v79, vcc
	global_load_dwordx4 v[42:45], v[42:43], off nt
.LBB0_274:
	s_or_b64 exec, exec, s[94:95]
	v_mov_b32_e32 v50, 0
	v_mov_b32_e32 v54, 0
	v_mov_b32_e32 v55, 0
	v_mov_b32_e32 v56, 0
	v_mov_b32_e32 v57, 0
	s_and_saveexec_b64 s[94:95], s[12:13]
	s_cbranch_execz .LBB0_276
	v_add_co_u32_e32 v52, vcc, 0x18000, v78
	s_nop 1
	v_addc_co_u32_e32 v53, vcc, 0, v79, vcc
	global_load_dwordx4 v[54:57], v[52:53], off nt
.LBB0_276:
	s_or_b64 exec, exec, s[94:95]
	v_mov_b32_e32 v51, 0
	v_mov_b32_e32 v52, 0
	v_mov_b32_e32 v53, 0
	s_and_saveexec_b64 s[94:95], s[12:13]
	s_cbranch_execz .LBB0_278
	v_add_co_u32_e32 v50, vcc, 0x1a000, v78
	s_nop 1
	v_addc_co_u32_e32 v51, vcc, 0, v79, vcc
	global_load_dwordx4 v[50:53], v[50:51], off nt
.LBB0_278:
	s_or_b64 exec, exec, s[94:95]
	v_mov_b32_e32 v58, 0
	v_mov_b32_e32 v62, 0
	v_mov_b32_e32 v63, 0
	v_mov_b32_e32 v64, 0
	v_mov_b32_e32 v65, 0
	s_and_saveexec_b64 s[94:95], s[12:13]
	s_cbranch_execz .LBB0_280
	v_add_co_u32_e32 v60, vcc, 0x1c000, v78
	s_nop 1
	v_addc_co_u32_e32 v61, vcc, 0, v79, vcc
	global_load_dwordx4 v[62:65], v[60:61], off nt
.LBB0_280:
	s_or_b64 exec, exec, s[94:95]
	v_mov_b32_e32 v59, 0
	v_mov_b32_e32 v60, 0
	v_mov_b32_e32 v61, 0
	s_and_saveexec_b64 s[94:95], s[12:13]
	s_cbranch_execz .LBB0_282
	v_add_co_u32_e32 v58, vcc, 0x1e000, v78
	s_nop 1
	v_addc_co_u32_e32 v59, vcc, 0, v79, vcc
	global_load_dwordx4 v[58:61], v[58:59], off nt

; DI unsigned cvt_pk_bf16(float lo, float hi) { unsigned r; asm volatile("v_cvt_pk_bf16_f32 %0, %1, %2" : "=v"(r) : "v"(lo), "v"(hi)); return r; }
; DI void conv_witem(const float* W, int K, int Nsrc, bf16_t* dst, const float* rowscale, bool perm_in, int kt, int ntile, int lane, bool glu_rows = false) {
;     ...
;     if (perm_in && cdst >= C_RQ && cdst < C_RV) { const int pp = cdst & 63, g = pp >> 5, e = pp & 31; csrc = (cdst & ~63) + ((e < 16) ? g * 16 + e : 32 + g * 16 + (e - 16)); }
;     const bool valid = csrc < Nsrc;
;     const float* src = W + (size_t)k0 * Nsrc + csrc;
;     f32x4 v[16];
; #pragma unroll
;     for (int i = 0; i < 16; ++i) v[i] = valid ? *(const f32x4*)(src + (size_t)i * Nsrc) : (f32x4){0.f, 0.f, 0.f, 0.f};
;     if (rowscale) {
; #pragma unroll
;         for (int i = 0; i < 16; ++i) v[i] *= rowscale[k0 + i];
;     }
;     int drow = cdst;
;     if (glu_rows) { const int hf = cdst >= DFF ? 1 : 0, jj = cdst - hf * DFF; drow = (jj >> 7) * 256 + hf * 128 + (jj & 127); }
;     bf16_t* dp = dst + (size_t)drow * K + k0;
; #pragma unroll
;     for (int j = 0; j < 4; ++j) {
;         u32x4 w0, w1;
;         w0.x = cvt_pk_bf16(v[0][j], v[1][j]); w0.y = cvt_pk_bf16(v[2][j], v[3][j]); w0.z = cvt_pk_bf16(v[4][j], v[5][j]); w0.w = cvt_pk_bf16(v[6][j], v[7][j]);
;         w1.x = cvt_pk_bf16(v[8][j], v[9][j]); w1.y = cvt_pk_bf16(v[10][j], v[11][j]); w1.z = cvt_pk_bf16(v[12][j], v[13][j]); w1.w = cvt_pk_bf16(v[14][j], v[15][j]);
;         *(u32x4*)(dp + (size_t)j * K) = w0; *(u32x4*)(dp + (size_t)j * K + 8) = w1;
;     }
.LBB0_283:
	s_andn2_saveexec_b64 s[12:13], s[92:93]
	s_cbranch_execz .LBB0_285
	v_add_u32_e32 v66, 0xffffeee0, v0
	v_lshlrev_b32_e32 v0, 4, v66
	v_and_b32_e32 v78, 0x7f0, v0
	v_lshlrev_b32_e32 v0, 1, v66
	s_mov_b32 s31, 0x7fffff00
	v_and_or_b32 v0, v0, s31, v83
	v_mov_b64_e32 v[2:3], s[28:29]
	s_mov_b32 s31, 0xb000
	v_mad_u64_u32 v[2:3], s[92:93], v78, s31, v[2:3]
	v_lshl_add_u64 v[58:59], v[0:1], 2, v[2:3]
	v_add_co_u32_e32 v6, vcc, 0xb000, v58
	s_mov_b32 s31, 0x16000
	s_nop 0
	v_addc_co_u32_e32 v7, vcc, 0, v59, vcc
	v_add_co_u32_e32 v10, vcc, s31, v58
	global_load_dwordx4 v[2:5], v[58:59], off nt
	s_nop 0
	global_load_dwordx4 v[6:9], v[6:7], off nt
	v_addc_co_u32_e32 v11, vcc, 0, v59, vcc
	v_add_co_u32_e32 v14, vcc, 0x21000, v58
	s_movk_i32 s31, 0xaff
	s_nop 0
	v_addc_co_u32_e32 v15, vcc, 0, v59, vcc
	v_add_co_u32_e32 v18, vcc, 0x2c000, v58
	global_load_dwordx4 v[10:13], v[10:11], off nt
	s_nop 0
	global_load_dwordx4 v[14:17], v[14:15], off nt
	v_addc_co_u32_e32 v19, vcc, 0, v59, vcc
	v_add_co_u32_e32 v22, vcc, 0x37000, v58
	v_readlane_b32 s92, v253, 15
	s_nop 0
	v_addc_co_u32_e32 v23, vcc, 0, v59, vcc
	v_add_co_u32_e32 v26, vcc, 0x42000, v58
	global_load_dwordx4 v[18:21], v[18:19], off nt
	s_nop 0
	global_load_dwordx4 v[22:25], v[22:23], off nt
	v_addc_co_u32_e32 v27, vcc, 0, v59, vcc
	v_add_co_u32_e32 v30, vcc, 0x4d000, v58
	v_readlane_b32 s93, v253, 16
	s_nop 0
	v_addc_co_u32_e32 v31, vcc, 0, v59, vcc
	v_add_co_u32_e32 v34, vcc, 0x58000, v58
	global_load_dwordx4 v[26:29], v[26:27], off nt
	s_nop 0
	global_load_dwordx4 v[30:33], v[30:31], off nt
	v_addc_co_u32_e32 v35, vcc, 0, v59, vcc
	v_add_co_u32_e32 v38, vcc, 0x63000, v58
	s_nop 1
	v_addc_co_u32_e32 v39, vcc, 0, v59, vcc
	v_add_co_u32_e32 v42, vcc, 0x6e000, v58
	global_load_dwordx4 v[34:37], v[34:35], off nt
	s_nop 0
	global_load_dwordx4 v[38:41], v[38:39], off nt
	v_addc_co_u32_e32 v43, vcc, 0, v59, vcc
	v_add_co_u32_e32 v46, vcc, 0x79000, v58
	s_nop 1
	v_addc_co_u32_e32 v47, vcc, 0, v59, vcc
	v_add_co_u32_e32 v50, vcc, 0x84000, v58
	global_load_dwordx4 v[42:45], v[42:43], off nt
	s_nop 0
	global_load_dwordx4 v[46:49], v[46:47], off nt
	v_addc_co_u32_e32 v51, vcc, 0, v59, vcc
	v_add_co_u32_e32 v54, vcc, 0x8f000, v58
	s_nop 1
	v_addc_co_u32_e32 v55, vcc, 0, v59, vcc
	v_add_co_u32_e32 v60, vcc, 0x9a000, v58
	global_load_dwordx4 v[50:53], v[50:51], off nt
	s_nop 0
	global_load_dwordx4 v[54:57], v[54:55], off nt
	v_addc_co_u32_e32 v61, vcc, 0, v59, vcc
	v_add_co_u32_e32 v62, vcc, 0xa5000, v58
	s_nop 1
	v_addc_co_u32_e32 v63, vcc, 0, v59, vcc
	global_load_dwordx4 v[58:61], v[60:61], off nt
	s_nop 0
	global_load_dwordx4 v[62:65], v[62:63], off nt
	v_cmp_lt_u32_e32 vcc, s31, v66
	s_movk_i32 s31, 0x1000
	s_nop 0
	v_cndmask_b32_e32 v66, 0, v95, vcc
	v_add_lshl_u32 v0, v0, v66, 1
	v_and_b32_e32 v0, 0xffffff00, v0
	v_cndmask_b32_e32 v66, 0, v96, vcc
	v_or3_b32 v66, v66, v84, v0
	v_ashrrev_i32_e32 v67, 31, v66
	v_lshlrev_b64 v[66:67], 12, v[66:67]
	v_lshl_add_u64 v[66:67], s[92:93], 0, v[66:67]
	v_lshlrev_b32_e32 v0, 1, v78
	v_lshl_add_u64 v[66:67], v[66:67], 0, v[0:1]
	s_waitcnt vmcnt(14)
	v_cvt_pk_bf16_f32 v78, v2, v6
	s_waitcnt vmcnt(12)
	v_cvt_pk_bf16_f32 v79, v10, v14
	s_waitcnt vmcnt(10)
	v_cvt_pk_bf16_f32 v80, v18, v22
	s_waitcnt vmcnt(8)
	v_cvt_pk_bf16_f32 v81, v26, v30
	v_add_co_u32_e32 v2, vcc, s31, v66
	s_waitcnt vmcnt(6)
	v_cvt_pk_bf16_f32 v98, v34, v38
	s_waitcnt vmcnt(4)
	v_cvt_pk_bf16_f32 v99, v42, v46
	s_waitcnt vmcnt(2)
	v_cvt_pk_bf16_f32 v100, v50, v54
	s_waitcnt vmcnt(0)
	v_cvt_pk_bf16_f32 v101, v58, v62
	global_store_dwordx4 v[66:67], v[78:81], off
	global_store_dwordx4 v[66:67], v[98:101], off offset:16
	s_nop 0
	v_cvt_pk_bf16_f32 v78, v3, v7
	v_addc_co_u32_e32 v3, vcc, 0, v67, vcc
	v_add_co_u32_e32 v6, vcc, s21, v66
	v_cvt_pk_bf16_f32 v79, v11, v15
	v_cvt_pk_bf16_f32 v80, v19, v23
	v_cvt_pk_bf16_f32 v81, v27, v31
	v_cvt_pk_bf16_f32 v98, v35, v39
	s_nop 1
	v_addc_co_u32_e32 v7, vcc, 0, v67, vcc
	v_cvt_pk_bf16_f32 v99, v43, v47
	v_cvt_pk_bf16_f32 v100, v51, v55
	v_cvt_pk_bf16_f32 v101, v59, v63
	global_store_dwordx4 v[6:7], v[78:81], off offset:-4096
	global_store_dwordx4 v[2:3], v[98:101], off offset:16
	v_add_co_u32_e32 v10, vcc, 0x3000, v66
	v_cvt_pk_bf16_f32 v78, v4, v8
	v_cvt_pk_bf16_f32 v79, v12, v16
	v_cvt_pk_bf16_f32 v80, v20, v24
	v_cvt_pk_bf16_f32 v81, v28, v32
	s_nop 0
	v_cvt_pk_bf16_f32 v98, v36, v40
	v_cvt_pk_bf16_f32 v99, v44, v48
	v_cvt_pk_bf16_f32 v100, v52, v56
	v_cvt_pk_bf16_f32 v101, v60, v64
	global_store_dwordx4 v[6:7], v[78:81], off
	global_store_dwordx4 v[6:7], v[98:101], off offset:16
	v_cvt_pk_bf16_f32 v2, v5, v9
	v_cvt_pk_bf16_f32 v3, v13, v17
	v_cvt_pk_bf16_f32 v4, v21, v25
	v_cvt_pk_bf16_f32 v5, v29, v33
	v_addc_co_u32_e32 v11, vcc, 0, v67, vcc
	v_cvt_pk_bf16_f32 v6, v37, v41
	v_cvt_pk_bf16_f32 v7, v45, v49
	v_cvt_pk_bf16_f32 v8, v53, v57
	v_cvt_pk_bf16_f32 v9, v61, v65
	global_store_dwordx4 v[10:11], v[2:5], off
	global_store_dwordx4 v[10:11], v[6:9], off offset:16

; DI unsigned cvt_pk_bf16(float lo, float hi) { unsigned r; asm volatile("v_cvt_pk_bf16_f32 %0, %1, %2" : "=v"(r) : "v"(lo), "v"(hi)); return r; }
; DI void conv_witem(const float* W, int K, int Nsrc, bf16_t* dst, const float* rowscale, bool perm_in, int kt, int ntile, int lane, bool glu_rows = false) {
;     ...
;     const float* src = W + (size_t)k0 * Nsrc + csrc;
;     f32x4 v[16];
; #pragma unroll
;     for (int i = 0; i < 16; ++i) v[i] = valid ? *(const f32x4*)(src + (size_t)i * Nsrc) : (f32x4){0.f, 0.f, 0.f, 0.f};
;     if (rowscale) {
; #pragma unroll
;         for (int i = 0; i < 16; ++i) v[i] *= rowscale[k0 + i];
;     }
;     int drow = cdst;
;     if (glu_rows) { const int hf = cdst >= DFF ? 1 : 0, jj = cdst - hf * DFF; drow = (jj >> 7) * 256 + hf * 128 + (jj & 127); }
;     bf16_t* dp = dst + (size_t)drow * K + k0;
; #pragma unroll
;     for (int j = 0; j < 4; ++j) {
;         u32x4 w0, w1;
;         w0.x = cvt_pk_bf16(v[0][j], v[1][j]); w0.y = cvt_pk_bf16(v[2][j], v[3][j]); w0.z = cvt_pk_bf16(v[4][j], v[5][j]); w0.w = cvt_pk_bf16(v[6][j], v[7][j]);
;         w1.x = cvt_pk_bf16(v[8][j], v[9][j]); w1.y = cvt_pk_bf16(v[10][j], v[11][j]); w1.z = cvt_pk_bf16(v[12][j], v[13][j]); w1.w = cvt_pk_bf16(v[14][j], v[15][j]);
;         *(u32x4*)(dp + (size_t)j * K) = w0; *(u32x4*)(dp + (size_t)j * K + 8) = w1;
;     }
.LBB0_286:
	s_andn2_saveexec_b64 s[12:13], s[90:91]
	s_cbranch_execz .LBB0_288
	v_add_u32_e32 v0, 0xfffff2e0, v0
	v_lshlrev_b32_e32 v2, 4, v0
	v_and_b32_e32 v78, 0x7f0, v2
	v_lshlrev_b32_e32 v0, 1, v0
	s_mov_b32 s31, 0x7fffff00
	v_and_or_b32 v66, v0, s31, v83
	v_lshlrev_b32_e32 v0, 13, v78
	v_lshl_add_u64 v[2:3], s[34:35], 0, v[0:1]
	v_mov_b32_e32 v67, v1
	v_lshl_add_u64 v[58:59], v[66:67], 2, v[2:3]
	v_add_co_u32_e32 v6, vcc, 0x2000, v58
	v_lshlrev_b64 v[66:67], 12, v[66:67]
	s_nop 0
	v_addc_co_u32_e32 v7, vcc, 0, v59, vcc
	v_add_co_u32_e32 v10, vcc, 0x4000, v58
	global_load_dwordx4 v[2:5], v[58:59], off nt
	s_nop 0
	global_load_dwordx4 v[6:9], v[6:7], off nt
	v_addc_co_u32_e32 v11, vcc, 0, v59, vcc
	v_add_co_u32_e32 v14, vcc, 0x6000, v58
	v_lshl_add_u64 v[66:67], s[36:37], 0, v[66:67]
	s_nop 0
	v_addc_co_u32_e32 v15, vcc, 0, v59, vcc
	v_add_co_u32_e32 v18, vcc, 0x8000, v58
	global_load_dwordx4 v[10:13], v[10:11], off nt
	s_nop 0
	global_load_dwordx4 v[14:17], v[14:15], off nt
	v_addc_co_u32_e32 v19, vcc, 0, v59, vcc
	v_add_co_u32_e32 v22, vcc, 0xa000, v58
	v_lshlrev_b32_e32 v0, 1, v78
	s_nop 0
	v_addc_co_u32_e32 v23, vcc, 0, v59, vcc
	v_add_co_u32_e32 v26, vcc, s27, v58
	global_load_dwordx4 v[18:21], v[18:19], off nt
	s_nop 0
	global_load_dwordx4 v[22:25], v[22:23], off nt
	v_addc_co_u32_e32 v27, vcc, 0, v59, vcc
	v_add_co_u32_e32 v30, vcc, 0xe000, v58
	v_lshl_add_u64 v[66:67], v[66:67], 0, v[0:1]
	s_nop 0
	v_addc_co_u32_e32 v31, vcc, 0, v59, vcc
	v_add_co_u32_e32 v34, vcc, 0x10000, v58
	global_load_dwordx4 v[26:29], v[26:27], off nt
	s_nop 0
	global_load_dwordx4 v[30:33], v[30:31], off nt
	v_addc_co_u32_e32 v35, vcc, 0, v59, vcc
	v_add_co_u32_e32 v38, vcc, 0x12000, v58
	s_movk_i32 s31, 0x1000
	s_nop 0
	v_addc_co_u32_e32 v39, vcc, 0, v59, vcc
	v_add_co_u32_e32 v42, vcc, 0x14000, v58
	global_load_dwordx4 v[34:37], v[34:35], off nt
	s_nop 0
	global_load_dwordx4 v[38:41], v[38:39], off nt
	v_addc_co_u32_e32 v43, vcc, 0, v59, vcc
	v_add_co_u32_e32 v46, vcc, 0x16000, v58
	s_nop 1
	v_addc_co_u32_e32 v47, vcc, 0, v59, vcc
	v_add_co_u32_e32 v50, vcc, 0x18000, v58
	global_load_dwordx4 v[42:45], v[42:43], off nt
	s_nop 0
	global_load_dwordx4 v[46:49], v[46:47], off nt
	v_addc_co_u32_e32 v51, vcc, 0, v59, vcc
	v_add_co_u32_e32 v54, vcc, 0x1a000, v58
	s_nop 1
	v_addc_co_u32_e32 v55, vcc, 0, v59, vcc
	v_add_co_u32_e32 v60, vcc, 0x1c000, v58
	global_load_dwordx4 v[50:53], v[50:51], off nt
	s_nop 0
	global_load_dwordx4 v[54:57], v[54:55], off nt
	v_addc_co_u32_e32 v61, vcc, 0, v59, vcc
	v_add_co_u32_e32 v62, vcc, 0x1e000, v58
	s_nop 1
	v_addc_co_u32_e32 v63, vcc, 0, v59, vcc
	global_load_dwordx4 v[58:61], v[60:61], off nt
	s_nop 0
	global_load_dwordx4 v[62:65], v[62:63], off nt
	s_waitcnt vmcnt(14)
	v_cvt_pk_bf16_f32 v78, v2, v6
	s_waitcnt vmcnt(12)
	v_cvt_pk_bf16_f32 v79, v10, v14
	s_waitcnt vmcnt(10)
	v_cvt_pk_bf16_f32 v80, v18, v22
	s_waitcnt vmcnt(8)
	v_cvt_pk_bf16_f32 v81, v26, v30
	v_add_co_u32_e32 v2, vcc, s31, v66
	s_waitcnt vmcnt(6)
	v_cvt_pk_bf16_f32 v98, v34, v38
	s_waitcnt vmcnt(4)
	v_cvt_pk_bf16_f32 v99, v42, v46
	s_waitcnt vmcnt(2)
	v_cvt_pk_bf16_f32 v100, v50, v54
	s_waitcnt vmcnt(0)
	v_cvt_pk_bf16_f32 v101, v58, v62
	global_store_dwordx4 v[66:67], v[78:81], off
	global_store_dwordx4 v[66:67], v[98:101], off offset:16
	s_nop 0
	v_cvt_pk_bf16_f32 v78, v3, v7
	v_addc_co_u32_e32 v3, vcc, 0, v67, vcc
	v_add_co_u32_e32 v6, vcc, s21, v66
	v_cvt_pk_bf16_f32 v79, v11, v15
	v_cvt_pk_bf16_f32 v80, v19, v23
	v_cvt_pk_bf16_f32 v81, v27, v31
	v_cvt_pk_bf16_f32 v98, v35, v39
	s_nop 1
	v_addc_co_u32_e32 v7, vcc, 0, v67, vcc
	v_cvt_pk_bf16_f32 v99, v43, v47
	v_cvt_pk_bf16_f32 v100, v51, v55
	v_cvt_pk_bf16_f32 v101, v59, v63
	global_store_dwordx4 v[6:7], v[78:81], off offset:-4096
	global_store_dwordx4 v[2:3], v[98:101], off offset:16
	v_add_co_u32_e32 v10, vcc, 0x3000, v66
	v_cvt_pk_bf16_f32 v78, v4, v8
	v_cvt_pk_bf16_f32 v79, v12, v16
	v_cvt_pk_bf16_f32 v80, v20, v24
	v_cvt_pk_bf16_f32 v81, v28, v32
	s_nop 0
	v_cvt_pk_bf16_f32 v98, v36, v40
	v_cvt_pk_bf16_f32 v99, v44, v48
	v_cvt_pk_bf16_f32 v100, v52, v56
	v_cvt_pk_bf16_f32 v101, v60, v64
	global_store_dwordx4 v[6:7], v[78:81], off
	global_store_dwordx4 v[6:7], v[98:101], off offset:16
	v_cvt_pk_bf16_f32 v2, v5, v9
	v_cvt_pk_bf16_f32 v3, v13, v17
	v_cvt_pk_bf16_f32 v4, v21, v25
	v_cvt_pk_bf16_f32 v5, v29, v33
	v_addc_co_u32_e32 v11, vcc, 0, v67, vcc
	v_cvt_pk_bf16_f32 v6, v37, v41
	v_cvt_pk_bf16_f32 v7, v45, v49
	v_cvt_pk_bf16_f32 v8, v53, v57
	v_cvt_pk_bf16_f32 v9, v61, v65
	global_store_dwordx4 v[10:11], v[2:5], off
	global_store_dwordx4 v[10:11], v[6:9], off offset:16

; DI void conv_witem(const float* W, int K, int Nsrc, bf16_t* dst, const float* rowscale, bool perm_in, int kt, int ntile, int lane, bool glu_rows = false) {
;     ...
;     const float* src = W + (size_t)k0 * Nsrc + csrc;
;     f32x4 v[16];
; #pragma unroll
;     for (int i = 0; i < 16; ++i) v[i] = valid ? *(const f32x4*)(src + (size_t)i * Nsrc) : (f32x4){0.f, 0.f, 0.f, 0.f};
.LBB0_289:
	s_andn2_saveexec_b64 s[18:19], s[18:19]
	s_cbranch_execz .LBB0_325
	v_lshlrev_b32_e32 v2, 4, v0
	v_lshlrev_b32_e32 v0, 3, v0
	v_and_b32_e32 v97, 0x1f0, v2
	v_and_b32_e32 v0, 0x7f00, v0
	v_mov_b64_e32 v[2:3], s[42:43]
	v_mov_b32_e32 v8, v1
	v_mov_b32_e32 v9, v1
	v_add_u32_e32 v78, v0, v85
	v_mad_u64_u32 v[2:3], s[90:91], v97, s94, v[2:3]
	v_mov_b32_e32 v79, v1
	v_mov_b32_e32 v10, v1
	v_mov_b32_e32 v11, v1
	v_mov_b64_e32 v[4:5], v[8:9]
	v_cmp_gt_i32_e64 s[12:13], s97, v78
	v_lshl_add_u64 v[80:81], v[78:79], 2, v[2:3]
	v_mov_b64_e32 v[6:7], v[10:11]
	s_and_saveexec_b64 s[90:91], s[12:13]
	s_cbranch_execz .LBB0_292
	global_load_dwordx4 v[4:7], v[80:81], off nt
.LBB0_292:
	s_or_b64 exec, exec, s[90:91]
	s_and_saveexec_b64 s[90:91], s[12:13]
	s_cbranch_execz .LBB0_294
	v_add_co_u32_e32 v2, vcc, 0x1000, v80
	s_nop 1
	v_addc_co_u32_e32 v3, vcc, 0, v81, vcc
	global_load_dwordx4 v[8:11], v[2:3], off offset:1024 nt
.LBB0_294:
	s_or_b64 exec, exec, s[90:91]
	v_mov_b32_e32 v2, v1
	v_mov_b32_e32 v3, v1
	v_mov_b32_e32 v0, v1
	v_mov_b64_e32 v[14:15], v[2:3]
	v_mov_b64_e32 v[12:13], v[0:1]
	s_and_saveexec_b64 s[90:91], s[12:13]
	s_cbranch_execz .LBB0_296
	v_add_co_u32_e32 v12, vcc, 0x2000, v80
	s_nop 1
	v_addc_co_u32_e32 v13, vcc, 0, v81, vcc
	global_load_dwordx4 v[12:15], v[12:13], off offset:2048 nt
.LBB0_296:
	s_or_b64 exec, exec, s[90:91]
	v_mov_b64_e32 v[18:19], v[2:3]
	v_mov_b64_e32 v[16:17], v[0:1]
	s_and_saveexec_b64 s[90:91], s[12:13]
	s_cbranch_execz .LBB0_298
	v_add_co_u32_e32 v2, vcc, 0x3000, v80
	s_nop 1
	v_addc_co_u32_e32 v3, vcc, 0, v81, vcc
	global_load_dwordx4 v[16:19], v[2:3], off offset:3072 nt
.LBB0_298:
	s_or_b64 exec, exec, s[90:91]
	v_mov_b32_e32 v2, v1
	v_mov_b32_e32 v3, v1
	v_mov_b32_e32 v0, v1
	v_mov_b64_e32 v[22:23], v[2:3]
	v_mov_b64_e32 v[20:21], v[0:1]
	s_and_saveexec_b64 s[90:91], s[12:13]
	s_cbranch_execz .LBB0_300
	v_add_co_u32_e32 v20, vcc, 0x5000, v80
	s_nop 1
	v_addc_co_u32_e32 v21, vcc, 0, v81, vcc
	global_load_dwordx4 v[20:23], v[20:21], off nt
.LBB0_300:
	s_or_b64 exec, exec, s[90:91]
	v_mov_b64_e32 v[26:27], v[2:3]
	v_mov_b64_e32 v[24:25], v[0:1]
	s_and_saveexec_b64 s[90:91], s[12:13]
	s_cbranch_execz .LBB0_302
	v_add_co_u32_e32 v2, vcc, 0x6000, v80
	s_nop 1
	v_addc_co_u32_e32 v3, vcc, 0, v81, vcc
	global_load_dwordx4 v[24:27], v[2:3], off offset:1024 nt
.LBB0_302:
	s_or_b64 exec, exec, s[90:91]
	v_mov_b32_e32 v2, v1
	v_mov_b32_e32 v3, v1
	v_mov_b32_e32 v0, v1
	v_mov_b64_e32 v[30:31], v[2:3]
	v_mov_b64_e32 v[28:29], v[0:1]
	s_and_saveexec_b64 s[90:91], s[12:13]
	s_cbranch_execz .LBB0_304
	v_add_co_u32_e32 v28, vcc, 0x7000, v80
	s_nop 1
	v_addc_co_u32_e32 v29, vcc, 0, v81, vcc
	global_load_dwordx4 v[28:31], v[28:29], off offset:2048 nt
.LBB0_304:
	s_or_b64 exec, exec, s[90:91]
	v_mov_b64_e32 v[34:35], v[2:3]
	v_mov_b64_e32 v[32:33], v[0:1]
	s_and_saveexec_b64 s[90:91], s[12:13]
	s_cbranch_execz .LBB0_306
	v_add_co_u32_e32 v2, vcc, 0x8000, v80
	s_nop 1
	v_addc_co_u32_e32 v3, vcc, 0, v81, vcc
	global_load_dwordx4 v[32:35], v[2:3], off offset:3072 nt
.LBB0_306:
	s_or_b64 exec, exec, s[90:91]
	v_mov_b32_e32 v2, v1
	v_mov_b32_e32 v3, v1
	v_mov_b32_e32 v0, v1
	v_mov_b64_e32 v[38:39], v[2:3]
	v_mov_b64_e32 v[36:37], v[0:1]
	s_and_saveexec_b64 s[90:91], s[12:13]
	s_cbranch_execz .LBB0_308
	v_add_co_u32_e32 v36, vcc, 0xa000, v80
	s_nop 1
	v_addc_co_u32_e32 v37, vcc, 0, v81, vcc
	global_load_dwordx4 v[36:39], v[36:37], off nt
.LBB0_308:
	s_or_b64 exec, exec, s[90:91]
	v_mov_b64_e32 v[42:43], v[2:3]
	v_mov_b64_e32 v[40:41], v[0:1]
	s_and_saveexec_b64 s[90:91], s[12:13]
	s_cbranch_execz .LBB0_310
	v_add_co_u32_e32 v2, vcc, 0xb000, v80
	s_nop 1
	v_addc_co_u32_e32 v3, vcc, 0, v81, vcc
	global_load_dwordx4 v[40:43], v[2:3], off offset:1024 nt
.LBB0_310:
	s_or_b64 exec, exec, s[90:91]
	v_mov_b32_e32 v2, v1
	v_mov_b32_e32 v3, v1
	v_mov_b32_e32 v0, v1
	v_mov_b64_e32 v[46:47], v[2:3]
	v_mov_b64_e32 v[44:45], v[0:1]
	s_and_saveexec_b64 s[90:91], s[12:13]
	s_cbranch_execz .LBB0_312
	v_add_co_u32_e32 v44, vcc, 0xc000, v80
	s_nop 1
	v_addc_co_u32_e32 v45, vcc, 0, v81, vcc
	global_load_dwordx4 v[44:47], v[44:45], off offset:2048 nt
; DI void conv_witem(const float* W, int K, int Nsrc, bf16_t* dst, const float* rowscale, bool perm_in, int kt, int ntile, int lane, bool glu_rows = false) {
;     ...
;     for (int i = 0; i < 16; ++i) v[i] = valid ? *(const f32x4*)(src + (size_t)i * Nsrc) : (f32x4){0.f, 0.f, 0.f, 0.f};
;     if (rowscale) {
; #pragma unroll
;         for (int i = 0; i < 16; ++i) v[i] *= rowscale[k0 + i];
.LBB0_312:
	s_or_b64 exec, exec, s[90:91]
	v_mov_b64_e32 v[50:51], v[2:3]
	v_mov_b64_e32 v[48:49], v[0:1]
	s_and_saveexec_b64 s[90:91], s[12:13]
	s_cbranch_execz .LBB0_314
	v_add_co_u32_e32 v2, vcc, 0xd000, v80
	s_nop 1
	v_addc_co_u32_e32 v3, vcc, 0, v81, vcc
	global_load_dwordx4 v[48:51], v[2:3], off offset:3072 nt
.LBB0_314:
	s_or_b64 exec, exec, s[90:91]
	v_mov_b32_e32 v2, v1
	v_mov_b32_e32 v3, v1
	v_mov_b32_e32 v0, v1
	v_mov_b64_e32 v[54:55], v[2:3]
	v_mov_b64_e32 v[52:53], v[0:1]
	s_and_saveexec_b64 s[90:91], s[12:13]
	s_cbranch_execz .LBB0_316
	v_add_co_u32_e32 v52, vcc, 0xf000, v80
	s_nop 1
	v_addc_co_u32_e32 v53, vcc, 0, v81, vcc
	global_load_dwordx4 v[52:55], v[52:53], off nt
.LBB0_316:
	s_or_b64 exec, exec, s[90:91]
	v_mov_b64_e32 v[58:59], v[2:3]
	v_mov_b64_e32 v[56:57], v[0:1]
	s_and_saveexec_b64 s[90:91], s[12:13]
	s_cbranch_execz .LBB0_318
	v_add_co_u32_e32 v2, vcc, 0x10000, v80
	s_nop 1
	v_addc_co_u32_e32 v3, vcc, 0, v81, vcc
	global_load_dwordx4 v[56:59], v[2:3], off offset:1024 nt
.LBB0_318:
	s_or_b64 exec, exec, s[90:91]
	v_mov_b32_e32 v2, v1
	v_mov_b32_e32 v3, v1
	v_mov_b32_e32 v0, v1
	v_mov_b64_e32 v[62:63], v[2:3]
	v_mov_b64_e32 v[60:61], v[0:1]
	s_and_saveexec_b64 s[90:91], s[12:13]
	s_cbranch_execz .LBB0_320
	v_add_co_u32_e32 v60, vcc, 0x11000, v80
	s_nop 1
	v_addc_co_u32_e32 v61, vcc, 0, v81, vcc
	global_load_dwordx4 v[60:63], v[60:61], off offset:2048 nt
.LBB0_320:
	s_or_b64 exec, exec, s[90:91]
	v_mov_b64_e32 v[66:67], v[2:3]
	v_mov_b64_e32 v[64:65], v[0:1]
	s_and_saveexec_b64 s[90:91], s[12:13]
	s_cbranch_execz .LBB0_322
	v_add_co_u32_e32 v2, vcc, 0x12000, v80
	s_nop 1
	v_addc_co_u32_e32 v3, vcc, 0, v81, vcc
	global_load_dwordx4 v[64:67], v[2:3], off offset:3072 nt
.LBB0_322:
	s_or_b64 exec, exec, s[90:91]
	v_readlane_b32 s12, v253, 9
	v_readlane_b32 s13, v253, 10
	s_and_b64 vcc, exec, s[12:13]
	s_cbranch_vccz .LBB0_324
	v_lshlrev_b32_e32 v0, 2, v97
	global_load_dwordx4 v[98:101], v0, s[52:53] offset:2048 nt
	global_load_dwordx4 v[102:105], v0, s[52:53] offset:2064 nt
	global_load_dwordx4 v[106:109], v0, s[52:53] offset:2080 nt
	global_load_dwordx4 v[110:113], v0, s[52:53] offset:2096 nt
	s_waitcnt vmcnt(3)
	v_pk_mul_f32 v[6:7], v[6:7], v[98:99] op_sel_hi:[1,0]
	v_pk_mul_f32 v[4:5], v[4:5], v[98:99] op_sel_hi:[1,0]
	v_pk_mul_f32 v[10:11], v[10:11], v[98:99] op_sel:[0,1]
	v_pk_mul_f32 v[8:9], v[8:9], v[98:99] op_sel:[0,1]
	v_mov_b32_e32 v0, v101
	s_waitcnt vmcnt(2)
	v_mov_b32_e32 v2, v105
	s_waitcnt vmcnt(1)
	v_mov_b32_e32 v80, v109
	s_waitcnt vmcnt(0)
	v_mov_b32_e32 v98, v113
	v_pk_mul_f32 v[14:15], v[14:15], v[100:101] op_sel_hi:[1,0]
	v_pk_mul_f32 v[12:13], v[12:13], v[100:101] op_sel_hi:[1,0]
	v_pk_mul_f32 v[22:23], v[22:23], v[102:103] op_sel_hi:[1,0]
	v_pk_mul_f32 v[20:21], v[20:21], v[102:103] op_sel_hi:[1,0]
	v_pk_mul_f32 v[26:27], v[26:27], v[102:103] op_sel:[0,1]
	v_pk_mul_f32 v[24:25], v[24:25], v[102:103] op_sel:[0,1]
	v_pk_mul_f32 v[30:31], v[30:31], v[104:105] op_sel_hi:[1,0]
	v_pk_mul_f32 v[28:29], v[28:29], v[104:105] op_sel_hi:[1,0]
	v_pk_mul_f32 v[38:39], v[38:39], v[106:107] op_sel_hi:[1,0]
	v_pk_mul_f32 v[36:37], v[36:37], v[106:107] op_sel_hi:[1,0]
	v_pk_mul_f32 v[42:43], v[42:43], v[106:107] op_sel:[0,1]
	v_pk_mul_f32 v[40:41], v[40:41], v[106:107] op_sel:[0,1]
	v_pk_mul_f32 v[46:47], v[46:47], v[108:109] op_sel_hi:[1,0]
	v_pk_mul_f32 v[44:45], v[44:45], v[108:109] op_sel_hi:[1,0]
	v_pk_mul_f32 v[54:55], v[54:55], v[110:111] op_sel_hi:[1,0]
	v_pk_mul_f32 v[52:53], v[52:53], v[110:111] op_sel_hi:[1,0]
	v_pk_mul_f32 v[58:59], v[58:59], v[110:111] op_sel:[0,1]
	v_pk_mul_f32 v[56:57], v[56:57], v[110:111] op_sel:[0,1]
	v_pk_mul_f32 v[62:63], v[62:63], v[112:113] op_sel_hi:[1,0]
	v_pk_mul_f32 v[60:61], v[60:61], v[112:113] op_sel_hi:[1,0]
	v_pk_mul_f32 v[18:19], v[18:19], v[0:1] op_sel_hi:[1,0]
	v_pk_mul_f32 v[16:17], v[16:17], v[0:1] op_sel_hi:[1,0]
	v_pk_mul_f32 v[34:35], v[34:35], v[2:3] op_sel_hi:[1,0]
	v_pk_mul_f32 v[32:33], v[32:33], v[2:3] op_sel_hi:[1,0]
	v_pk_mul_f32 v[50:51], v[50:51], v[80:81] op_sel_hi:[1,0]
	v_pk_mul_f32 v[48:49], v[48:49], v[80:81] op_sel_hi:[1,0]
	v_pk_mul_f32 v[66:67], v[66:67], v[98:99] op_sel_hi:[1,0]
	v_pk_mul_f32 v[64:65], v[64:65], v[98:99] op_sel_hi:[1,0]

; DI void conv_witem(const float* W, int K, int Nsrc, bf16_t* dst, const float* rowscale, bool perm_in, int kt, int ntile, int lane, bool glu_rows = false) {
;     const int k0 = kt * 16, c0 = ntile * 256, n4 = lane * 4;
;     const int cdst = c0 + n4;
;     int csrc = cdst;
;     if (perm_in && cdst >= C_RQ && cdst < C_RV) { const int pp = cdst & 63, g = pp >> 5, e = pp & 31; csrc = (cdst & ~63) + ((e < 16) ? g * 16 + e : 32 + g * 16 + (e - 16)); }
;     const bool valid = csrc < Nsrc;
;     const float* src = W + (size_t)k0 * Nsrc + csrc;
;     f32x4 v[16];
; #pragma unroll
;     for (int i = 0; i < 16; ++i) v[i] = valid ? *(const f32x4*)(src + (size_t)i * Nsrc) : (f32x4){0.f, 0.f, 0.f, 0.f};
.LBB0_326:
	s_andn2_saveexec_b64 s[16:17], s[16:17]
	s_cbranch_execz .LBB0_362
	v_lshlrev_b32_e32 v2, 4, v0
	v_lshlrev_b32_e32 v0, 3, v0
	v_and_b32_e32 v97, 0x1f0, v2
	v_and_b32_e32 v0, 0x7f00, v0
	v_mov_b64_e32 v[2:3], s[54:55]
	s_movk_i32 s18, 0xf00
	v_mov_b32_e32 v6, v1
	v_mov_b32_e32 v7, v1
	v_add_u32_e32 v78, v0, v86
	s_movk_i32 s12, 0x3c0
	v_mad_u64_u32 v[2:3], s[18:19], v97, s18, v[2:3]
	v_mov_b32_e32 v79, v1
	v_mov_b32_e32 v4, v1
	v_mov_b32_e32 v5, v1
	v_mov_b64_e32 v[10:11], v[6:7]
	v_cmp_gt_i32_e64 s[12:13], s12, v78
	v_lshl_add_u64 v[80:81], v[78:79], 2, v[2:3]
	v_mov_b64_e32 v[8:9], v[4:5]
	s_and_saveexec_b64 s[18:19], s[12:13]
	s_cbranch_execz .LBB0_329
	global_load_dwordx4 v[8:11], v[80:81], off nt

; DI void conv_witem(const float* W, int K, int Nsrc, bf16_t* dst, const float* rowscale, bool perm_in, int kt, int ntile, int lane, bool glu_rows = false) {
;     ...
;     if (rowscale) {
; #pragma unroll
;         for (int i = 0; i < 16; ++i) v[i] *= rowscale[k0 + i];
.LBB0_359:
	s_or_b64 exec, exec, s[18:19]
	v_readlane_b32 s12, v253, 13
	v_readlane_b32 s13, v253, 14
	s_and_b64 vcc, exec, s[12:13]
	s_cbranch_vccz .LBB0_361
	v_lshlrev_b32_e32 v0, 2, v97
	global_load_dwordx4 v[98:101], v0, s[82:83] offset:2048 nt
	global_load_dwordx4 v[102:105], v0, s[82:83] offset:2064 nt
	global_load_dwordx4 v[106:109], v0, s[82:83] offset:2080 nt
	global_load_dwordx4 v[110:113], v0, s[82:83] offset:2096 nt
	s_waitcnt vmcnt(3)
	v_pk_mul_f32 v[10:11], v[10:11], v[98:99] op_sel_hi:[1,0]
	v_pk_mul_f32 v[8:9], v[8:9], v[98:99] op_sel_hi:[1,0]
	v_pk_mul_f32 v[6:7], v[6:7], v[98:99] op_sel:[0,1]
	v_pk_mul_f32 v[4:5], v[4:5], v[98:99] op_sel:[0,1]
	v_mov_b32_e32 v0, v101
	s_waitcnt vmcnt(2)
	v_mov_b32_e32 v2, v105
	s_waitcnt vmcnt(1)
	v_mov_b32_e32 v80, v109
	s_waitcnt vmcnt(0)
	v_mov_b32_e32 v98, v113
	v_pk_mul_f32 v[14:15], v[14:15], v[100:101] op_sel_hi:[1,0]
	v_pk_mul_f32 v[12:13], v[12:13], v[100:101] op_sel_hi:[1,0]
	v_pk_mul_f32 v[22:23], v[22:23], v[102:103] op_sel_hi:[1,0]
	v_pk_mul_f32 v[20:21], v[20:21], v[102:103] op_sel_hi:[1,0]
	v_pk_mul_f32 v[26:27], v[26:27], v[102:103] op_sel:[0,1]
	v_pk_mul_f32 v[24:25], v[24:25], v[102:103] op_sel:[0,1]
	v_pk_mul_f32 v[30:31], v[30:31], v[104:105] op_sel_hi:[1,0]
	v_pk_mul_f32 v[28:29], v[28:29], v[104:105] op_sel_hi:[1,0]
	v_pk_mul_f32 v[38:39], v[38:39], v[106:107] op_sel_hi:[1,0]
	v_pk_mul_f32 v[36:37], v[36:37], v[106:107] op_sel_hi:[1,0]
	v_pk_mul_f32 v[42:43], v[42:43], v[106:107] op_sel:[0,1]
	v_pk_mul_f32 v[40:41], v[40:41], v[106:107] op_sel:[0,1]
	v_pk_mul_f32 v[46:47], v[46:47], v[108:109] op_sel_hi:[1,0]
	v_pk_mul_f32 v[44:45], v[44:45], v[108:109] op_sel_hi:[1,0]
	v_pk_mul_f32 v[54:55], v[54:55], v[110:111] op_sel_hi:[1,0]
	v_pk_mul_f32 v[52:53], v[52:53], v[110:111] op_sel_hi:[1,0]
	v_pk_mul_f32 v[58:59], v[58:59], v[110:111] op_sel:[0,1]
	v_pk_mul_f32 v[56:57], v[56:57], v[110:111] op_sel:[0,1]
	v_pk_mul_f32 v[62:63], v[62:63], v[112:113] op_sel_hi:[1,0]
	v_pk_mul_f32 v[60:61], v[60:61], v[112:113] op_sel_hi:[1,0]
	v_pk_mul_f32 v[18:19], v[18:19], v[0:1] op_sel_hi:[1,0]
	v_pk_mul_f32 v[16:17], v[16:17], v[0:1] op_sel_hi:[1,0]
	v_pk_mul_f32 v[34:35], v[34:35], v[2:3] op_sel_hi:[1,0]
	v_pk_mul_f32 v[32:33], v[32:33], v[2:3] op_sel_hi:[1,0]
	v_pk_mul_f32 v[50:51], v[50:51], v[80:81] op_sel_hi:[1,0]
	v_pk_mul_f32 v[48:49], v[48:49], v[80:81] op_sel_hi:[1,0]
	v_pk_mul_f32 v[66:67], v[66:67], v[98:99] op_sel_hi:[1,0]
	v_pk_mul_f32 v[64:65], v[64:65], v[98:99] op_sel_hi:[1,0]

; DI void conv_witem(const float* W, int K, int Nsrc, bf16_t* dst, const float* rowscale, bool perm_in, int kt, int ntile, int lane, bool glu_rows = false) {
;     const int k0 = kt * 16, c0 = ntile * 256, n4 = lane * 4;
;     const int cdst = c0 + n4;
;     int csrc = cdst;
;     if (perm_in && cdst >= C_RQ && cdst < C_RV) { const int pp = cdst & 63, g = pp >> 5, e = pp & 31; csrc = (cdst & ~63) + ((e < 16) ? g * 16 + e : 32 + g * 16 + (e - 16)); }
;     const bool valid = csrc < Nsrc;
;     const float* src = W + (size_t)k0 * Nsrc + csrc;
;     f32x4 v[16];
; #pragma unroll
;     for (int i = 0; i < 16; ++i) v[i] = valid ? *(const f32x4*)(src + (size_t)i * Nsrc) : (f32x4){0.f, 0.f, 0.f, 0.f};
.LBB0_363:
	s_andn2_saveexec_b64 s[16:17], s[88:89]
	s_cbranch_execz .LBB0_397
	v_ashrrev_i32_e32 v2, 31, v0
	v_lshrrev_b32_e32 v2, 25, v2
	v_add_u32_e32 v2, v0, v2
	v_and_b32_e32 v3, 0xfffff80, v2
	v_sub_u32_e32 v0, v0, v3
	v_lshlrev_b32_e32 v66, 4, v0
	v_lshlrev_b32_e32 v0, 1, v2
	v_and_b32_e32 v0, 0xffffff00, v0
	v_or_b32_e32 v78, v0, v83
	s_movk_i32 s12, 0x1fc0
	v_add_u32_e32 v2, 0xfffff2c0, v78
	v_bitop3_b32 v0, v0, s12, v83 bitop3:0xc8
	v_add_u32_e32 v0, v0, v87
	v_cmp_gt_u32_e32 vcc, s97, v2
	v_mov_b64_e32 v[4:5], s[80:81]
	s_movk_i32 s18, 0x5d00
	v_cndmask_b32_e32 v2, v78, v0, vcc
	s_movk_i32 s12, 0x1740
	v_mad_i64_i32 v[4:5], s[18:19], v66, s18, v[4:5]
	v_ashrrev_i32_e32 v3, 31, v2
	v_cmp_gt_i32_e64 s[12:13], s12, v2
	v_lshl_add_u64 v[80:81], v[2:3], 2, v[4:5]
	v_mov_b32_e32 v6, 0
	v_mov_b32_e32 v2, 0
	v_mov_b32_e32 v3, 0
	v_mov_b32_e32 v4, 0
	v_mov_b32_e32 v5, 0
	s_and_saveexec_b64 s[18:19], s[12:13]
	s_cbranch_execz .LBB0_366
	global_load_dwordx4 v[2:5], v[80:81], off nt
.LBB0_366:
	s_or_b64 exec, exec, s[18:19]
	v_mov_b32_e32 v7, 0
	v_mov_b32_e32 v8, 0
	v_mov_b32_e32 v9, 0
	s_and_saveexec_b64 s[18:19], s[12:13]
	s_cbranch_execz .LBB0_368
	v_add_co_u32_e32 v6, vcc, 0x5000, v80
	s_nop 1
	v_addc_co_u32_e32 v7, vcc, 0, v81, vcc
	global_load_dwordx4 v[6:9], v[6:7], off offset:3328 nt
.LBB0_368:
	s_or_b64 exec, exec, s[18:19]
	v_mov_b32_e32 v10, 0
	v_mov_b32_e32 v14, 0
	v_mov_b32_e32 v15, 0
	v_mov_b32_e32 v16, 0
	v_mov_b32_e32 v17, 0
	s_and_saveexec_b64 s[18:19], s[12:13]
	s_cbranch_execz .LBB0_370
	v_add_co_u32_e32 v12, vcc, 0xb000, v80
	s_nop 1
	v_addc_co_u32_e32 v13, vcc, 0, v81, vcc
	global_load_dwordx4 v[14:17], v[12:13], off offset:2560 nt
.LBB0_370:
	s_or_b64 exec, exec, s[18:19]
	v_mov_b32_e32 v11, 0
	v_mov_b32_e32 v12, 0
	v_mov_b32_e32 v13, 0
	s_and_saveexec_b64 s[18:19], s[12:13]
	s_cbranch_execz .LBB0_372
	v_add_co_u32_e32 v10, vcc, 0x11000, v80
	s_nop 1
	v_addc_co_u32_e32 v11, vcc, 0, v81, vcc
	global_load_dwordx4 v[10:13], v[10:11], off offset:1792 nt
.LBB0_372:
	s_or_b64 exec, exec, s[18:19]
	v_mov_b32_e32 v18, 0
	v_mov_b32_e32 v22, 0
	v_mov_b32_e32 v23, 0
	v_mov_b32_e32 v24, 0
	v_mov_b32_e32 v25, 0
	s_and_saveexec_b64 s[18:19], s[12:13]
	s_cbranch_execz .LBB0_374
	v_add_co_u32_e32 v20, vcc, 0x17000, v80
	s_nop 1
	v_addc_co_u32_e32 v21, vcc, 0, v81, vcc
	global_load_dwordx4 v[22:25], v[20:21], off offset:1024 nt
.LBB0_374:
	s_or_b64 exec, exec, s[18:19]
	v_mov_b32_e32 v19, 0
	v_mov_b32_e32 v20, 0
	v_mov_b32_e32 v21, 0
	s_and_saveexec_b64 s[18:19], s[12:13]
	s_cbranch_execz .LBB0_376
	v_add_co_u32_e32 v18, vcc, 0x1d000, v80
	s_nop 1
	v_addc_co_u32_e32 v19, vcc, 0, v81, vcc
	global_load_dwordx4 v[18:21], v[18:19], off offset:256 nt
.LBB0_376:
	s_or_b64 exec, exec, s[18:19]
	v_mov_b32_e32 v26, 0
	v_mov_b32_e32 v30, 0
	v_mov_b32_e32 v31, 0
	v_mov_b32_e32 v32, 0
	v_mov_b32_e32 v33, 0
	s_and_saveexec_b64 s[18:19], s[12:13]
	s_cbranch_execz .LBB0_378
	v_add_co_u32_e32 v28, vcc, 0x22000, v80
	s_nop 1
	v_addc_co_u32_e32 v29, vcc, 0, v81, vcc
	global_load_dwordx4 v[30:33], v[28:29], off offset:3584 nt
.LBB0_378:
	s_or_b64 exec, exec, s[18:19]
	v_mov_b32_e32 v27, 0
	v_mov_b32_e32 v28, 0
	v_mov_b32_e32 v29, 0
	s_and_saveexec_b64 s[18:19], s[12:13]
	s_cbranch_execz .LBB0_380
	v_add_co_u32_e32 v26, vcc, 0x28000, v80
	s_nop 1
	v_addc_co_u32_e32 v27, vcc, 0, v81, vcc
	global_load_dwordx4 v[26:29], v[26:27], off offset:2816 nt
.LBB0_380:
	s_or_b64 exec, exec, s[18:19]
	v_mov_b32_e32 v34, 0
	v_mov_b32_e32 v38, 0
	v_mov_b32_e32 v39, 0
	v_mov_b32_e32 v40, 0
	v_mov_b32_e32 v41, 0
	s_and_saveexec_b64 s[18:19], s[12:13]
	s_cbranch_execz .LBB0_382
	v_add_co_u32_e32 v36, vcc, 0x2e000, v80
	s_nop 1
	v_addc_co_u32_e32 v37, vcc, 0, v81, vcc
	global_load_dwordx4 v[38:41], v[36:37], off offset:2048 nt
.LBB0_382:
	s_or_b64 exec, exec, s[18:19]
	v_mov_b32_e32 v35, 0
	v_mov_b32_e32 v36, 0
	v_mov_b32_e32 v37, 0
	s_and_saveexec_b64 s[18:19], s[12:13]
	s_cbranch_execz .LBB0_384
	v_add_co_u32_e32 v34, vcc, 0x34000, v80
	s_nop 1
	v_addc_co_u32_e32 v35, vcc, 0, v81, vcc
	global_load_dwordx4 v[34:37], v[34:35], off offset:1280 nt
.LBB0_384:
	s_or_b64 exec, exec, s[18:19]
	v_mov_b32_e32 v42, 0
	v_mov_b32_e32 v46, 0
	v_mov_b32_e32 v47, 0
	v_mov_b32_e32 v48, 0
	v_mov_b32_e32 v49, 0
	s_and_saveexec_b64 s[18:19], s[12:13]
	s_cbranch_execz .LBB0_386
	v_add_co_u32_e32 v44, vcc, 0x3a000, v80
	s_nop 1
	v_addc_co_u32_e32 v45, vcc, 0, v81, vcc
	global_load_dwordx4 v[46:49], v[44:45], off offset:512 nt
.LBB0_386:
	s_or_b64 exec, exec, s[18:19]
	v_mov_b32_e32 v43, 0
	v_mov_b32_e32 v44, 0
	v_mov_b32_e32 v45, 0
	s_and_saveexec_b64 s[18:19], s[12:13]
	s_cbranch_execz .LBB0_388
	v_add_co_u32_e32 v42, vcc, 0x3f000, v80
	s_nop 1
	v_addc_co_u32_e32 v43, vcc, 0, v81, vcc
	global_load_dwordx4 v[42:45], v[42:43], off offset:3840 nt
.LBB0_388:
	s_or_b64 exec, exec, s[18:19]
	v_mov_b32_e32 v50, 0
	v_mov_b32_e32 v54, 0
	v_mov_b32_e32 v55, 0
	v_mov_b32_e32 v56, 0
	v_mov_b32_e32 v57, 0
	s_and_saveexec_b64 s[18:19], s[12:13]
	s_cbranch_execz .LBB0_390
	v_add_co_u32_e32 v52, vcc, 0x45000, v80
	s_nop 1
	v_addc_co_u32_e32 v53, vcc, 0, v81, vcc
	global_load_dwordx4 v[54:57], v[52:53], off offset:3072 nt
.LBB0_390:
	s_or_b64 exec, exec, s[18:19]
	v_mov_b32_e32 v51, 0
	v_mov_b32_e32 v52, 0
	v_mov_b32_e32 v53, 0
	s_and_saveexec_b64 s[18:19], s[12:13]
	s_cbranch_execz .LBB0_392
	v_add_co_u32_e32 v50, vcc, 0x4b000, v80
	s_nop 1
	v_addc_co_u32_e32 v51, vcc, 0, v81, vcc
	global_load_dwordx4 v[50:53], v[50:51], off offset:2304 nt
.LBB0_392:
	s_or_b64 exec, exec, s[18:19]
	v_mov_b32_e32 v58, 0
	v_mov_b32_e32 v62, 0
	v_mov_b32_e32 v63, 0
	v_mov_b32_e32 v64, 0
	v_mov_b32_e32 v65, 0
	s_and_saveexec_b64 s[18:19], s[12:13]
	s_cbranch_execz .LBB0_394
	v_add_co_u32_e32 v60, vcc, 0x51000, v80
	s_nop 1
	v_addc_co_u32_e32 v61, vcc, 0, v81, vcc
	global_load_dwordx4 v[62:65], v[60:61], off offset:1536 nt
.LBB0_394:
	s_or_b64 exec, exec, s[18:19]
	v_mov_b32_e32 v59, 0
	v_mov_b32_e32 v60, 0
	v_mov_b32_e32 v61, 0
	s_and_saveexec_b64 s[18:19], s[12:13]
	s_cbranch_execz .LBB0_396
	v_add_co_u32_e32 v58, vcc, 0x57000, v80
	s_nop 1
	v_addc_co_u32_e32 v59, vcc, 0, v81, vcc
	global_load_dwordx4 v[58:61], v[58:59], off offset:768 nt

; #define LAS __attribute__((address_space(3)))
; DI void prep_items(const Params& p, LAS unsigned char* lds, int l, unsigned* ctr, int max_items) {
;     ...
;             const int n0 = it * 256;
;             const float* W = p.in[4] + (size_t)l * 2048 * 12288 + n0 + lane * 4;
;             f32x4 a0 = (f32x4){0.f, 0.f, 0.f, 0.f}, a1 = a0, a2 = a0, a3 = a0, a4 = a0;
; #pragma unroll 8
;             for (int k = wid; k < 2048; k += 8) { const f32x4 w = *(const f32x4*)(W + (size_t)k * 12288); a0 += w * s_c[k]; a1 += w * s_c[2048 + k]; a2 += w * s_c[4096 + k]; a3 += w * s_c[6144 + k]; a4 += w * s_c[8192 + k]; }
;             *(LAS f32x4*)(s_red + (wid * 5 + 0) * 256 + lane * 4) = a0; *(LAS f32x4*)(s_red + (wid * 5 + 1) * 256 + lane * 4) = a1; *(LAS f32x4*)(s_red + (wid * 5 + 2) * 256 + lane * 4) = a2;
;             *(LAS f32x4*)(s_red + (wid * 5 + 3) * 256 + lane * 4) = a3; *(LAS f32x4*)(s_red + (wid * 5 + 4) * 256 + lane * 4) = a4;
.LBB0_407:
	global_load_dwordx4 v[26:29], v[22:23], off nt
	ds_read2st64_b32 v[30:31], v24 offset1:32
	ds_read2st64_b32 v[32:33], v24 offset0:64 offset1:96
	ds_read_b32 v34, v24 offset:32768
	s_mov_b64 s[30:31], 0x60000
	v_add_co_u32_e32 v0, vcc, 1, v0
	s_waitcnt lgkmcnt(2)
	v_mov_b32_e32 v38, v31
	s_waitcnt lgkmcnt(1)
	v_mov_b32_e32 v40, v33
	v_add_u32_e32 v36, 8, v36
	v_add_u32_e32 v24, 32, v24
	v_lshl_add_u64 v[22:23], v[22:23], 0, s[30:31]
	s_or_b64 s[76:77], vcc, s[76:77]
	s_waitcnt vmcnt(0)
	v_pk_fma_f32 v[4:5], v[28:29], v[30:31], v[4:5] op_sel_hi:[1,0,1]
	v_pk_fma_f32 v[2:3], v[26:27], v[30:31], v[2:3] op_sel_hi:[1,0,1]
	v_pk_fma_f32 v[8:9], v[28:29], v[38:39], v[8:9] op_sel_hi:[1,0,1]
	v_pk_fma_f32 v[6:7], v[26:27], v[38:39], v[6:7] op_sel_hi:[1,0,1]
	v_pk_fma_f32 v[12:13], v[28:29], v[32:33], v[12:13] op_sel_hi:[1,0,1]
	v_pk_fma_f32 v[10:11], v[26:27], v[32:33], v[10:11] op_sel_hi:[1,0,1]
	v_pk_fma_f32 v[16:17], v[28:29], v[40:41], v[16:17] op_sel_hi:[1,0,1]
	v_pk_fma_f32 v[14:15], v[26:27], v[40:41], v[14:15] op_sel_hi:[1,0,1]
	s_waitcnt lgkmcnt(0)
	v_pk_fma_f32 v[20:21], v[28:29], v[34:35], v[20:21] op_sel_hi:[1,0,1]
	v_pk_fma_f32 v[18:19], v[26:27], v[34:35], v[18:19] op_sel_hi:[1,0,1]
	s_andn2_b64 exec, exec, s[76:77]
	s_cbranch_execnz .LBB0_407
	s_or_b64 exec, exec, s[76:77]

; #define LAS __attribute__((address_space(3)))
; DI void prep_items(const Params& p, LAS unsigned char* lds, int l, unsigned* ctr, int max_items) {
;     ...
;             const int n0 = it * 256;
;             const float* W = p.in[4] + (size_t)l * 2048 * 12288 + n0 + lane * 4;
;             f32x4 a0 = (f32x4){0.f, 0.f, 0.f, 0.f}, a1 = a0, a2 = a0, a3 = a0, a4 = a0;
; #pragma unroll 8
;             for (int k = wid; k < 2048; k += 8) { const f32x4 w = *(const f32x4*)(W + (size_t)k * 12288); a0 += w * s_c[k]; a1 += w * s_c[2048 + k]; a2 += w * s_c[4096 + k]; a3 += w * s_c[6144 + k]; a4 += w * s_c[8192 + k]; }
;             *(LAS f32x4*)(s_red + (wid * 5 + 0) * 256 + lane * 4) = a0; *(LAS f32x4*)(s_red + (wid * 5 + 1) * 256 + lane * 4) = a1; *(LAS f32x4*)(s_red + (wid * 5 + 2) * 256 + lane * 4) = a2;
;             *(LAS f32x4*)(s_red + (wid * 5 + 3) * 256 + lane * 4) = a3; *(LAS f32x4*)(s_red + (wid * 5 + 4) * 256 + lane * 4) = a4;
.LBB0_411:
	v_lshl_add_u64 v[42:43], v[36:37], 0, s[76:77]
	ds_read2_b32 v[38:39], v52 offset1:8
	v_add_u32_e32 v53, 0x2000, v52
	v_lshl_add_u64 v[46:47], v[34:35], 0, s[76:77]
	v_lshl_add_u64 v[50:51], v[32:33], 0, s[76:77]
	ds_read2_b32 v[40:41], v52 offset0:16 offset1:24
	v_lshl_add_u64 v[66:67], v[30:31], 0, s[76:77]
	v_lshl_add_u64 v[98:99], v[28:29], 0, s[76:77]
	ds_read2_b32 v[44:45], v52 offset0:32 offset1:40
	ds_read2_b32 v[48:49], v52 offset0:48 offset1:56
	global_load_dwordx4 v[54:57], v[42:43], off nt
	global_load_dwordx4 v[58:61], v[46:47], off nt
	global_load_dwordx4 v[62:65], v[50:51], off nt
	global_load_dwordx4 v[78:81], v[66:67], off nt
	v_add_u32_e32 v97, 0x4000, v52
	v_add_u32_e32 v112, 0x6000, v52
	v_lshl_add_u64 v[102:103], v[26:27], 0, s[76:77]
	ds_read2_b32 v[42:43], v53 offset1:8
	ds_read2_b32 v[46:47], v97 offset1:8
	global_load_dwordx4 v[98:101], v[98:99], off nt
	v_add_u32_e32 v113, 0x8000, v52
	v_lshl_add_u64 v[106:107], v[24:25], 0, s[76:77]
	ds_read2_b32 v[50:51], v112 offset1:8
	ds_read2_b32 v[66:67], v113 offset1:8
	ds_read2_b32 v[114:115], v53 offset0:16 offset1:24
	ds_read2_b32 v[116:117], v97 offset0:16 offset1:24
	ds_read2_b32 v[118:119], v112 offset0:16 offset1:24
	ds_read2_b32 v[120:121], v113 offset0:16 offset1:24
	ds_read2_b32 v[122:123], v53 offset0:32 offset1:40
	ds_read2_b32 v[124:125], v97 offset0:32 offset1:40
	ds_read2_b32 v[126:127], v112 offset0:32 offset1:40
	global_load_dwordx4 v[102:105], v[102:103], off nt
	v_lshl_add_u64 v[110:111], v[22:23], 0, s[76:77]
	global_load_dwordx4 v[106:109], v[106:107], off nt
	ds_read2_b32 v[128:129], v113 offset0:32 offset1:40
	ds_read2_b32 v[130:131], v53 offset0:48 offset1:56
	ds_read2_b32 v[132:133], v97 offset0:48 offset1:56
	ds_read2_b32 v[134:135], v112 offset0:48 offset1:56
	ds_read2_b32 v[136:137], v113 offset0:48 offset1:56
	global_load_dwordx4 v[110:113], v[110:111], off nt
	s_waitcnt lgkmcnt(14)
	v_mov_b32_e32 v138, v39
	v_mov_b32_e32 v146, v43
	v_mov_b32_e32 v148, v47
	s_waitcnt lgkmcnt(13)
	v_mov_b32_e32 v150, v51
	s_waitcnt lgkmcnt(12)
	v_mov_b32_e32 v152, v67
	v_mov_b32_e32 v140, v41
	s_waitcnt lgkmcnt(11)
	v_mov_b32_e32 v154, v115
	s_waitcnt lgkmcnt(10)
	v_mov_b32_e32 v156, v117
	s_waitcnt lgkmcnt(9)
	v_mov_b32_e32 v158, v119
	s_waitcnt lgkmcnt(8)
	v_mov_b32_e32 v160, v121
	v_mov_b32_e32 v142, v45
	s_waitcnt lgkmcnt(7)
	v_mov_b32_e32 v162, v123
	s_waitcnt lgkmcnt(6)
	v_mov_b32_e32 v164, v125
	s_waitcnt lgkmcnt(5)
	v_mov_b32_e32 v166, v127
	s_waitcnt lgkmcnt(4)
	v_mov_b32_e32 v168, v129
	v_add_u32_e32 v0, 64, v0
	s_movk_i32 s30, 0x7bf
	v_cmp_lt_i32_e32 vcc, s30, v0
	v_mov_b32_e32 v144, v49
	s_waitcnt lgkmcnt(3)
	v_mov_b32_e32 v170, v131
	s_waitcnt lgkmcnt(2)
	v_mov_b32_e32 v172, v133
	s_waitcnt lgkmcnt(1)
	v_mov_b32_e32 v174, v135
	s_waitcnt lgkmcnt(0)
	v_mov_b32_e32 v176, v137
	v_lshl_add_u64 v[22:23], v[22:23], 0, s[70:71]
	v_lshl_add_u64 v[24:25], v[24:25], 0, s[70:71]
	v_lshl_add_u64 v[26:27], v[26:27], 0, s[70:71]
	v_lshl_add_u64 v[28:29], v[28:29], 0, s[70:71]
	v_lshl_add_u64 v[30:31], v[30:31], 0, s[70:71]
	v_lshl_add_u64 v[32:33], v[32:33], 0, s[70:71]
	v_lshl_add_u64 v[34:35], v[34:35], 0, s[70:71]
	v_add_u32_e32 v52, 0x100, v52
	v_lshl_add_u64 v[36:37], v[36:37], 0, s[70:71]
	s_or_b64 s[86:87], vcc, s[86:87]
	s_waitcnt vmcnt(7)
	v_pk_fma_f32 v[2:3], v[54:55], v[38:39], v[2:3] op_sel_hi:[1,0,1]
	v_pk_fma_f32 v[4:5], v[56:57], v[38:39], v[4:5] op_sel_hi:[1,0,1]
	v_pk_fma_f32 v[6:7], v[54:55], v[42:43], v[6:7] op_sel_hi:[1,0,1]
	v_pk_fma_f32 v[8:9], v[56:57], v[42:43], v[8:9] op_sel_hi:[1,0,1]
	v_pk_fma_f32 v[10:11], v[54:55], v[46:47], v[10:11] op_sel_hi:[1,0,1]
	v_pk_fma_f32 v[12:13], v[56:57], v[46:47], v[12:13] op_sel_hi:[1,0,1]
	v_pk_fma_f32 v[14:15], v[54:55], v[50:51], v[14:15] op_sel_hi:[1,0,1]
	v_pk_fma_f32 v[16:17], v[56:57], v[50:51], v[16:17] op_sel_hi:[1,0,1]
	v_pk_fma_f32 v[18:19], v[54:55], v[66:67], v[18:19] op_sel_hi:[1,0,1]
	v_pk_fma_f32 v[20:21], v[56:57], v[66:67], v[20:21] op_sel_hi:[1,0,1]
	s_waitcnt vmcnt(6)
	v_pk_fma_f32 v[4:5], v[60:61], v[138:139], v[4:5] op_sel_hi:[1,0,1]
	v_pk_fma_f32 v[2:3], v[58:59], v[138:139], v[2:3] op_sel_hi:[1,0,1]
	v_pk_fma_f32 v[8:9], v[60:61], v[146:147], v[8:9] op_sel_hi:[1,0,1]
	v_pk_fma_f32 v[6:7], v[58:59], v[146:147], v[6:7] op_sel_hi:[1,0,1]
	v_pk_fma_f32 v[12:13], v[60:61], v[148:149], v[12:13] op_sel_hi:[1,0,1]
	v_pk_fma_f32 v[10:11], v[58:59], v[148:149], v[10:11] op_sel_hi:[1,0,1]
	v_pk_fma_f32 v[16:17], v[60:61], v[150:151], v[16:17] op_sel_hi:[1,0,1]
	v_pk_fma_f32 v[14:15], v[58:59], v[150:151], v[14:15] op_sel_hi:[1,0,1]
	v_pk_fma_f32 v[20:21], v[60:61], v[152:153], v[20:21] op_sel_hi:[1,0,1]
	v_pk_fma_f32 v[18:19], v[58:59], v[152:153], v[18:19] op_sel_hi:[1,0,1]
	s_waitcnt vmcnt(5)
; #define LAS __attribute__((address_space(3)))
; DI void prep_items(const Params& p, LAS unsigned char* lds, int l, unsigned* ctr, int max_items) {
;     ...
;             const int n0 = it * 256;
;             const float* W = p.in[4] + (size_t)l * 2048 * 12288 + n0 + lane * 4;
;             f32x4 a0 = (f32x4){0.f, 0.f, 0.f, 0.f}, a1 = a0, a2 = a0, a3 = a0, a4 = a0;
; #pragma unroll 8
;             for (int k = wid; k < 2048; k += 8) { const f32x4 w = *(const f32x4*)(W + (size_t)k * 12288); a0 += w * s_c[k]; a1 += w * s_c[2048 + k]; a2 += w * s_c[4096 + k]; a3 += w * s_c[6144 + k]; a4 += w * s_c[8192 + k]; }
;             *(LAS f32x4*)(s_red + (wid * 5 + 0) * 256 + lane * 4) = a0; *(LAS f32x4*)(s_red + (wid * 5 + 1) * 256 + lane * 4) = a1; *(LAS f32x4*)(s_red + (wid * 5 + 2) * 256 + lane * 4) = a2;
;             *(LAS f32x4*)(s_red + (wid * 5 + 3) * 256 + lane * 4) = a3; *(LAS f32x4*)(s_red + (wid * 5 + 4) * 256 + lane * 4) = a4;
	v_pk_fma_f32 v[4:5], v[64:65], v[40:41], v[4:5] op_sel_hi:[1,0,1]
	v_pk_fma_f32 v[2:3], v[62:63], v[40:41], v[2:3] op_sel_hi:[1,0,1]
	v_pk_fma_f32 v[8:9], v[64:65], v[114:115], v[8:9] op_sel_hi:[1,0,1]
	v_pk_fma_f32 v[6:7], v[62:63], v[114:115], v[6:7] op_sel_hi:[1,0,1]
	v_pk_fma_f32 v[12:13], v[64:65], v[116:117], v[12:13] op_sel_hi:[1,0,1]
	v_pk_fma_f32 v[10:11], v[62:63], v[116:117], v[10:11] op_sel_hi:[1,0,1]
	v_pk_fma_f32 v[16:17], v[64:65], v[118:119], v[16:17] op_sel_hi:[1,0,1]
	v_pk_fma_f32 v[14:15], v[62:63], v[118:119], v[14:15] op_sel_hi:[1,0,1]
	v_pk_fma_f32 v[20:21], v[64:65], v[120:121], v[20:21] op_sel_hi:[1,0,1]
	v_pk_fma_f32 v[18:19], v[62:63], v[120:121], v[18:19] op_sel_hi:[1,0,1]
	s_waitcnt vmcnt(4)
	v_pk_fma_f32 v[4:5], v[80:81], v[140:141], v[4:5] op_sel_hi:[1,0,1]
	v_pk_fma_f32 v[2:3], v[78:79], v[140:141], v[2:3] op_sel_hi:[1,0,1]
	v_pk_fma_f32 v[8:9], v[80:81], v[154:155], v[8:9] op_sel_hi:[1,0,1]
	v_pk_fma_f32 v[6:7], v[78:79], v[154:155], v[6:7] op_sel_hi:[1,0,1]
	v_pk_fma_f32 v[12:13], v[80:81], v[156:157], v[12:13] op_sel_hi:[1,0,1]
	v_pk_fma_f32 v[10:11], v[78:79], v[156:157], v[10:11] op_sel_hi:[1,0,1]
	v_pk_fma_f32 v[16:17], v[80:81], v[158:159], v[16:17] op_sel_hi:[1,0,1]
	v_pk_fma_f32 v[14:15], v[78:79], v[158:159], v[14:15] op_sel_hi:[1,0,1]
	v_pk_fma_f32 v[20:21], v[80:81], v[160:161], v[20:21] op_sel_hi:[1,0,1]
	v_pk_fma_f32 v[18:19], v[78:79], v[160:161], v[18:19] op_sel_hi:[1,0,1]
	s_waitcnt vmcnt(3)
	v_pk_fma_f32 v[4:5], v[100:101], v[44:45], v[4:5] op_sel_hi:[1,0,1]
	v_pk_fma_f32 v[2:3], v[98:99], v[44:45], v[2:3] op_sel_hi:[1,0,1]
	v_pk_fma_f32 v[8:9], v[100:101], v[122:123], v[8:9] op_sel_hi:[1,0,1]
	v_pk_fma_f32 v[6:7], v[98:99], v[122:123], v[6:7] op_sel_hi:[1,0,1]
	v_pk_fma_f32 v[12:13], v[100:101], v[124:125], v[12:13] op_sel_hi:[1,0,1]
	v_pk_fma_f32 v[10:11], v[98:99], v[124:125], v[10:11] op_sel_hi:[1,0,1]
	v_pk_fma_f32 v[16:17], v[100:101], v[126:127], v[16:17] op_sel_hi:[1,0,1]
	v_pk_fma_f32 v[14:15], v[98:99], v[126:127], v[14:15] op_sel_hi:[1,0,1]
	v_pk_fma_f32 v[20:21], v[100:101], v[128:129], v[20:21] op_sel_hi:[1,0,1]
	v_pk_fma_f32 v[18:19], v[98:99], v[128:129], v[18:19] op_sel_hi:[1,0,1]
	s_waitcnt vmcnt(2)
	v_pk_fma_f32 v[4:5], v[104:105], v[142:143], v[4:5] op_sel_hi:[1,0,1]
	v_pk_fma_f32 v[2:3], v[102:103], v[142:143], v[2:3] op_sel_hi:[1,0,1]
	v_pk_fma_f32 v[8:9], v[104:105], v[162:163], v[8:9] op_sel_hi:[1,0,1]
	v_pk_fma_f32 v[6:7], v[102:103], v[162:163], v[6:7] op_sel_hi:[1,0,1]
	v_pk_fma_f32 v[12:13], v[104:105], v[164:165], v[12:13] op_sel_hi:[1,0,1]
	v_pk_fma_f32 v[10:11], v[102:103], v[164:165], v[10:11] op_sel_hi:[1,0,1]
	v_pk_fma_f32 v[16:17], v[104:105], v[166:167], v[16:17] op_sel_hi:[1,0,1]
	v_pk_fma_f32 v[14:15], v[102:103], v[166:167], v[14:15] op_sel_hi:[1,0,1]
	v_pk_fma_f32 v[20:21], v[104:105], v[168:169], v[20:21] op_sel_hi:[1,0,1]
	v_pk_fma_f32 v[18:19], v[102:103], v[168:169], v[18:19] op_sel_hi:[1,0,1]
	s_waitcnt vmcnt(1)
	v_pk_fma_f32 v[4:5], v[108:109], v[48:49], v[4:5] op_sel_hi:[1,0,1]
	v_pk_fma_f32 v[2:3], v[106:107], v[48:49], v[2:3] op_sel_hi:[1,0,1]
	v_pk_fma_f32 v[8:9], v[108:109], v[130:131], v[8:9] op_sel_hi:[1,0,1]
	v_pk_fma_f32 v[6:7], v[106:107], v[130:131], v[6:7] op_sel_hi:[1,0,1]
	v_pk_fma_f32 v[12:13], v[108:109], v[132:133], v[12:13] op_sel_hi:[1,0,1]
	v_pk_fma_f32 v[10:11], v[106:107], v[132:133], v[10:11] op_sel_hi:[1,0,1]
	v_pk_fma_f32 v[16:17], v[108:109], v[134:135], v[16:17] op_sel_hi:[1,0,1]
	v_pk_fma_f32 v[14:15], v[106:107], v[134:135], v[14:15] op_sel_hi:[1,0,1]
	v_pk_fma_f32 v[20:21], v[108:109], v[136:137], v[20:21] op_sel_hi:[1,0,1]
	v_pk_fma_f32 v[18:19], v[106:107], v[136:137], v[18:19] op_sel_hi:[1,0,1]
	s_waitcnt vmcnt(0)
	v_pk_fma_f32 v[4:5], v[112:113], v[144:145], v[4:5] op_sel_hi:[1,0,1]
	v_pk_fma_f32 v[2:3], v[110:111], v[144:145], v[2:3] op_sel_hi:[1,0,1]
	v_pk_fma_f32 v[8:9], v[112:113], v[170:171], v[8:9] op_sel_hi:[1,0,1]
	v_pk_fma_f32 v[6:7], v[110:111], v[170:171], v[6:7] op_sel_hi:[1,0,1]
	v_pk_fma_f32 v[12:13], v[112:113], v[172:173], v[12:13] op_sel_hi:[1,0,1]
	v_pk_fma_f32 v[10:11], v[110:111], v[172:173], v[10:11] op_sel_hi:[1,0,1]
	v_pk_fma_f32 v[16:17], v[112:113], v[174:175], v[16:17] op_sel_hi:[1,0,1]
	v_pk_fma_f32 v[14:15], v[110:111], v[174:175], v[14:15] op_sel_hi:[1,0,1]
	v_pk_fma_f32 v[20:21], v[112:113], v[176:177], v[20:21] op_sel_hi:[1,0,1]
	v_pk_fma_f32 v[18:19], v[110:111], v[176:177], v[18:19] op_sel_hi:[1,0,1]
	s_andn2_b64 exec, exec, s[86:87]
	s_cbranch_execnz .LBB0_411
	s_or_b64 exec, exec, s[86:87]

; #define LAS __attribute__((address_space(3)))
; DI int otid() { int t = threadIdx.x; asm volatile("" : "+v"(t)); return t; }
; DI void prep_items(const Params& p, LAS unsigned char* lds, int l, unsigned* ctr, int max_items) {
;     const int tid = otid(), lane = tid & 63, wid = tid >> 6;
;     LAS float* s_c = (LAS float*)lds;
;     LAS float* s_red = (LAS float*)(lds + 40960);
;     volatile LAS int* slot = (volatile LAS int*)(lds + LDS_CTRL + 64);
;     constexpr int N_ADA = 48, PER_L = 12832, N_CONV = PER_L / 8;
;     const int n_tab = (l == 0) ? 48 : 0;
;     float* mod = (float*)(p.ws + WS_MOD);
;     bool have_c = false;
;     for (int done = 0; done < max_items; ++done) {
.LBB0_922:
	s_cmpk_lt_u32 s26, 96
	s_cbranch_scc1 .Ldef_skip_1
	v_writelane_b32 v254, s0, 0
	v_writelane_b32 v254, s1, 1
	v_writelane_b32 v254, s2, 2
	v_writelane_b32 v254, s3, 3
	v_writelane_b32 v254, s4, 4
	v_writelane_b32 v254, s5, 5
	v_writelane_b32 v254, s6, 6
	v_writelane_b32 v254, s7, 7
	v_writelane_b32 v254, s8, 8
	v_writelane_b32 v254, s9, 9
	v_writelane_b32 v254, s10, 10
	v_writelane_b32 v254, s11, 11
	v_writelane_b32 v254, s12, 12
	v_writelane_b32 v254, s13, 13
	v_writelane_b32 v254, s14, 14
	v_writelane_b32 v254, s15, 15
	v_writelane_b32 v254, s16, 16
	v_writelane_b32 v254, s17, 17
	v_writelane_b32 v254, s18, 18
	v_writelane_b32 v254, s19, 19
	v_writelane_b32 v254, s20, 20
	v_writelane_b32 v254, s21, 21
	v_writelane_b32 v254, s22, 22
	v_writelane_b32 v254, s23, 23
	v_writelane_b32 v254, s24, 24
	v_writelane_b32 v254, s25, 25
	v_writelane_b32 v254, s26, 26
	v_writelane_b32 v254, s27, 27
	v_writelane_b32 v254, s28, 28
	v_writelane_b32 v254, s29, 29
	v_writelane_b32 v254, s30, 30
	v_writelane_b32 v254, s31, 31
	v_writelane_b32 v254, s32, 32
	v_writelane_b32 v254, s33, 33
	v_writelane_b32 v254, s34, 34
	v_writelane_b32 v254, s35, 35
	v_writelane_b32 v254, s36, 36
	v_writelane_b32 v254, s37, 37
	v_writelane_b32 v254, s38, 38
	v_writelane_b32 v254, s39, 39
	v_writelane_b32 v254, s40, 40
	v_writelane_b32 v254, s41, 41
	v_writelane_b32 v254, s42, 42
	v_writelane_b32 v254, s43, 43
	v_writelane_b32 v254, s44, 44
	v_writelane_b32 v254, s45, 45
	v_writelane_b32 v254, s46, 46
	v_writelane_b32 v254, s47, 47
	v_writelane_b32 v254, s48, 48
	v_writelane_b32 v254, s49, 49
	v_writelane_b32 v254, s50, 50
	v_writelane_b32 v254, s51, 51
	v_writelane_b32 v254, s52, 52
	v_writelane_b32 v254, s53, 53
	v_writelane_b32 v254, s54, 54
	v_writelane_b32 v254, s55, 55
	v_writelane_b32 v254, s56, 56
	v_writelane_b32 v254, s57, 57
	v_writelane_b32 v254, s58, 58
	v_writelane_b32 v254, s59, 59
	v_writelane_b32 v254, s60, 60
	v_writelane_b32 v254, s61, 61
	v_writelane_b32 v254, s62, 62
	v_writelane_b32 v254, s63, 63
	v_writelane_b32 v255, s64, 0
	v_writelane_b32 v255, s65, 1
	v_writelane_b32 v255, s66, 2
	v_writelane_b32 v255, s67, 3
	v_writelane_b32 v255, s68, 4
	v_writelane_b32 v255, s69, 5
	v_writelane_b32 v255, s70, 6
	v_writelane_b32 v255, s71, 7
	v_writelane_b32 v255, s72, 8
	v_writelane_b32 v255, s73, 9
	v_writelane_b32 v255, s74, 10
	v_writelane_b32 v255, s75, 11
	v_writelane_b32 v255, s76, 12
	v_writelane_b32 v255, s77, 13
	v_writelane_b32 v255, s78, 14
	v_writelane_b32 v255, s79, 15
	v_writelane_b32 v255, s80, 16
	v_writelane_b32 v255, s81, 17
	v_writelane_b32 v255, s82, 18
	v_writelane_b32 v255, s83, 19
	v_writelane_b32 v255, s84, 20
	v_writelane_b32 v255, s85, 21
	v_writelane_b32 v255, s86, 22
	v_writelane_b32 v255, s87, 23
	v_writelane_b32 v255, s88, 24
	v_writelane_b32 v255, s89, 25
	v_writelane_b32 v255, s90, 26
	v_writelane_b32 v255, s91, 27
	v_writelane_b32 v255, s92, 28
	v_writelane_b32 v255, s93, 29
	v_writelane_b32 v255, s94, 30
	v_writelane_b32 v255, s95, 31
	v_writelane_b32 v255, s96, 32
	v_writelane_b32 v255, s97, 33
	v_readlane_b32 s2, v253, 9
	s_nop 0
	v_writelane_b32 v255, s2, 40
	v_readlane_b32 s2, v253, 10
	s_nop 0
	v_writelane_b32 v255, s2, 41
	v_readlane_b32 s2, v253, 13
	s_nop 0
	v_writelane_b32 v255, s2, 42
	v_readlane_b32 s2, v253, 14
	s_nop 0
	v_writelane_b32 v255, s2, 43
	v_readlane_b32 s2, v253, 15
	s_nop 0
	v_writelane_b32 v255, s2, 44
	v_readlane_b32 s2, v253, 16
	s_nop 0
	v_writelane_b32 v255, s2, 45
	v_readlane_b32 s2, v253, 17
	s_nop 0
	v_writelane_b32 v255, s2, 46
	v_readlane_b32 s2, v253, 18
	s_nop 0
	v_writelane_b32 v255, s2, 47
	v_readlane_b32 s2, v255, 62
	v_readlane_b32 s3, v255, 63
	s_nop 4
	s_load_dwordx16 s[36:51], s[2:3], 0x80
	s_load_dwordx16 s[68:83], s[2:3], 0x0
	s_load_dwordx16 s[52:67], s[2:3], 0x40
	s_mov_b32 s4, -1
	s_nop 0
	v_writelane_b32 v253, s4, 9
	v_writelane_b32 v253, s4, 10
	v_writelane_b32 v253, s4, 13
	v_writelane_b32 v253, s4, 14
	s_waitcnt lgkmcnt(0)
	s_add_u32 s14, s50, 0x8000
	s_addc_u32 s15, s51, 0
	s_add_u32 s0, s50, 0x4600
	s_addc_u32 s1, s51, 0
	v_mov_b32_e32 v68, v202
	s_movk_i32 s6, 0x3000
	s_movk_i32 s94, 0x1400
	v_or_b32_sdwa v90, v68, s6 dst_sel:DWORD dst_unused:UNUSED_PAD src0_sel:BYTE_0 src1_sel:DWORD
	s_add_u32 s6, s42, 0x2c00000
	s_addc_u32 s7, s43, 0
	s_add_u32 s22, s50, 0xb5a0000
	s_addc_u32 s23, s51, 0
	s_add_u32 s28, s36, 0x5800000
	v_writelane_b32 v253, s6, 17
	s_addc_u32 s29, s37, 0
	v_and_b32_e32 v0, 63, v68
	v_writelane_b32 v253, s7, 18
	s_add_u32 s6, s50, 0x73a0000
	s_addc_u32 s7, s51, 0
	s_add_u32 s34, s62, 0x1000000
	s_addc_u32 s35, s63, 0
	s_add_u32 s36, s50, 0x3fa0000
	s_addc_u32 s37, s51, 0
	v_lshlrev_b32_e32 v83, 2, v0
	v_lshlrev_b32_e32 v2, 1, v68
	s_add_u32 s42, s56, 0x280000
	v_and_b32_e32 v1, 28, v83
	v_and_b32_e32 v2, 16, v2
	s_addc_u32 s43, s57, 0
	v_ashrrev_i32_e32 v82, 6, v68
	v_or_b32_e32 v3, v2, v1
	v_add3_u32 v2, v1, v2, 16
	v_cmp_gt_u32_e32 vcc, 16, v1
	s_add_u32 s56, s50, 0x3660000
	v_mul_lo_u32 v1, v82, s94
	v_cndmask_b32_e32 v87, v2, v3, vcc
	v_lshlrev_b32_e32 v2, 4, v0
	v_mov_b32_e32 v0, 2
	s_addc_u32 s57, s51, 0
	v_add3_u32 v88, 0, v1, v2
	v_lshlrev_b32_sdwa v0, v0, v68 dst_sel:DWORD dst_unused:UNUSED_PAD src0_sel:DWORD src1_sel:BYTE_0
	v_mov_b32_e32 v1, 0
	s_add_u32 s54, s54, 0x1e0000
	v_add_u32_e32 v89, 0, v0
	v_lshl_add_u64 v[70:71], s[14:15], 0, v[0:1]
	s_addc_u32 s55, s55, 0
	v_max_i32_e32 v0, 0x7f8, v82
	s_add_u32 s62, s50, 0x3420000
	v_sub_u32_e32 v0, v0, v82
	s_addc_u32 s63, s51, 0
	v_add_u32_e32 v0, 7, v0
	v_writelane_b32 v253, s6, 15
	s_add_u32 s80, s80, 0x2e80000
	v_lshrrev_b32_e32 v3, 3, v0
	s_mov_b32 s27, 0xc000
	v_writelane_b32 v253, s7, 16
	s_addc_u32 s81, s81, 0
	v_add_u32_e32 v3, 1, v3
	v_mad_i64_i32 v[4:5], s[6:7], v82, s27, 0
	s_add_u32 s84, s50, 0x1b20000
	v_and_b32_e32 v6, 7, v3
	v_mov_b32_e32 v3, v1
	v_or_b32_e32 v4, v4, v2
	s_movk_i32 s2, 0x2800
	s_movk_i32 s4, 0x800
	s_movk_i32 s97, 0x500
	s_addc_u32 s85, s51, 0
	v_and_b32_e32 v7, 56, v0
	v_ashrrev_i32_e32 v69, 31, v68
	v_lshl_add_u64 v[4:5], s[76:77], 0, v[4:5]
	s_mov_b64 s[6:7], 0x6000000
	v_lshl_add_u64 v[2:3], s[76:77], 0, v[2:3]
	s_add_i32 s20, 0, 0x22040
	v_and_b32_e32 v84, 0x7c, v83
	v_or_b32_e32 v85, 0xffff9c00, v83
	v_or_b32_e32 v86, 0xffffa000, v83
	v_cmp_gt_i32_e64 s[2:3], s2, v68
	v_cmp_gt_i32_e64 s[4:5], s4, v82
	s_mov_b32 s96, 0x3ffffffc
	v_add_u32_e32 v91, 0xfffffe80, v82
	v_lshl_add_u32 v92, v68, 2, 0
	v_lshl_add_u64 v[72:73], v[68:69], 2, s[70:71]
	v_lshl_add_u32 v69, v82, 2, 0
	v_lshl_add_u64 v[74:75], v[4:5], 0, s[6:7]
	v_sub_u32_e32 v93, 0, v6
	v_lshl_add_u64 v[76:77], v[2:3], 0, s[6:7]
	v_mov_b32_e32 v94, s20
	v_mov_b32_e32 v95, 0xffffea00
	v_mov_b32_e32 v96, 0x80
	s_movk_i32 s21, 0x2000
	v_cmp_gt_i32_e64 s[6:7], s97, v68
	v_cmp_ne_u32_e64 s[8:9], 56, v7
	v_cmp_lt_u32_e64 s[10:11], 55, v0
	s_mov_b64 s[76:77], 0
	s_mov_b64 s[70:71], 0x300000
	s_branch .Ldq1_239

; DI void prep_items(const Params& p, LAS unsigned char* lds, int l, unsigned* ctr, int max_items) {
;     ...
;     for (int done = 0; done < max_items; ++done) {
;         const int it = next_item(ctr, slot);
;         if (it >= N_ADA + n_tab + N_CONV) break;
;         if (it < N_ADA) {
;     ...
;             int id = (it - N_ADA - n_tab) * 8 + wid;
;             if (id < 3072) conv_witem(p.in[6] + (size_t)l * 2048 * INW, 2048, INW, (bf16_t*)(p.ws + WS_WIN) + (size_t)l * 6144 * 2048, nullptr, true, id % 128, id / 128, lane);
;             else if ((id -= 3072) < 128) conv_witem(p.in[9] + (size_t)l * 512 * 960, 512, 960, (bf16_t*)(p.ws + WS_WUQ) + (size_t)l * 1024 * 512, p.in[7] + l * 512, false, id % 32, id / 32, lane);
;             else if ((id -= 128) < 160) conv_witem(p.in[10] + (size_t)l * 512 * 1280, 512, 1280, (bf16_t*)(p.ws + WS_WUKV) + (size_t)l * 1280 * 512, p.in[8] + l * 512, false, id % 32, id / 32, lane);
;             else if ((id -= 160) < 1024) conv_witem(p.in[13] + (size_t)l * 2048 * 2048, 2048, 2048, (bf16_t*)(p.ws + WS_WO) + (size_t)l * 2048 * 2048, nullptr, false, id % 128, id / 128, lane);
;             else if ((id -= 1024) < 5632) conv_witem(p.in[16] + (size_t)l * 2048 * 11264, 2048, 11264, (bf16_t*)(p.ws + WS_WUP) + (size_t)l * 11264 * 2048, nullptr, false, id % 128, id / 128, lane, true);
;             else { id -= 5632; conv_witem(p.in[19] + (size_t)l * 5632 * 2048, 5632, 2048, (bf16_t*)(p.ws + WS_WDN) + (size_t)l * 2048 * 5632, nullptr, false, id % 352, id / 352, lane); }
.Ldq1_243:
	s_or_b64 exec, exec, s[12:13]
	s_waitcnt lgkmcnt(0)
	s_barrier
	ds_read_b32 v0, v94
	s_movk_i32 s12, 0x673
	s_xor_b64 s[86:87], s[76:77], -1
	s_waitcnt lgkmcnt(0)
	v_add_u32_e32 v0, 48, v0
	v_cmp_lt_i32_e32 vcc, s12, v0
	v_readfirstlane_b32 s30, v0
	s_mov_b64 s[12:13], -1
	s_cbranch_vccnz .Ldq1_238
	s_cmp_gt_i32 s30, 47
	s_cbranch_scc0 .Ldq1_398
	v_lshl_add_u32 v0, s30, 3, v91
	s_movk_i32 s12, 0xbff
	v_cmp_lt_i32_e32 vcc, s12, v0
	s_and_saveexec_b64 s[12:13], vcc
	s_xor_b64 s[88:89], exec, s[12:13]
	s_cbranch_execz .Ldq1_363
	s_movk_i32 s12, 0xc7f
	v_cmp_lt_u32_e32 vcc, s12, v0
	s_and_saveexec_b64 s[12:13], vcc
	s_xor_b64 s[16:17], exec, s[12:13]
	s_cbranch_execz .Ldq1_326
	s_movk_i32 s12, 0xd1f
	v_cmp_lt_u32_e32 vcc, s12, v0
	s_and_saveexec_b64 s[12:13], vcc
	s_xor_b64 s[18:19], exec, s[12:13]
	s_cbranch_execz .Ldq1_289
	s_movk_i32 s12, 0x111f
	v_cmp_lt_u32_e32 vcc, s12, v0
	s_and_saveexec_b64 s[12:13], vcc
	s_xor_b64 s[90:91], exec, s[12:13]
	s_cbranch_execz .Ldq1_286
	s_movk_i32 s12, 0x271f
	v_cmp_lt_u32_e32 vcc, s12, v0
	s_and_saveexec_b64 s[12:13], vcc
	s_xor_b64 s[92:93], exec, s[12:13]
	s_cbranch_execz .Ldq1_283
	v_add_u32_e32 v2, 0xffffd8e0, v0
	s_mov_b32 s12, 0xba2e8ba3
	v_mul_hi_u32 v3, v2, s12
	v_lshrrev_b32_e32 v0, 8, v3
	v_mul_u32_u24_e32 v0, 0x160, v0
	v_sub_u32_e32 v0, v2, v0
	s_movk_i32 s12, 0xff00
	v_lshlrev_b32_e32 v0, 4, v0
	v_and_or_b32 v66, v3, s12, v83
	s_movk_i32 s12, 0xb00
	v_readlane_b32 s94, v253, 17
	v_cmp_gt_u32_e64 s[12:13], s12, v2
	v_lshlrev_b64 v[2:3], 13, v[0:1]
	v_readlane_b32 s95, v253, 18
	v_mov_b32_e32 v67, v1
	v_mov_b32_e32 v6, 0
	v_lshl_add_u64 v[2:3], s[94:95], 0, v[2:3]
	v_lshl_add_u64 v[78:79], v[66:67], 2, v[2:3]
	v_mov_b32_e32 v2, 0
	v_mov_b32_e32 v3, 0
	v_mov_b32_e32 v4, 0
	v_mov_b32_e32 v5, 0
	s_and_saveexec_b64 s[94:95], s[12:13]
	s_cbranch_execz .Ldq1_252
	global_load_dwordx4 v[2:5], v[78:79], off nt

; #define LAS __attribute__((address_space(3)))
; DI int otid() { int t = threadIdx.x; asm volatile("" : "+v"(t)); return t; }
; DI void prep_items(const Params& p, LAS unsigned char* lds, int l, unsigned* ctr, int max_items) {
;     const int tid = otid(), lane = tid & 63, wid = tid >> 6;
;     LAS float* s_c = (LAS float*)lds;
;     LAS float* s_red = (LAS float*)(lds + 40960);
;     volatile LAS int* slot = (volatile LAS int*)(lds + LDS_CTRL + 64);
;     constexpr int N_ADA = 48, PER_L = 12832, N_CONV = PER_L / 8;
;     const int n_tab = (l == 0) ? 48 : 0;
;     float* mod = (float*)(p.ws + WS_MOD);
;     bool have_c = false;
;     for (int done = 0; done < max_items; ++done) {
.LBB0_1541:
	s_cmpk_lt_u32 s26, 48
	s_cbranch_scc1 .Ldef_skip_2
	v_writelane_b32 v254, s0, 0
	v_writelane_b32 v254, s1, 1
	v_writelane_b32 v254, s2, 2
	v_writelane_b32 v254, s3, 3
	v_writelane_b32 v254, s4, 4
	v_writelane_b32 v254, s5, 5
	v_writelane_b32 v254, s6, 6
	v_writelane_b32 v254, s7, 7
	v_writelane_b32 v254, s8, 8
	v_writelane_b32 v254, s9, 9
	v_writelane_b32 v254, s10, 10
	v_writelane_b32 v254, s11, 11
	v_writelane_b32 v254, s12, 12
	v_writelane_b32 v254, s13, 13
	v_writelane_b32 v254, s14, 14
	v_writelane_b32 v254, s15, 15
	v_writelane_b32 v254, s16, 16
	v_writelane_b32 v254, s17, 17
	v_writelane_b32 v254, s18, 18
	v_writelane_b32 v254, s19, 19
	v_writelane_b32 v254, s20, 20
	v_writelane_b32 v254, s21, 21
	v_writelane_b32 v254, s22, 22
	v_writelane_b32 v254, s23, 23
	v_writelane_b32 v254, s24, 24
	v_writelane_b32 v254, s25, 25
	v_writelane_b32 v254, s26, 26
	v_writelane_b32 v254, s27, 27
	v_writelane_b32 v254, s28, 28
	v_writelane_b32 v254, s29, 29
	v_writelane_b32 v254, s30, 30
	v_writelane_b32 v254, s31, 31
	v_writelane_b32 v254, s32, 32
	v_writelane_b32 v254, s33, 33
	v_writelane_b32 v254, s34, 34
	v_writelane_b32 v254, s35, 35
	v_writelane_b32 v254, s36, 36
	v_writelane_b32 v254, s37, 37
	v_writelane_b32 v254, s38, 38
	v_writelane_b32 v254, s39, 39
	v_writelane_b32 v254, s40, 40
	v_writelane_b32 v254, s41, 41
	v_writelane_b32 v254, s42, 42
	v_writelane_b32 v254, s43, 43
	v_writelane_b32 v254, s44, 44
	v_writelane_b32 v254, s45, 45
	v_writelane_b32 v254, s46, 46
	v_writelane_b32 v254, s47, 47
	v_writelane_b32 v254, s48, 48
	v_writelane_b32 v254, s49, 49
	v_writelane_b32 v254, s50, 50
	v_writelane_b32 v254, s51, 51
	v_writelane_b32 v254, s52, 52
	v_writelane_b32 v254, s53, 53
	v_writelane_b32 v254, s54, 54
	v_writelane_b32 v254, s55, 55
	v_writelane_b32 v254, s56, 56
	v_writelane_b32 v254, s57, 57
	v_writelane_b32 v254, s58, 58
	v_writelane_b32 v254, s59, 59
	v_writelane_b32 v254, s60, 60
	v_writelane_b32 v254, s61, 61
	v_writelane_b32 v254, s62, 62
	v_writelane_b32 v254, s63, 63
	v_writelane_b32 v255, s64, 0
	v_writelane_b32 v255, s65, 1
	v_writelane_b32 v255, s66, 2
	v_writelane_b32 v255, s67, 3
	v_writelane_b32 v255, s68, 4
	v_writelane_b32 v255, s69, 5
	v_writelane_b32 v255, s70, 6
	v_writelane_b32 v255, s71, 7
	v_writelane_b32 v255, s72, 8
	v_writelane_b32 v255, s73, 9
	v_writelane_b32 v255, s74, 10
	v_writelane_b32 v255, s75, 11
	v_writelane_b32 v255, s76, 12
	v_writelane_b32 v255, s77, 13
	v_writelane_b32 v255, s78, 14
	v_writelane_b32 v255, s79, 15
	v_writelane_b32 v255, s80, 16
	v_writelane_b32 v255, s81, 17
	v_writelane_b32 v255, s82, 18
	v_writelane_b32 v255, s83, 19
	v_writelane_b32 v255, s84, 20
	v_writelane_b32 v255, s85, 21
	v_writelane_b32 v255, s86, 22
	v_writelane_b32 v255, s87, 23
	v_writelane_b32 v255, s88, 24
	v_writelane_b32 v255, s89, 25
	v_writelane_b32 v255, s90, 26
	v_writelane_b32 v255, s91, 27
	v_writelane_b32 v255, s92, 28
	v_writelane_b32 v255, s93, 29
	v_writelane_b32 v255, s94, 30
	v_writelane_b32 v255, s95, 31
	v_writelane_b32 v255, s96, 32
	v_writelane_b32 v255, s97, 33
	v_readlane_b32 s2, v253, 9
	s_nop 0
	v_writelane_b32 v255, s2, 40
	v_readlane_b32 s2, v253, 10
	s_nop 0
	v_writelane_b32 v255, s2, 41
	v_readlane_b32 s2, v253, 13
	s_nop 0
	v_writelane_b32 v255, s2, 42
	v_readlane_b32 s2, v253, 14
	s_nop 0
	v_writelane_b32 v255, s2, 43
	v_readlane_b32 s2, v253, 15
	s_nop 0
	v_writelane_b32 v255, s2, 44
	v_readlane_b32 s2, v253, 16
	s_nop 0
	v_writelane_b32 v255, s2, 45
	v_readlane_b32 s2, v253, 17
	s_nop 0
	v_writelane_b32 v255, s2, 46
	v_readlane_b32 s2, v253, 18
	s_nop 0
	v_writelane_b32 v255, s2, 47
	v_readlane_b32 s2, v255, 62
	v_readlane_b32 s3, v255, 63
	s_nop 4
	s_load_dwordx16 s[36:51], s[2:3], 0x80
	s_load_dwordx16 s[68:83], s[2:3], 0x0
	s_load_dwordx16 s[52:67], s[2:3], 0x40
	s_mov_b32 s4, -1
	s_nop 0
	v_writelane_b32 v253, s4, 9
	v_writelane_b32 v253, s4, 10
	v_writelane_b32 v253, s4, 13
	v_writelane_b32 v253, s4, 14
	s_waitcnt lgkmcnt(0)
	s_add_u32 s14, s50, 0x8000
	s_addc_u32 s15, s51, 0
	s_add_u32 s0, s50, 0x4600
	s_addc_u32 s1, s51, 0
	v_mov_b32_e32 v68, v202
	s_movk_i32 s6, 0x3000
	s_movk_i32 s94, 0x1400
	v_or_b32_sdwa v90, v68, s6 dst_sel:DWORD dst_unused:UNUSED_PAD src0_sel:BYTE_0 src1_sel:DWORD
	s_add_u32 s6, s42, 0x2c00000
	s_addc_u32 s7, s43, 0
	s_add_u32 s22, s50, 0xb5a0000
	s_addc_u32 s23, s51, 0
	s_add_u32 s28, s36, 0x5800000
	v_writelane_b32 v253, s6, 17
	s_addc_u32 s29, s37, 0
	v_and_b32_e32 v0, 63, v68
	v_writelane_b32 v253, s7, 18
	s_add_u32 s6, s50, 0x73a0000
	s_addc_u32 s7, s51, 0
	s_add_u32 s34, s62, 0x1000000
	s_addc_u32 s35, s63, 0
	s_add_u32 s36, s50, 0x3fa0000
	s_addc_u32 s37, s51, 0
	v_lshlrev_b32_e32 v83, 2, v0
	v_lshlrev_b32_e32 v2, 1, v68
	s_add_u32 s42, s56, 0x280000
	v_and_b32_e32 v1, 28, v83
	v_and_b32_e32 v2, 16, v2
	s_addc_u32 s43, s57, 0
	v_ashrrev_i32_e32 v82, 6, v68
	v_or_b32_e32 v3, v2, v1
	v_add3_u32 v2, v1, v2, 16
	v_cmp_gt_u32_e32 vcc, 16, v1
	s_add_u32 s56, s50, 0x3660000
	v_mul_lo_u32 v1, v82, s94
	v_cndmask_b32_e32 v87, v2, v3, vcc
	v_lshlrev_b32_e32 v2, 4, v0
	v_mov_b32_e32 v0, 2
	s_addc_u32 s57, s51, 0
	v_add3_u32 v88, 0, v1, v2
	v_lshlrev_b32_sdwa v0, v0, v68 dst_sel:DWORD dst_unused:UNUSED_PAD src0_sel:DWORD src1_sel:BYTE_0
	v_mov_b32_e32 v1, 0
	s_add_u32 s54, s54, 0x1e0000
	v_add_u32_e32 v89, 0, v0
	v_lshl_add_u64 v[70:71], s[14:15], 0, v[0:1]
	s_addc_u32 s55, s55, 0
	v_max_i32_e32 v0, 0x7f8, v82
	s_add_u32 s62, s50, 0x3420000
	v_sub_u32_e32 v0, v0, v82
	s_addc_u32 s63, s51, 0
	v_add_u32_e32 v0, 7, v0
	v_writelane_b32 v253, s6, 15
	s_add_u32 s80, s80, 0x2e80000
	v_lshrrev_b32_e32 v3, 3, v0
	s_mov_b32 s27, 0xc000
	v_writelane_b32 v253, s7, 16
	s_addc_u32 s81, s81, 0
	v_add_u32_e32 v3, 1, v3
	v_mad_i64_i32 v[4:5], s[6:7], v82, s27, 0
	s_add_u32 s84, s50, 0x1b20000
	v_and_b32_e32 v6, 7, v3
	v_mov_b32_e32 v3, v1
	v_or_b32_e32 v4, v4, v2
	s_movk_i32 s2, 0x2800
	s_movk_i32 s4, 0x800
	s_movk_i32 s97, 0x500
	s_addc_u32 s85, s51, 0
	v_and_b32_e32 v7, 56, v0
	v_ashrrev_i32_e32 v69, 31, v68
	v_lshl_add_u64 v[4:5], s[76:77], 0, v[4:5]
	s_mov_b64 s[6:7], 0x6000000
	v_lshl_add_u64 v[2:3], s[76:77], 0, v[2:3]
	s_add_i32 s20, 0, 0x22040
	v_and_b32_e32 v84, 0x7c, v83
	v_or_b32_e32 v85, 0xffff9c00, v83
	v_or_b32_e32 v86, 0xffffa000, v83
	v_cmp_gt_i32_e64 s[2:3], s2, v68
	v_cmp_gt_i32_e64 s[4:5], s4, v82
	s_mov_b32 s96, 0x3ffffffb
	v_add_u32_e32 v91, 0xfffffe80, v82
	v_lshl_add_u32 v92, v68, 2, 0
	v_lshl_add_u64 v[72:73], v[68:69], 2, s[70:71]
	v_lshl_add_u32 v69, v82, 2, 0
	v_lshl_add_u64 v[74:75], v[4:5], 0, s[6:7]
	v_sub_u32_e32 v93, 0, v6
	v_lshl_add_u64 v[76:77], v[2:3], 0, s[6:7]
	v_mov_b32_e32 v94, s20
	v_mov_b32_e32 v95, 0xffffea00
	v_mov_b32_e32 v96, 0x80
	s_movk_i32 s21, 0x2000
	v_cmp_gt_i32_e64 s[6:7], s97, v68
	v_cmp_ne_u32_e64 s[8:9], 56, v7
	v_cmp_lt_u32_e64 s[10:11], 55, v0
	s_mov_b64 s[76:77], 0
	s_mov_b64 s[70:71], 0x300000
	s_branch .Ldq2_239

; #define LAS __attribute__((address_space(3)))
; DI void phase_prep(const Params& p, LAS unsigned char* lds) { prep_items(p, lds, 0, (unsigned*)(p.ws + WS_QCTR), 1 << 30); prep_items(p, lds, 1, (unsigned*)(p.ws + WS_QCTR + 256 * 5), 1 << 30); }
; #define SEAM(k) do { if ((k) != 19) xcd_barrier(bar); } while (0)
; __global__ void __launch_bounds__(512, 2) fwd_kernel(Params p) {
;     extern __shared__ __attribute__((aligned(16))) unsigned char smem[];
;     LAS unsigned char* lds = (LAS unsigned char*)smem;
;     cg::grid_group grid = cg::this_grid();
;     if (threadIdx.x < 32) ((volatile LAS unsigned*)(lds + LDS_CTRL))[threadIdx.x] = 0u;
;     __syncthreads();
;     const XcdBarrier bar = xcd_barrier_post((unsigned*)(p.ws + WS_CTL), (volatile LAS unsigned*)(lds + LDS_CTRL));
;     if (p.ph_lo == 0x7fffffff) grid.sync();
;     if (IN(0)) { phase_prep(p, lds); xcd_barrier(bar); }
;     if (IN(1)) { phase_init_x(p); SEAM(1); }
;     layer_body<0>(p, lds, grid, bar);
;     layer_body<1>(p, lds, grid, bar);
; }
	.amdhsa_kernel _Z10fwd_kernel6Params
		.amdhsa_group_segment_fixed_size 0
		.amdhsa_private_segment_fixed_size 0
		.amdhsa_kernarg_size 456
		.amdhsa_user_sgpr_count 2
		.amdhsa_user_sgpr_dispatch_ptr 0
		.amdhsa_user_sgpr_queue_ptr 0
		.amdhsa_user_sgpr_kernarg_segment_ptr 1
		.amdhsa_user_sgpr_dispatch_id 0
		.amdhsa_user_sgpr_kernarg_preload_length 0
		.amdhsa_user_sgpr_kernarg_preload_offset 0
		.amdhsa_user_sgpr_private_segment_size 0
		.amdhsa_uses_dynamic_stack 0
		.amdhsa_enable_private_segment 0
		.amdhsa_system_sgpr_workgroup_id_x 1
		.amdhsa_system_sgpr_workgroup_id_y 0
		.amdhsa_system_sgpr_workgroup_id_z 0
		.amdhsa_system_sgpr_workgroup_info 0
		.amdhsa_system_vgpr_workitem_id 2
		.amdhsa_next_free_vgpr 256
		.amdhsa_next_free_sgpr 102
		.amdhsa_accum_offset 256
		.amdhsa_reserve_vcc 1
		.amdhsa_float_round_mode_32 0
		.amdhsa_float_round_mode_16_64 0
		.amdhsa_float_denorm_mode_32 3
		.amdhsa_float_denorm_mode_16_64 3
		.amdhsa_dx10_clamp 1
		.amdhsa_ieee_mode 1
		.amdhsa_fp16_overflow 0
		.amdhsa_tg_split 0
		.amdhsa_exception_fp_ieee_invalid_op 0
		.amdhsa_exception_fp_denorm_src 0
		.amdhsa_exception_fp_ieee_div_zero 0
		.amdhsa_exception_fp_ieee_overflow 0
		.amdhsa_exception_fp_ieee_underflow 0
		.amdhsa_exception_fp_ieee_inexact 0
		.amdhsa_exception_int_div_zero 0
	.end_amdhsa_kernel

; #define LAS __attribute__((address_space(3)))
; DI void phase_prep(const Params& p, LAS unsigned char* lds) { prep_items(p, lds, 0, (unsigned*)(p.ws + WS_QCTR), 1 << 30); prep_items(p, lds, 1, (unsigned*)(p.ws + WS_QCTR + 256 * 5), 1 << 30); }
; #define SEAM(k) do { if ((k) != 19) xcd_barrier(bar); } while (0)
; __global__ void __launch_bounds__(512, 2) fwd_kernel(Params p) {
;     extern __shared__ __attribute__((aligned(16))) unsigned char smem[];
;     LAS unsigned char* lds = (LAS unsigned char*)smem;
;     cg::grid_group grid = cg::this_grid();
;     if (threadIdx.x < 32) ((volatile LAS unsigned*)(lds + LDS_CTRL))[threadIdx.x] = 0u;
;     __syncthreads();
;     const XcdBarrier bar = xcd_barrier_post((unsigned*)(p.ws + WS_CTL), (volatile LAS unsigned*)(lds + LDS_CTRL));
;     if (p.ph_lo == 0x7fffffff) grid.sync();
;     if (IN(0)) { phase_prep(p, lds); xcd_barrier(bar); }
;     if (IN(1)) { phase_init_x(p); SEAM(1); }
;     layer_body<0>(p, lds, grid, bar);
;     layer_body<1>(p, lds, grid, bar);
; }
amdhsa.kernels:
  - .agpr_count:     0
    .args:
      - .offset:         0
        .size:           200
        .value_kind:     by_value
      - .offset:         200
        .size:           4
        .value_kind:     hidden_block_count_x
      - .offset:         204
        .size:           4
        .value_kind:     hidden_block_count_y
      - .offset:         208
        .size:           4
        .value_kind:     hidden_block_count_z
      - .offset:         212
        .size:           2
        .value_kind:     hidden_group_size_x
      - .offset:         214
        .size:           2
        .value_kind:     hidden_group_size_y
      - .offset:         216
        .size:           2
        .value_kind:     hidden_group_size_z
      - .offset:         218
        .size:           2
        .value_kind:     hidden_remainder_x
      - .offset:         220
        .size:           2
        .value_kind:     hidden_remainder_y
      - .offset:         222
        .size:           2
        .value_kind:     hidden_remainder_z
      - .offset:         240
        .size:           8
        .value_kind:     hidden_global_offset_x
      - .offset:         248
        .size:           8
        .value_kind:     hidden_global_offset_y
      - .offset:         256
        .size:           8
        .value_kind:     hidden_global_offset_z
      - .offset:         264
        .size:           2
        .value_kind:     hidden_grid_dims
      - .offset:         288
        .size:           8
        .value_kind:     hidden_multigrid_sync_arg
      - .offset:         320
        .size:           4
        .value_kind:     hidden_dynamic_lds_size
    .group_segment_fixed_size: 0
    .kernarg_segment_align: 8
    .kernarg_segment_size: 456
    .language:       OpenCL C
    .language_version:
      - 2
      - 0
    .max_flat_workgroup_size: 512
    .name:           _Z10fwd_kernel6Params
    .private_segment_fixed_size: 0
    .sgpr_count:     108
    .sgpr_spill_count: 52
    .symbol:         _Z10fwd_kernel6Params.kd
    .uniform_work_group_size: 1
    .uses_dynamic_stack: false
    .vgpr_count:     256
    .vgpr_spill_count: 0
    .wavefront_size: 64
